# phase-3 work queue: next item claimed (atomic) at the start of short prep units and consumed at the next loop top; long units still claim synchronously
# baseline (speedup 1.0000x reference)
; DI int opaque_tid() { int t = threadIdx.x; asm volatile("" : "+v"(t)); return t; }
; DI void attn_unit(const Params& p, int l, int unit, unsigned char* smem) {
;     ...
;   const float lam_init = 0.8f - 0.6f * expf(-0.3f * (float)l);
; __global__ void __launch_bounds__(256, 2) mega(Params p) {
;     ...
;     {
;       constexpr int N_DFT = 544, N_DN = DN_UNITS, N_HG = HG_UNITS;
;       const int tid = opaque_tid();
;       unsigned* ctr3 = (unsigned*)(p.ws + O_CTR) + 8 + l;
;       const int n_att3 = (l < 3) ? 96 : 64;
;       if (gridDim.x == 512) {
;         const int xcd = blockIdx.x & 7, local = blockIdx.x >> 3;
;         const int mt = (xcd & 3) * 8 + (local >> 3), nn = (xcd >> 2) * 8 + (local & 7);
;         dft_tile(p, (nn >> 2) * 128 + mt * 4 + (nn & 3), smem);
;       }
;       const int dft0 = (gridDim.x == 512) ? 512 : 0;
;       for (;;) {
;         __syncthreads();
;         if (tid == 0) s_item = (int)atomicAdd(ctr3, 1u);
;         __syncthreads();
;         const int it = s_item - n_att3 + dft0;
.LBB0_308:
	v_readlane_b32 s6, v254, 49
	v_readlane_b32 s7, v254, 50
	s_lshl_b64 s[16:17], s[6:7], 2
	v_readlane_b32 s4, v255, 17
	s_add_u32 s20, s4, s16
	v_readlane_b32 s4, v255, 19
	v_cvt_f32_u32_e32 v0, s6
	s_addc_u32 s21, s4, s17
	s_cmp_eq_u32 s6, 3
	s_cselect_b64 s[12:13], -1, 0
	s_and_b64 s[4:5], s[12:13], exec
	v_mul_f32_e32 v0, 0xbe99999a, v0
	v_mul_f32_e32 v1, 0x3fb8aa3b, v0
	s_mov_b32 s5, 0x3fb8aa3b
	v_fma_f32 v2, v0, s5, -v1
	v_rndne_f32_e32 v3, v1
	v_fmac_f32_e32 v2, 0x32a5705f, v0
	v_sub_f32_e32 v1, v1, v3
	s_mov_b64 s[14:15], s[60:61]
	v_add_f32_e32 v1, v1, v2
	v_readlane_b32 s56, v254, 0
	s_movk_i32 s4, 0xffa0
	v_exp_f32_e32 v1, v1
	v_cvt_i32_f32_e32 v2, v3
	v_readlane_b32 s57, v254, 1
	v_readlane_b32 s58, v254, 2
	v_readlane_b32 s59, v254, 3
	v_readlane_b32 s60, v254, 4
	v_readlane_b32 s61, v254, 5
	v_readlane_b32 s62, v254, 6
	v_readlane_b32 s63, v254, 7
	s_cselect_b32 s35, 0xffffffc0, s4
	s_lshl_b32 s36, s6, 10
	s_lshl_b32 s37, s6, 3
	s_mul_i32 s5, s6, 0x4800
	v_readlane_b32 s64, v254, 8
	v_readlane_b32 s65, v254, 9
	v_readlane_b32 s66, v254, 10
	v_readlane_b32 s67, v254, 11
	s_mov_b64 s[56:57], s[60:61]
	s_mul_hi_u32 s4, s6, 0x4800
	s_add_u32 s22, s56, s5
	s_addc_u32 s23, s57, s4
	s_mov_b32 s4, 0xc2ce8ed0
	v_ldexp_f32 v1, v1, v2
	v_cmp_ngt_f32_e32 vcc, s4, v0
	s_mov_b32 s4, 0x42b17218
	s_mov_b32 s5, s45
	v_cndmask_b32_e32 v1, 0, v1, vcc
	v_cmp_nlt_f32_e32 vcc, s4, v0
	s_lshl_b32 s4, s6, 7
	v_readlane_b32 s24, v254, 20
	v_writelane_b32 v255, s4, 15
	v_readlane_b32 s26, v254, 22
	v_readlane_b32 s27, v254, 23
	v_cndmask_b32_e32 v0, v214, v1, vcc
	v_mov_b32_e32 v1, 0xbf4ccccd
	v_writelane_b32 v255, s5, 16
	s_lshl_b64 s[4:5], s[4:5], 2
	s_mov_b64 s[6:7], s[26:27]
	v_fmamk_f32 v0, v0, 0x3f19999a, v1
	s_add_u32 s18, s6, s4
	v_cmp_eq_u32_e64 s[10:11], 0, v80
	v_add_f32_e32 v244, 1.0, v0
	s_addc_u32 s19, s7, s5
	v_readlane_b32 s68, v254, 12
	v_readlane_b32 s69, v254, 13
	v_readlane_b32 s70, v254, 14
	v_readlane_b32 s71, v254, 15
	s_mov_b64 s[58:59], s[62:63]
	s_mov_b64 s[60:61], s[64:65]
	s_mov_b64 s[62:63], s[66:67]
	v_readlane_b32 s25, v254, 21
	v_readlane_b32 s28, v254, 24
	v_readlane_b32 s29, v254, 25
	v_readlane_b32 s30, v254, 26
	v_readlane_b32 s31, v254, 27
	v_mov_b32_e32 v241, -1
	s_branch .LBB0_311

; DI float bf2f(bfr v) { return __uint_as_float(((unsigned)v) << 16); }
; DI unsigned char* launder_ptr(unsigned char* q) { asm volatile("" : "+s"(q)); return q; }
; DI int opaque_tid() { int t = threadIdx.x; asm volatile("" : "+v"(t)); return t; }
; DI void stream_of(int n, int cpc, int& m, int& T, int& soff) { if (n < cpc) { m = n; T = CTX; soff = 0; } else { m = n - cpc; T = SEQ; soff = CTX; } }
; DI void hg_prep_unit(const Params& p, int l, int unit, unsigned char* smem) {
;   unsigned char* const WS_ = launder_ptr(p.ws);
;   const int tid = opaque_tid(), lane = tid & 63, wv = tid >> 6, l31 = lane & 31, h = lane >> 5;
;   const int n = unit % 136, hd = (unit / 136) & 3, b = (unit / 544) & 3, dir = unit / 2176;
;   int m, T, soff; stream_of(n, 8, m, T, soff);
;   bfr* sQt = (bfr*)smem;
;   bfr* sKt = (bfr*)(smem + 8704);
;   bfr* sVT = (bfr*)(smem + 17408);
;   const bfr* P = (const bfr*)(WS_ + O_P);
;   bfr* U = (bfr*)(WS_ + O_HGU) + (size_t)unit * HG_USZ;
;   bfr* g_qhat = U; bfr* g_khT = U + 4096; bfr* g_vT = U + 8192;
;   float* OHG = (float*)(WS_ + O_OHG) + (size_t)dir * NTOK * 512;
;   const int rowbase = b * SP + soff;
;   float* sTot = (float*)(smem + 27648);
;   __syncthreads();
;   {
;     const int dk = tid & 127, hf = tid >> 7, i0 = 16 * hf;
;     const float lbv = ((const float*)(WS_ + O_LB))[(l * 2 + dir) * 512 + hd * 128 + dk];
;     float G[16], KK[16], Q[16];
;     unsigned vv[8];
; #pragma unroll
;     for (int i = 0; i < 16; ++i) {
;       const int pos = 32 * m + i0 + i, t = dir ? T - 1 - pos : pos;
;       const size_t row = rowbase + t;
;       KK[i] = bf2f(P[row * PLD + C_HGF + dir * 512 + hd * 128 + dk]);
;       Q[i] = bf2f(P[row * PLD + C_HGQ + hd * 128 + dk]);
;       const unsigned x = P[row * PLD + C_HGI + hd * 128 + dk];
; __global__ void __launch_bounds__(256, 2) mega(Params p) {
;     ...
;       for (;;) {
;         __syncthreads();
;         if (tid == 0) s_item = (int)atomicAdd(ctr3, 1u);
;         __syncthreads();
;         const int it = s_item - n_att3 + dft0;
;         if (it >= N_DFT + N_DN + N_HG) break;
;         if (it < dft0) attn_unit(p, l, 448 + (it - dft0) + n_att3, smem);
;         else if (it < N_DFT) dft_tile(p, it, smem);
;         else if (it < N_DFT + N_DN) dn_prep_unit(p, l, it - N_DFT, smem);
;         else hg_prep_unit(p, l, it - N_DFT - N_DN, smem);
.LBB0_311:
	s_waitcnt lgkmcnt(0)
	s_barrier
	s_and_saveexec_b64 s[4:5], s[10:11]
	s_cbranch_execz .LBB0_315
	s_waitcnt vmcnt(0)
	v_cmp_eq_u32_e32 vcc, -1, v241
	s_and_saveexec_b64 s[6:7], vcc
	s_cbranch_execz .LBB0_314
	v_mov_b32_e32 v241, 1
	s_nop 0
	global_atomic_add v241, v209, v241, s[20:21] sc0
	s_waitcnt vmcnt(0)
.LBB0_314:
	s_or_b64 exec, exec, s[6:7]
	ds_write_b32 v218, v241
.LBB0_315:
	s_or_b64 exec, exec, s[4:5]
	s_waitcnt lgkmcnt(0)
	s_barrier
	ds_read_b32 v0, v218
	v_mov_b32_e32 v241, -1
	s_mov_b64 s[4:5], -1
	s_waitcnt lgkmcnt(0)
	v_readfirstlane_b32 s38, v0
	s_add_i32 s39, s38, s35
	s_add_i32 s41, s39, s34
	s_cmpk_gt_i32 s41, 0x1b9f
	s_cbranch_scc1 .LBB0_310
	s_cmp_gt_i32 s39, -1
	s_cbranch_scc0 .LBB0_471
	s_cmpk_gt_i32 s41, 0x21f
	s_cbranch_scc0 .LBB0_462
	s_mov_b64 s[6:7], exec
	s_mov_b64 exec, s[10:11]
	v_mov_b32_e32 v241, 1
	s_nop 0
	global_atomic_add v241, v209, v241, s[20:21] sc0
	s_mov_b64 exec, s[6:7]
	s_cmpk_gt_u32 s41, 0xa9f
	s_cbranch_scc0 .LBB0_322
	s_add_i32 s24, s41, 0xfffff560
	s_and_b32 s4, s24, 0xffff
	s_mul_i32 s4, s4, 0xf0f1
	s_lshr_b32 s25, s4, 16
	s_lshr_b32 s4, s4, 23
	s_mulk_i32 s4, 0x88
	s_sub_i32 s4, s24, s4
	s_and_b32 s4, s4, 0xffff
	s_cmp_lt_u32 s4, 8
	s_cselect_b32 s6, 0, -8
	s_mov_b64 s[8:9], s[84:85]
	s_cselect_b32 s46, 0x100, s95
	s_cselect_b32 s47, 0, 0x100
	s_add_i32 s30, s6, s4
	s_add_u32 s6, s8, 0xcc00000
	s_addc_u32 s7, s9, 0
	s_mul_i32 s26, s24, 0x6000
	s_mul_hi_u32 s4, s24, 0x6000
	s_add_u32 s26, s8, s26
	s_addc_u32 s4, s9, s4
	s_mul_i32 s5, s24, 0xf0f1
	s_add_u32 s28, s26, 0x619cf600
	s_addc_u32 s29, s4, 0
	s_bfe_u32 s4, s5, 0x20019
	s_mulk_i32 s4, 0x1100
	s_add_i32 s47, s47, s4
	s_cmpk_gt_u32 s24, 0x87f
	s_cselect_b64 s[26:27], -1, 0
	s_and_b64 s[4:5], s[26:27], exec
	s_cselect_b32 s31, 0x200, 0
	s_and_b32 s50, s25, 0x180
	v_mov_b32_e32 v28, v216
	s_or_b32 s4, s36, s50
	s_or_b32 s4, s4, s31
	v_and_b32_e32 v29, 0x7f, v28
	v_ashrrev_i32_e32 v30, 3, v28
	v_and_b32_e32 v31, -16, v30
	v_or_b32_e32 v208, s4, v29
	s_lshl_b32 s51, s30, 5
	v_lshl_add_u64 v[0:1], v[208:209], 2, s[8:9]
	s_mov_b32 s4, 0x53cc8000
	v_add_u32_e32 v2, s51, v31
	s_cmpk_lt_u32 s24, 0x880
	v_add_co_u32_e32 v0, vcc, s4, v0
	v_xad_u32 v3, v2, -1, s46
	s_cselect_b64 s[4:5], -1, 0
	v_cndmask_b32_e64 v3, v3, v2, s[4:5]
	v_add_u32_e32 v4, s47, v3
	v_ashrrev_i32_e32 v5, 31, v4
	v_lshlrev_b64 v[4:5], 15, v[4:5]
	v_lshl_add_u64 v[4:5], s[6:7], 0, v[4:5]
	s_lshl_b32 s44, s31, 1
	v_lshl_add_u64 v[6:7], v[4:5], 0, s[44:45]
	s_lshl_b32 s30, s50, 1
	s_mov_b32 s31, s45
	v_or_b32_e32 v3, 1, v2
	v_xad_u32 v10, v2, -2, s46
	v_lshl_add_u64 v[6:7], v[6:7], 0, s[30:31]
	v_lshlrev_b32_e32 v208, 1, v29
	v_cndmask_b32_e64 v3, v10, v3, s[4:5]
	v_addc_co_u32_e32 v1, vcc, 0, v1, vcc
	v_lshl_add_u64 v[6:7], v[6:7], 0, v[208:209]
	s_movk_i32 s25, 0x2000
	v_add_u32_e32 v10, s47, v3
	v_add_co_u32_e32 v6, vcc, s25, v6
	v_lshl_add_u64 v[4:5], v[4:5], 0, s[30:31]
	v_ashrrev_i32_e32 v11, 31, v10
	v_addc_co_u32_e32 v7, vcc, 0, v7, vcc
	v_lshl_add_u64 v[4:5], v[4:5], 0, v[208:209]
	v_lshlrev_b64 v[10:11], 15, v[10:11]
	v_add_co_u32_e32 v8, vcc, s95, v4
	v_lshl_add_u64 v[10:11], s[6:7], 0, v[10:11]
	s_nop 0
	v_addc_co_u32_e32 v9, vcc, 0, v5, vcc
	v_lshl_add_u64 v[12:13], v[10:11], 0, s[44:45]
	v_or_b32_e32 v3, 2, v2
	v_xad_u32 v16, v2, -3, s46
	v_add_co_u32_e32 v4, vcc, s25, v4
	v_lshl_add_u64 v[12:13], v[12:13], 0, s[30:31]
	v_cndmask_b32_e64 v3, v16, v3, s[4:5]
	v_addc_co_u32_e32 v5, vcc, 0, v5, vcc
	v_lshl_add_u64 v[12:13], v[12:13], 0, v[208:209]
	v_add_u32_e32 v16, s47, v3
	v_add_co_u32_e32 v12, vcc, s25, v12
	v_lshl_add_u64 v[10:11], v[10:11], 0, s[30:31]
	v_ashrrev_i32_e32 v17, 31, v16
	v_addc_co_u32_e32 v13, vcc, 0, v13, vcc
	v_lshl_add_u64 v[10:11], v[10:11], 0, v[208:209]
	v_lshlrev_b64 v[16:17], 15, v[16:17]
	v_add_co_u32_e32 v14, vcc, s95, v10
	v_lshl_add_u64 v[16:17], s[6:7], 0, v[16:17]
	s_nop 0
	v_addc_co_u32_e32 v15, vcc, 0, v11, vcc
	v_lshl_add_u64 v[18:19], v[16:17], 0, s[44:45]
	v_add_co_u32_e32 v10, vcc, s25, v10
	v_lshl_add_u64 v[18:19], v[18:19], 0, s[30:31]
	s_nop 0
	v_addc_co_u32_e32 v11, vcc, 0, v11, vcc
	v_lshl_add_u64 v[18:19], v[18:19], 0, v[208:209]
	v_add_co_u32_e32 v18, vcc, s25, v18
	s_barrier
	s_nop 0
	v_addc_co_u32_e32 v19, vcc, 0, v19, vcc
	flat_load_ushort v22, v[6:7]
	flat_load_ushort v23, v[8:9] offset:3072
	flat_load_ushort v26, v[4:5] offset:2048
	flat_load_ushort v27, v[12:13]
	flat_load_ushort v32, v[14:15] offset:3072
	flat_load_ushort v33, v[10:11] offset:2048
	flat_load_ushort v34, v[18:19]
	v_or_b32_e32 v3, 3, v2
	v_xad_u32 v8, v2, -4, s46
	v_cndmask_b32_e64 v3, v8, v3, s[4:5]
	v_add_u32_e32 v8, s47, v3
	v_lshl_add_u64 v[4:5], v[16:17], 0, s[30:31]
	v_ashrrev_i32_e32 v9, 31, v8
	v_lshl_add_u64 v[4:5], v[4:5], 0, v[208:209]
	v_lshlrev_b64 v[8:9], 15, v[8:9]
	v_add_co_u32_e32 v6, vcc, s95, v4
	v_lshl_add_u64 v[8:9], s[6:7], 0, v[8:9]
	s_nop 0
	v_addc_co_u32_e32 v7, vcc, 0, v5, vcc
	v_lshl_add_u64 v[10:11], v[8:9], 0, s[44:45]
	v_or_b32_e32 v3, 4, v2
	v_xad_u32 v14, v2, -5, s46
	v_add_co_u32_e32 v4, vcc, s25, v4
	v_lshl_add_u64 v[10:11], v[10:11], 0, s[30:31]
	v_cndmask_b32_e64 v3, v14, v3, s[4:5]
	v_addc_co_u32_e32 v5, vcc, 0, v5, vcc
	v_lshl_add_u64 v[10:11], v[10:11], 0, v[208:209]
	v_add_u32_e32 v14, s47, v3
	v_add_co_u32_e32 v10, vcc, s25, v10
	v_lshl_add_u64 v[8:9], v[8:9], 0, s[30:31]
	v_ashrrev_i32_e32 v15, 31, v14
	v_addc_co_u32_e32 v11, vcc, 0, v11, vcc
	v_lshl_add_u64 v[8:9], v[8:9], 0, v[208:209]
	v_lshlrev_b64 v[14:15], 15, v[14:15]
	v_add_co_u32_e32 v12, vcc, s95, v8
	v_lshl_add_u64 v[14:15], s[6:7], 0, v[14:15]
	s_nop 0
	v_addc_co_u32_e32 v13, vcc, 0, v9, vcc
	v_lshl_add_u64 v[16:17], v[14:15], 0, s[44:45]
	v_add_co_u32_e32 v8, vcc, s25, v8
	v_lshl_add_u64 v[16:17], v[16:17], 0, s[30:31]
	s_nop 0
	v_addc_co_u32_e32 v9, vcc, 0, v9, vcc
	v_lshl_add_u64 v[16:17], v[16:17], 0, v[208:209]
	v_add_co_u32_e32 v16, vcc, s25, v16
	v_lshl_add_u64 v[14:15], v[14:15], 0, s[30:31]
	s_nop 0
	v_addc_co_u32_e32 v17, vcc, 0, v17, vcc
	v_lshl_add_u64 v[14:15], v[14:15], 0, v[208:209]
	v_add_co_u32_e32 v18, vcc, s95, v14
	v_or_b32_e32 v3, 5, v2
	s_nop 0
	v_addc_co_u32_e32 v19, vcc, 0, v15, vcc
	v_add_co_u32_e32 v14, vcc, s25, v14
	s_waitcnt vmcnt(0) lgkmcnt(0)
; DI float bf2f(bfr v) { return __uint_as_float(((unsigned)v) << 16); }
; DI void hg_prep_unit(const Params& p, int l, int unit, unsigned char* smem) {
;     ...
; #pragma unroll
;     for (int i = 0; i < 16; ++i) {
;       const int pos = 32 * m + i0 + i, t = dir ? T - 1 - pos : pos;
;       const size_t row = rowbase + t;
;       KK[i] = bf2f(P[row * PLD + C_HGF + dir * 512 + hd * 128 + dk]);
;       Q[i] = bf2f(P[row * PLD + C_HGQ + hd * 128 + dk]);
;       const unsigned x = P[row * PLD + C_HGI + hd * 128 + dk];
;       if (i & 1) vv[i >> 1] |= x << 16; else vv[i >> 1] = x;
;     }
	v_lshlrev_b32_e32 v74, 16, v22
	v_addc_co_u32_e32 v15, vcc, 0, v15, vcc
	flat_load_ushort v35, v[6:7] offset:3072
	flat_load_ushort v36, v[4:5] offset:2048
	flat_load_ushort v37, v[10:11]
	flat_load_ushort v38, v[12:13] offset:3072
	flat_load_ushort v39, v[8:9] offset:2048
	flat_load_ushort v40, v[16:17]
	flat_load_ushort v44, v[18:19] offset:3072
	flat_load_ushort v45, v[14:15] offset:2048
	v_xad_u32 v4, v2, -6, s46
	v_cndmask_b32_e64 v3, v4, v3, s[4:5]
	v_add_u32_e32 v4, s47, v3
	v_ashrrev_i32_e32 v5, 31, v4
	v_lshlrev_b64 v[4:5], 15, v[4:5]
	v_lshl_add_u64 v[4:5], s[6:7], 0, v[4:5]
	v_lshl_add_u64 v[6:7], v[4:5], 0, s[44:45]
	v_or_b32_e32 v3, 6, v2
	v_xad_u32 v10, v2, -7, s46
	v_lshl_add_u64 v[6:7], v[6:7], 0, s[30:31]
	v_cndmask_b32_e64 v3, v10, v3, s[4:5]
	v_lshl_add_u64 v[6:7], v[6:7], 0, v[208:209]
	v_add_u32_e32 v10, s47, v3
	v_add_co_u32_e32 v6, vcc, s25, v6
	v_lshl_add_u64 v[4:5], v[4:5], 0, s[30:31]
	v_ashrrev_i32_e32 v11, 31, v10
	v_addc_co_u32_e32 v7, vcc, 0, v7, vcc
	v_lshl_add_u64 v[4:5], v[4:5], 0, v[208:209]
	v_lshlrev_b64 v[10:11], 15, v[10:11]
	v_add_co_u32_e32 v8, vcc, s95, v4
	v_lshl_add_u64 v[10:11], s[6:7], 0, v[10:11]
	s_nop 0
	v_addc_co_u32_e32 v9, vcc, 0, v5, vcc
	v_lshl_add_u64 v[12:13], v[10:11], 0, s[44:45]
	v_or_b32_e32 v3, 7, v2
	v_xad_u32 v16, v2, -8, s46
	v_add_co_u32_e32 v4, vcc, s25, v4
	v_lshl_add_u64 v[12:13], v[12:13], 0, s[30:31]
	v_cndmask_b32_e64 v3, v16, v3, s[4:5]
	v_addc_co_u32_e32 v5, vcc, 0, v5, vcc
	v_lshl_add_u64 v[12:13], v[12:13], 0, v[208:209]
	v_add_u32_e32 v16, s47, v3
	v_add_co_u32_e32 v12, vcc, s25, v12
	v_lshl_add_u64 v[10:11], v[10:11], 0, s[30:31]
	v_ashrrev_i32_e32 v17, 31, v16
	v_addc_co_u32_e32 v13, vcc, 0, v13, vcc
	v_lshl_add_u64 v[10:11], v[10:11], 0, v[208:209]
	v_lshlrev_b64 v[16:17], 15, v[16:17]
	v_add_co_u32_e32 v14, vcc, s95, v10
	v_lshl_add_u64 v[16:17], s[6:7], 0, v[16:17]
	s_nop 0
	v_addc_co_u32_e32 v15, vcc, 0, v11, vcc
	v_lshl_add_u64 v[18:19], v[16:17], 0, s[44:45]
	v_add_co_u32_e32 v10, vcc, s25, v10
	v_lshl_add_u64 v[18:19], v[18:19], 0, s[30:31]
	s_nop 0
	v_addc_co_u32_e32 v11, vcc, 0, v11, vcc
	v_lshl_add_u64 v[18:19], v[18:19], 0, v[208:209]
	v_add_co_u32_e32 v18, vcc, s25, v18
	v_lshl_add_u64 v[16:17], v[16:17], 0, s[30:31]
	s_nop 0
	v_addc_co_u32_e32 v19, vcc, 0, v19, vcc
	v_lshl_add_u64 v[16:17], v[16:17], 0, v[208:209]
	v_add_co_u32_e32 v20, vcc, s95, v16
	v_or_b32_e32 v3, 8, v2
	s_nop 0
	v_addc_co_u32_e32 v21, vcc, 0, v17, vcc
	flat_load_ushort v46, v[6:7]
	flat_load_ushort v47, v[8:9] offset:3072
	flat_load_ushort v48, v[4:5] offset:2048
	flat_load_ushort v49, v[12:13]
	flat_load_ushort v50, v[14:15] offset:3072
	flat_load_ushort v51, v[10:11] offset:2048
	flat_load_ushort v52, v[18:19]
	flat_load_ushort v53, v[20:21] offset:3072
	v_xad_u32 v6, v2, -9, s46
	v_cndmask_b32_e64 v3, v6, v3, s[4:5]
	v_add_u32_e32 v6, s47, v3
	v_ashrrev_i32_e32 v7, 31, v6
	v_lshlrev_b64 v[6:7], 15, v[6:7]
	v_lshl_add_u64 v[6:7], s[6:7], 0, v[6:7]
	v_lshl_add_u64 v[8:9], v[6:7], 0, s[44:45]
	v_or_b32_e32 v3, 9, v2
	v_xad_u32 v12, v2, -10, s46
	v_add_co_u32_e32 v4, vcc, s25, v16
	v_lshl_add_u64 v[8:9], v[8:9], 0, s[30:31]
	v_cndmask_b32_e64 v3, v12, v3, s[4:5]
	v_addc_co_u32_e32 v5, vcc, 0, v17, vcc
	v_lshl_add_u64 v[8:9], v[8:9], 0, v[208:209]
	v_add_u32_e32 v12, s47, v3
	v_add_co_u32_e32 v8, vcc, s25, v8
	v_lshl_add_u64 v[6:7], v[6:7], 0, s[30:31]
	v_ashrrev_i32_e32 v13, 31, v12
	v_addc_co_u32_e32 v9, vcc, 0, v9, vcc
	v_lshl_add_u64 v[6:7], v[6:7], 0, v[208:209]
	v_lshlrev_b64 v[12:13], 15, v[12:13]
	v_add_co_u32_e32 v10, vcc, s95, v6
	v_lshl_add_u64 v[12:13], s[6:7], 0, v[12:13]
	s_nop 0
	v_addc_co_u32_e32 v11, vcc, 0, v7, vcc
	v_lshl_add_u64 v[14:15], v[12:13], 0, s[44:45]
	v_or_b32_e32 v3, 10, v2
	v_xad_u32 v18, v2, -11, s46
	v_add_co_u32_e32 v6, vcc, s25, v6
	v_lshl_add_u64 v[14:15], v[14:15], 0, s[30:31]
	v_cndmask_b32_e64 v3, v18, v3, s[4:5]
	v_addc_co_u32_e32 v7, vcc, 0, v7, vcc
	v_lshl_add_u64 v[14:15], v[14:15], 0, v[208:209]
	v_add_u32_e32 v18, s47, v3
	v_add_co_u32_e32 v14, vcc, s25, v14
	v_lshl_add_u64 v[12:13], v[12:13], 0, s[30:31]
	v_ashrrev_i32_e32 v19, 31, v18
	v_addc_co_u32_e32 v15, vcc, 0, v15, vcc
	v_lshl_add_u64 v[12:13], v[12:13], 0, v[208:209]
	v_lshlrev_b64 v[18:19], 15, v[18:19]
	v_add_co_u32_e32 v16, vcc, s95, v12
	v_lshl_add_u64 v[18:19], s[6:7], 0, v[18:19]
	s_nop 0
	v_addc_co_u32_e32 v17, vcc, 0, v13, vcc
	v_lshl_add_u64 v[20:21], v[18:19], 0, s[44:45]
	v_add_co_u32_e32 v12, vcc, s25, v12
	v_lshl_add_u64 v[20:21], v[20:21], 0, s[30:31]
	s_nop 0
	v_addc_co_u32_e32 v13, vcc, 0, v13, vcc
	v_lshl_add_u64 v[20:21], v[20:21], 0, v[208:209]
	v_add_co_u32_e32 v20, vcc, s25, v20
	v_or_b32_e32 v3, 11, v2
	s_nop 0
	v_addc_co_u32_e32 v21, vcc, 0, v21, vcc
	flat_load_ushort v54, v[4:5] offset:2048
	flat_load_ushort v55, v[8:9]
	flat_load_ushort v56, v[10:11] offset:3072
	flat_load_ushort v57, v[6:7] offset:2048
	flat_load_ushort v58, v[14:15]
	flat_load_ushort v59, v[16:17] offset:3072
	flat_load_ushort v60, v[12:13] offset:2048
	s_nop 0
	flat_load_ushort v21, v[20:21]
	v_xad_u32 v8, v2, -12, s46
	v_cndmask_b32_e64 v3, v8, v3, s[4:5]
	v_add_u32_e32 v8, s47, v3
	v_lshl_add_u64 v[4:5], v[18:19], 0, s[30:31]
	v_ashrrev_i32_e32 v9, 31, v8
	v_lshl_add_u64 v[4:5], v[4:5], 0, v[208:209]
	v_lshlrev_b64 v[8:9], 15, v[8:9]
	v_add_co_u32_e32 v6, vcc, s95, v4
	v_lshl_add_u64 v[8:9], s[6:7], 0, v[8:9]
	s_nop 0
	v_addc_co_u32_e32 v7, vcc, 0, v5, vcc
	v_lshl_add_u64 v[10:11], v[8:9], 0, s[44:45]
	v_or_b32_e32 v3, 12, v2
	v_xad_u32 v14, v2, -13, s46
	v_add_co_u32_e32 v4, vcc, s25, v4
	v_lshl_add_u64 v[10:11], v[10:11], 0, s[30:31]
	v_cndmask_b32_e64 v3, v14, v3, s[4:5]
	v_addc_co_u32_e32 v5, vcc, 0, v5, vcc
	v_lshl_add_u64 v[10:11], v[10:11], 0, v[208:209]
	v_add_u32_e32 v14, s47, v3
	v_add_co_u32_e32 v10, vcc, s25, v10
	v_lshl_add_u64 v[8:9], v[8:9], 0, s[30:31]
	v_ashrrev_i32_e32 v15, 31, v14
	v_addc_co_u32_e32 v11, vcc, 0, v11, vcc
	v_lshl_add_u64 v[8:9], v[8:9], 0, v[208:209]
	v_lshlrev_b64 v[14:15], 15, v[14:15]
	v_add_co_u32_e32 v12, vcc, s95, v8
	v_lshl_add_u64 v[14:15], s[6:7], 0, v[14:15]
	s_nop 0
	v_addc_co_u32_e32 v13, vcc, 0, v9, vcc
	v_lshl_add_u64 v[16:17], v[14:15], 0, s[44:45]
	v_add_co_u32_e32 v8, vcc, s25, v8
	v_lshl_add_u64 v[16:17], v[16:17], 0, s[30:31]
	s_nop 0
	v_addc_co_u32_e32 v9, vcc, 0, v9, vcc
	v_lshl_add_u64 v[16:17], v[16:17], 0, v[208:209]
	v_add_co_u32_e32 v16, vcc, s25, v16
	v_lshl_add_u64 v[14:15], v[14:15], 0, s[30:31]
	s_nop 0
	v_addc_co_u32_e32 v17, vcc, 0, v17, vcc
	v_lshl_add_u64 v[14:15], v[14:15], 0, v[208:209]
	v_add_co_u32_e32 v18, vcc, s95, v14
	v_or_b32_e32 v3, 13, v2
	s_nop 0
	v_addc_co_u32_e32 v19, vcc, 0, v15, vcc
	v_add_co_u32_e32 v14, vcc, s25, v14
	s_waitcnt vmcnt(0) lgkmcnt(0)
; DI float bf2f(bfr v) { return __uint_as_float(((unsigned)v) << 16); }
; DI float sigmoidf_(float x) { return 1.f / (1.f + __expf(-x)); }
; DI void hg_prep_unit(const Params& p, int l, int unit, unsigned char* smem) {
;     ...
;     const float lbv = ((const float*)(WS_ + O_LB))[(l * 2 + dir) * 512 + hd * 128 + dk];
;     float G[16], KK[16], Q[16];
;     unsigned vv[8];
; #pragma unroll
;     for (int i = 0; i < 16; ++i) {
;       const int pos = 32 * m + i0 + i, t = dir ? T - 1 - pos : pos;
;       const size_t row = rowbase + t;
;       KK[i] = bf2f(P[row * PLD + C_HGF + dir * 512 + hd * 128 + dk]);
;       Q[i] = bf2f(P[row * PLD + C_HGQ + hd * 128 + dk]);
;       const unsigned x = P[row * PLD + C_HGI + hd * 128 + dk];
;       if (i & 1) vv[i >> 1] |= x << 16; else vv[i >> 1] = x;
;     }
;     float cum = 0.f;
; #pragma unroll
;     for (int i = 0; i < 16; ++i) {
;       const float kkv = fminf((1.f - lbv) * sigmoidf_(-KK[i]), 0.9999999f);
;       KK[i] = kkv;
	v_lshlrev_b32_e32 v41, 16, v38
	v_addc_co_u32_e32 v15, vcc, 0, v15, vcc
	flat_load_ushort v61, v[6:7] offset:3072
	flat_load_ushort v62, v[4:5] offset:2048
	flat_load_ushort v63, v[10:11]
	flat_load_ushort v64, v[12:13] offset:3072
	flat_load_ushort v65, v[8:9] offset:2048
	s_nop 0
	flat_load_ushort v17, v[16:17]
	s_nop 0
	flat_load_ushort v66, v[18:19] offset:3072
	flat_load_ushort v67, v[14:15] offset:2048
	v_xad_u32 v4, v2, -14, s46
	v_cndmask_b32_e64 v3, v4, v3, s[4:5]
	v_add_u32_e32 v4, s47, v3
	v_ashrrev_i32_e32 v5, 31, v4
	v_lshlrev_b64 v[4:5], 15, v[4:5]
	v_or_b32_e32 v3, 14, v2
	v_xad_u32 v10, v2, -15, s46
	v_lshl_add_u64 v[4:5], s[6:7], 0, v[4:5]
	v_cndmask_b32_e64 v3, v10, v3, s[4:5]
	v_lshl_add_u64 v[6:7], v[4:5], 0, s[44:45]
	v_add_u32_e32 v10, s47, v3
	v_lshl_add_u64 v[6:7], v[6:7], 0, s[30:31]
	v_ashrrev_i32_e32 v11, 31, v10
	v_lshl_add_u64 v[6:7], v[6:7], 0, v[208:209]
	v_lshlrev_b64 v[10:11], 15, v[10:11]
	v_or_b32_e32 v3, 15, v2
	v_xad_u32 v2, v2, -16, s46
	v_add_co_u32_e32 v6, vcc, s25, v6
	v_lshl_add_u64 v[4:5], v[4:5], 0, s[30:31]
	v_lshl_add_u64 v[10:11], s[6:7], 0, v[10:11]
	v_cndmask_b32_e64 v2, v2, v3, s[4:5]
	v_addc_co_u32_e32 v7, vcc, 0, v7, vcc
	v_lshl_add_u64 v[8:9], v[4:5], 0, v[208:209]
	v_lshl_add_u64 v[12:13], v[10:11], 0, s[44:45]
	v_add_u32_e32 v2, s47, v2
	v_add_co_u32_e32 v4, vcc, s25, v8
	v_lshl_add_u64 v[12:13], v[12:13], 0, s[30:31]
	v_ashrrev_i32_e32 v3, 31, v2
	v_addc_co_u32_e32 v5, vcc, 0, v9, vcc
	v_lshl_add_u64 v[12:13], v[12:13], 0, v[208:209]
	v_lshlrev_b64 v[2:3], 15, v[2:3]
	v_add_co_u32_e32 v12, vcc, s25, v12
	v_lshl_add_u64 v[10:11], v[10:11], 0, s[30:31]
	v_lshl_add_u64 v[2:3], s[6:7], 0, v[2:3]
	v_addc_co_u32_e32 v13, vcc, 0, v13, vcc
	v_lshl_add_u64 v[24:25], v[10:11], 0, v[208:209]
	v_lshl_add_u64 v[14:15], v[2:3], 0, s[44:45]
	v_add_co_u32_e32 v10, vcc, s25, v24
	v_lshl_add_u64 v[14:15], v[14:15], 0, s[30:31]
	s_nop 0
	v_addc_co_u32_e32 v11, vcc, 0, v25, vcc
	v_lshl_add_u64 v[14:15], v[14:15], 0, v[208:209]
	v_add_co_u32_e32 v14, vcc, s25, v14
	v_lshl_add_u64 v[2:3], v[2:3], 0, s[30:31]
	s_nop 0
	v_addc_co_u32_e32 v15, vcc, 0, v15, vcc
	flat_load_ushort v68, v[6:7]
	flat_load_ushort v69, v[4:5] offset:2048
	flat_load_ushort v70, v[12:13]
	s_nop 0
	flat_load_ushort v10, v[10:11] offset:2048
	s_nop 0
	flat_load_ushort v71, v[14:15]
	v_lshl_add_u64 v[6:7], v[2:3], 0, v[208:209]
	v_add_co_u32_e32 v2, vcc, s25, v6
	v_lshlrev_b32_e32 v12, 16, v40
	s_nop 0
	v_addc_co_u32_e32 v3, vcc, 0, v7, vcc
	flat_load_ushort v72, v[2:3] offset:2048
	flat_load_dword v73, v[0:1]
	v_add_co_u32_e32 v8, vcc, s95, v8
	v_lshlrev_b32_e32 v40, 16, v44
	s_nop 0
	v_addc_co_u32_e32 v9, vcc, 0, v9, vcc
	v_add_co_u32_e32 v24, vcc, s95, v24
	v_lshlrev_b32_e32 v14, 16, v46
	s_nop 0
	v_addc_co_u32_e32 v25, vcc, 0, v25, vcc
	v_add_co_u32_e32 v6, vcc, s95, v6
	v_lshl_or_b32 v2, v48, 16, v45
	s_nop 0
	v_addc_co_u32_e32 v7, vcc, 0, v7, vcc
	flat_load_ushort v44, v[6:7] offset:3072
	flat_load_ushort v45, v[24:25] offset:3072
	flat_load_ushort v46, v[8:9] offset:3072
	v_mul_f32_e32 v6, 0x3fb8aa3b, v74
	v_exp_f32_e32 v7, v6
	s_waitcnt vmcnt(0) lgkmcnt(0)
	v_lshlrev_b32_e32 v22, 16, v17
	v_lshl_or_b32 v1, v39, 16, v36
	v_lshlrev_b32_e32 v39, 16, v47
	v_add_f32_e32 v8, 1.0, v7
	v_div_scale_f32 v9, s[6:7], v8, v8, 1.0
	v_rcp_f32_e32 v17, v9
	v_lshlrev_b32_e32 v13, 16, v49
	s_mov_b32 s25, 0x3f2aaaab
	v_lshlrev_b32_e32 v38, 16, v50
	v_lshlrev_b32_e32 v36, 16, v56
	v_lshl_or_b32 v4, v60, 16, v57
	v_lshlrev_b32_e32 v15, 16, v52
	v_lshl_or_b32 v3, v54, 16, v51
	v_lshlrev_b32_e32 v11, 16, v37
	v_lshlrev_b32_e32 v37, 16, v53
	v_lshlrev_b32_e32 v18, 16, v55
	v_lshlrev_b32_e32 v20, 16, v58
	s_mov_b32 s30, 0x3f317218
	v_lshlrev_b32_e32 v16, 16, v35
	v_lshlrev_b32_e32 v35, 16, v59
	v_lshlrev_b32_e32 v75, 16, v34
	v_lshlrev_b32_e32 v34, 16, v61
	v_lshlrev_b32_e32 v27, 16, v27
	s_mov_b32 s31, 0xff800000
	s_mov_b32 s44, 0x33800000
	v_lshlrev_b32_e32 v19, 16, v21
	v_lshlrev_b32_e32 v21, 16, v63
	v_lshl_or_b32 v5, v65, 16, v62
	v_mul_f32_e32 v11, 0x3fb8aa3b, v11
	v_exp_f32_e32 v11, v11
	v_mul_f32_e32 v12, 0x3fb8aa3b, v12
	v_exp_f32_e32 v12, v12
	v_mul_f32_e32 v14, 0x3fb8aa3b, v14
	v_add_f32_e32 v11, 1.0, v11
	v_exp_f32_e32 v14, v14
	v_add_f32_e32 v12, 1.0, v12
	v_lshl_or_b32 v0, v33, 16, v26
	v_lshlrev_b32_e32 v33, 16, v64
	v_add_f32_e32 v14, 1.0, v14
	v_mul_f32_e32 v13, 0x3fb8aa3b, v13
	v_exp_f32_e32 v13, v13
	v_mul_f32_e32 v15, 0x3fb8aa3b, v15
	v_exp_f32_e32 v15, v15
	v_lshlrev_b32_e32 v42, 16, v32
	v_add_f32_e32 v13, 1.0, v13
	v_lshlrev_b32_e32 v32, 16, v66
	v_add_f32_e32 v15, 1.0, v15
	v_mul_f32_e32 v18, 0x3fb8aa3b, v18
	v_exp_f32_e32 v18, v18
	v_mul_f32_e32 v20, 0x3fb8aa3b, v20
	v_lshl_or_b32 v6, v69, 16, v67
	v_exp_f32_e32 v20, v20
	v_add_f32_e32 v18, 1.0, v18
	v_lshlrev_b32_e32 v24, 16, v68
	v_mul_f32_e32 v19, 0x3fb8aa3b, v19
	v_add_f32_e32 v20, 1.0, v20
	v_exp_f32_e32 v19, v19
	v_lshlrev_b32_e32 v43, 16, v23
	v_lshlrev_b32_e32 v23, 16, v70
	v_lshl_or_b32 v7, v72, 16, v10
	v_fma_f32 v10, -v9, v17, 1.0
	v_fmac_f32_e32 v17, v10, v17
	v_div_scale_f32 v10, vcc, 1.0, v8, 1.0
	v_mul_f32_e32 v47, v10, v17
	v_fma_f32 v48, -v9, v47, v10
	v_fmac_f32_e32 v47, v48, v17
	v_fma_f32 v9, -v9, v47, v10
	v_div_fmas_f32 v9, v9, v17, v47
	v_sub_f32_e32 v25, 1.0, v73
	v_div_fixup_f32 v8, v9, v8, 1.0
	v_mul_f32_e32 v8, v25, v8
	v_min_f32_e32 v8, 0x3f7ffffe, v8
	v_sub_f32_e32 v9, 1.0, v8
	v_add_f32_e32 v10, -1.0, v9
	v_sub_f32_e32 v17, v10, v9
	v_add_f32_e32 v17, 1.0, v17
	v_sub_f32_e64 v10, -v8, v10
	v_add_f32_e32 v10, v10, v17
	v_frexp_mant_f32_e32 v17, v9
	v_cvt_f64_f32_e32 v[48:49], v9
	v_frexp_exp_i32_f64_e32 v47, v[48:49]
	v_cmp_gt_f32_e32 vcc, s25, v17
; DI float sigmoidf_(float x) { return 1.f / (1.f + __expf(-x)); }
; DI void hg_prep_unit(const Params& p, int l, int unit, unsigned char* smem) {
;     ...
;     float cum = 0.f;
; #pragma unroll
;     for (int i = 0; i < 16; ++i) {
;       const float kkv = fminf((1.f - lbv) * sigmoidf_(-KK[i]), 0.9999999f);
;       KK[i] = kkv;
;       cum += log1pf(-kkv);
;       G[i] = cum;
;     }
	v_add_f32_e32 v19, 1.0, v19
	v_lshlrev_b32_e32 v26, 16, v71
	v_subbrev_co_u32_e32 v17, vcc, 0, v47, vcc
	v_sub_u32_e32 v47, 0, v17
	v_ldexp_f32 v9, v9, v47
	v_ldexp_f32 v10, v10, v47
	v_add_f32_e32 v47, -1.0, v9
	v_add_f32_e32 v49, 1.0, v9
	v_add_f32_e32 v48, 1.0, v47
	v_add_f32_e32 v50, -1.0, v49
	v_sub_f32_e32 v48, v9, v48
	v_sub_f32_e32 v9, v9, v50
	v_add_f32_e32 v9, v10, v9
	v_add_f32_e32 v48, v10, v48
	v_add_f32_e32 v10, v49, v9
	v_rcp_f32_e32 v56, v10
	v_sub_f32_e32 v49, v10, v49
	v_sub_f32_e32 v9, v9, v49
	v_add_f32_e32 v49, v47, v48
	v_mul_f32_e32 v57, v49, v56
	v_mul_f32_e32 v50, v10, v57
	v_fma_f32 v52, v57, v10, -v50
	v_sub_f32_e32 v47, v49, v47
	v_fmac_f32_e32 v52, v57, v9
	v_sub_f32_e32 v47, v48, v47
	v_add_f32_e32 v48, v50, v52
	v_sub_f32_e32 v51, v49, v48
	v_pk_add_f32 v[54:55], v[48:49], v[50:51] neg_lo:[0,1] neg_hi:[0,1]
	v_mov_b32_e32 v53, v48
	v_pk_add_f32 v[48:49], v[54:55], v[52:53] neg_lo:[0,1] neg_hi:[0,1]
	v_cmp_neq_f32_e32 vcc, s31, v8
	v_add_f32_e32 v47, v47, v49
	v_add_f32_e32 v47, v48, v47
	v_add_f32_e32 v49, v51, v47
	v_mul_f32_e32 v58, v56, v49
	v_mul_f32_e32 v50, v10, v58
	v_fma_f32 v52, v58, v10, -v50
	v_fmac_f32_e32 v52, v58, v9
	v_add_f32_e32 v48, v50, v52
	v_sub_f32_e32 v9, v51, v49
	v_sub_f32_e32 v51, v49, v48
	v_pk_add_f32 v[54:55], v[48:49], v[50:51] neg_lo:[0,1] neg_hi:[0,1]
	v_mov_b32_e32 v53, v48
	v_add_f32_e32 v9, v47, v9
	v_pk_add_f32 v[48:49], v[54:55], v[52:53] neg_lo:[0,1] neg_hi:[0,1]
	v_add_f32_e32 v10, v57, v58
	v_add_f32_e32 v9, v9, v49
	v_add_f32_e32 v9, v48, v9
	v_add_f32_e32 v9, v51, v9
	v_sub_f32_e32 v47, v10, v57
	v_mul_f32_e32 v9, v56, v9
	v_sub_f32_e32 v47, v58, v47
	v_add_f32_e32 v9, v47, v9
	v_add_f32_e32 v47, v10, v9
	v_mul_f32_e32 v49, v47, v47
	v_fmamk_f32 v48, v49, 0x3e9b6dac, v212
	v_fmaak_f32 v211, v49, v48, 0x3f2aaada
	v_cvt_f32_i32_e32 v48, v17
	v_mul_f32_e32 v49, v47, v49
	v_ldexp_f32 v51, v47, 1
	v_sub_f32_e32 v10, v47, v10
	v_pk_mul_f32 v[52:53], v[48:49], v[210:211]
	v_sub_f32_e32 v9, v9, v10
	v_fma_f32 v50, v48, s30, -v52
	v_fmac_f32_e32 v50, 0xb102e308, v48
	v_pk_add_f32 v[48:49], v[52:53], v[50:51]
	v_ldexp_f32 v9, v9, 1
	v_sub_f32_e32 v10, v49, v51
	v_sub_f32_e32 v10, v53, v10
	v_add_f32_e32 v55, v9, v10
	v_mov_b32_e32 v54, v52
	v_pk_add_f32 v[52:53], v[48:49], v[52:53] neg_lo:[0,1] neg_hi:[0,1]
	v_pk_add_f32 v[56:57], v[48:49], v[54:55]
	v_mov_b32_e32 v51, v48
	v_mov_b32_e32 v53, v57
	v_pk_add_f32 v[58:59], v[50:51], v[52:53] neg_lo:[0,1] neg_hi:[0,1]
	v_pk_add_f32 v[50:51], v[50:51], v[52:53]
	v_mov_b32_e32 v54, v55
	v_pk_add_f32 v[52:53], v[50:51], v[48:49] op_sel:[1,0] op_sel_hi:[0,1] neg_lo:[0,1] neg_hi:[0,1]
	v_pk_add_f32 v[60:61], v[56:57], v[52:53] op_sel_hi:[1,0] neg_lo:[0,1] neg_hi:[0,1]
	v_mov_b32_e32 v56, v57
	v_mov_b32_e32 v57, v51
	v_pk_mov_b32 v[52:53], v[48:49], v[52:53] op_sel:[1,0]
	v_mov_b32_e32 v55, v48
	v_pk_add_f32 v[52:53], v[56:57], v[52:53] neg_lo:[0,1] neg_hi:[0,1]
	v_mov_b32_e32 v60, v58
	v_pk_add_f32 v[48:49], v[54:55], v[52:53] neg_lo:[0,1] neg_hi:[0,1]
	v_mul_f32_e32 v10, 0x3fb8aa3b, v27
	v_pk_add_f32 v[52:53], v[60:61], v[48:49]
	v_mov_b32_e32 v59, v51
	v_pk_add_f32 v[54:55], v[52:53], v[52:53] op_sel:[0,1] op_sel_hi:[1,0]
	v_exp_f32_e32 v10, v10
	v_pk_add_f32 v[50:51], v[50:51], v[54:55] op_sel:[1,0] op_sel_hi:[0,1]
	v_mov_b32_e32 v53, v50
	v_pk_add_f32 v[56:57], v[52:53], v[58:59] neg_lo:[0,1] neg_hi:[0,1]
	v_mov_b32_e32 v49, v54
	v_sub_f32_e32 v9, v52, v56
	v_pk_add_f32 v[48:49], v[48:49], v[56:57] neg_lo:[0,1] neg_hi:[0,1]
	v_sub_f32_e32 v9, v58, v9
	v_add_f32_e32 v10, 1.0, v10
	v_add_f32_e32 v9, v48, v9
	v_div_scale_f32 v17, s[6:7], v10, v10, 1.0
	v_add_f32_e32 v9, v9, v49
	v_rcp_f32_e32 v27, v17
	v_add_f32_e32 v9, v50, v9
	v_cndmask_b32_e32 v9, v214, v9, vcc
	v_cmp_lt_f32_e64 s[6:7], |v8|, s44
	v_mul_f32_e32 v21, 0x3fb8aa3b, v21
	v_exp_f32_e32 v21, v21
	v_cndmask_b32_e64 v9, v9, -v8, s[6:7]
	v_add_f32_e32 v47, 0, v9
	v_fma_f32 v9, -v17, v27, 1.0
	v_fmac_f32_e32 v27, v9, v27
	v_div_scale_f32 v9, vcc, 1.0, v10, 1.0
	v_mul_f32_e32 v48, v9, v27
	v_fma_f32 v49, -v17, v48, v9
	v_fmac_f32_e32 v48, v49, v27
	v_fma_f32 v9, -v17, v48, v9
	v_div_fmas_f32 v9, v9, v27, v48
	v_div_fixup_f32 v9, v9, v10, 1.0
	v_mul_f32_e32 v9, v25, v9
	v_min_f32_e32 v10, 0x3f7ffffe, v9
	v_sub_f32_e32 v9, 1.0, v10
	v_add_f32_e32 v17, -1.0, v9
	v_sub_f32_e32 v27, v17, v9
	v_add_f32_e32 v27, 1.0, v27
	v_sub_f32_e64 v17, -v10, v17
	v_add_f32_e32 v17, v17, v27
	v_frexp_mant_f32_e32 v27, v9
	v_cvt_f64_f32_e32 v[48:49], v9
	v_frexp_exp_i32_f64_e32 v48, v[48:49]
	v_cmp_gt_f32_e32 vcc, s25, v27
	v_add_f32_e32 v21, 1.0, v21
	v_mul_f32_e32 v22, 0x3fb8aa3b, v22
	v_subbrev_co_u32_e32 v27, vcc, 0, v48, vcc
	v_sub_u32_e32 v48, 0, v27
	v_ldexp_f32 v9, v9, v48
	v_ldexp_f32 v17, v17, v48
	v_add_f32_e32 v48, -1.0, v9
	v_add_f32_e32 v49, 1.0, v48
	v_sub_f32_e32 v49, v9, v49
	v_add_f32_e32 v50, v17, v49
	v_add_f32_e32 v49, 1.0, v9
	v_add_f32_e32 v51, -1.0, v49
	v_sub_f32_e32 v9, v9, v51
	v_add_f32_e32 v9, v17, v9
	v_add_f32_e32 v17, v49, v9
	v_rcp_f32_e32 v56, v17
	v_sub_f32_e32 v49, v17, v49
	v_sub_f32_e32 v9, v9, v49
	v_add_f32_e32 v49, v48, v50
	v_sub_f32_e32 v48, v49, v48
	v_mul_f32_e32 v58, v49, v56
	v_sub_f32_e32 v57, v50, v48
	v_mul_f32_e32 v50, v17, v58
	v_fma_f32 v52, v58, v17, -v50
	v_fmac_f32_e32 v52, v58, v9
	v_add_f32_e32 v48, v50, v52
	v_sub_f32_e32 v51, v49, v48
	v_pk_add_f32 v[54:55], v[48:49], v[50:51] neg_lo:[0,1] neg_hi:[0,1]
	v_mov_b32_e32 v53, v48
	v_pk_add_f32 v[48:49], v[54:55], v[52:53] neg_lo:[0,1] neg_hi:[0,1]
	v_cmp_neq_f32_e32 vcc, s31, v10
	v_add_f32_e32 v49, v57, v49
	v_add_f32_e32 v48, v48, v49
	v_add_f32_e32 v49, v51, v48
	v_mul_f32_e32 v57, v56, v49
; DI float sigmoidf_(float x) { return 1.f / (1.f + __expf(-x)); }
; DI void hg_prep_unit(const Params& p, int l, int unit, unsigned char* smem) {
;     ...
;     float cum = 0.f;
; #pragma unroll
;     for (int i = 0; i < 16; ++i) {
;       const float kkv = fminf((1.f - lbv) * sigmoidf_(-KK[i]), 0.9999999f);
;       KK[i] = kkv;
;       cum += log1pf(-kkv);
;       G[i] = cum;
;     }
	v_mul_f32_e32 v50, v17, v57
	v_fma_f32 v52, v57, v17, -v50
	v_fmac_f32_e32 v52, v57, v9
	v_sub_f32_e32 v9, v51, v49
	v_add_f32_e32 v9, v48, v9
	v_add_f32_e32 v48, v50, v52
	v_sub_f32_e32 v51, v49, v48
	v_pk_add_f32 v[54:55], v[48:49], v[50:51] neg_lo:[0,1] neg_hi:[0,1]
	v_mov_b32_e32 v53, v48
	v_pk_add_f32 v[48:49], v[54:55], v[52:53] neg_lo:[0,1] neg_hi:[0,1]
	v_add_f32_e32 v17, v58, v57
	v_add_f32_e32 v9, v9, v49
	v_add_f32_e32 v9, v48, v9
	v_add_f32_e32 v9, v51, v9
	v_sub_f32_e32 v48, v17, v58
	v_mul_f32_e32 v9, v56, v9
	v_sub_f32_e32 v48, v57, v48
	v_add_f32_e32 v9, v48, v9
	v_add_f32_e32 v49, v17, v9
	v_mul_f32_e32 v50, v49, v49
	v_fmamk_f32 v48, v50, 0x3e9b6dac, v212
	v_fmaak_f32 v211, v50, v48, 0x3f2aaada
	v_cvt_f32_i32_e32 v48, v27
	v_sub_f32_e32 v17, v49, v17
	v_ldexp_f32 v51, v49, 1
	v_mul_f32_e32 v49, v49, v50
	v_pk_mul_f32 v[52:53], v[48:49], v[210:211]
	v_sub_f32_e32 v9, v9, v17
	v_fma_f32 v50, v48, s30, -v52
	v_fmac_f32_e32 v50, 0xb102e308, v48
	v_pk_add_f32 v[48:49], v[52:53], v[50:51]
	v_ldexp_f32 v9, v9, 1
	v_sub_f32_e32 v17, v49, v51
	v_sub_f32_e32 v17, v53, v17
	v_add_f32_e32 v55, v9, v17
	v_mov_b32_e32 v54, v52
	v_pk_add_f32 v[52:53], v[48:49], v[52:53] neg_lo:[0,1] neg_hi:[0,1]
	v_pk_add_f32 v[56:57], v[48:49], v[54:55]
	v_mov_b32_e32 v51, v48
	v_mov_b32_e32 v53, v57
	v_pk_add_f32 v[58:59], v[50:51], v[52:53] neg_lo:[0,1] neg_hi:[0,1]
	v_pk_add_f32 v[50:51], v[50:51], v[52:53]
	v_mov_b32_e32 v54, v55
	v_pk_add_f32 v[52:53], v[50:51], v[48:49] op_sel:[1,0] op_sel_hi:[0,1] neg_lo:[0,1] neg_hi:[0,1]
	v_pk_add_f32 v[60:61], v[56:57], v[52:53] op_sel_hi:[1,0] neg_lo:[0,1] neg_hi:[0,1]
	v_mov_b32_e32 v56, v57
	v_mov_b32_e32 v57, v51
	v_pk_mov_b32 v[52:53], v[48:49], v[52:53] op_sel:[1,0]
	v_mov_b32_e32 v55, v48
	v_pk_add_f32 v[52:53], v[56:57], v[52:53] neg_lo:[0,1] neg_hi:[0,1]
	v_mov_b32_e32 v60, v58
	v_pk_add_f32 v[48:49], v[54:55], v[52:53] neg_lo:[0,1] neg_hi:[0,1]
	v_mul_f32_e32 v17, 0x3fb8aa3b, v75
	v_pk_add_f32 v[52:53], v[60:61], v[48:49]
	v_mov_b32_e32 v59, v51
	v_pk_add_f32 v[54:55], v[52:53], v[52:53] op_sel:[0,1] op_sel_hi:[1,0]
	v_exp_f32_e32 v17, v17
	v_pk_add_f32 v[50:51], v[50:51], v[54:55] op_sel:[1,0] op_sel_hi:[0,1]
	v_mov_b32_e32 v53, v50
	v_pk_add_f32 v[56:57], v[52:53], v[58:59] neg_lo:[0,1] neg_hi:[0,1]
	v_mov_b32_e32 v49, v54
	v_sub_f32_e32 v9, v52, v56
	v_pk_add_f32 v[48:49], v[48:49], v[56:57] neg_lo:[0,1] neg_hi:[0,1]
	v_sub_f32_e32 v9, v58, v9
	v_add_f32_e32 v17, 1.0, v17
	v_add_f32_e32 v9, v48, v9
	v_div_scale_f32 v27, s[6:7], v17, v17, 1.0
	v_add_f32_e32 v9, v9, v49
	v_rcp_f32_e32 v49, v27
	v_add_f32_e32 v9, v50, v9
	v_cndmask_b32_e32 v9, v214, v9, vcc
	v_cmp_lt_f32_e64 s[6:7], |v10|, s44
	v_exp_f32_e32 v22, v22
	v_mul_f32_e32 v24, 0x3fb8aa3b, v24
	v_cndmask_b32_e64 v9, v9, -v10, s[6:7]
	v_add_f32_e32 v48, v47, v9
	v_fma_f32 v9, -v27, v49, 1.0
	v_fmac_f32_e32 v49, v9, v49
	v_div_scale_f32 v9, vcc, 1.0, v17, 1.0
	v_mul_f32_e32 v50, v9, v49
	v_fma_f32 v51, -v27, v50, v9
	v_fmac_f32_e32 v50, v51, v49
	v_fma_f32 v9, -v27, v50, v9
	v_div_fmas_f32 v9, v9, v49, v50
	v_div_fixup_f32 v9, v9, v17, 1.0
	v_mul_f32_e32 v9, v25, v9
	v_min_f32_e32 v9, 0x3f7ffffe, v9
	v_sub_f32_e32 v17, 1.0, v9
	v_add_f32_e32 v27, -1.0, v17
	v_sub_f32_e32 v49, v27, v17
	v_add_f32_e32 v49, 1.0, v49
	v_sub_f32_e64 v27, -v9, v27
	v_add_f32_e32 v27, v27, v49
	v_frexp_mant_f32_e32 v49, v17
	v_cvt_f64_f32_e32 v[50:51], v17
	v_frexp_exp_i32_f64_e32 v50, v[50:51]
	v_cmp_gt_f32_e32 vcc, s25, v49
	v_add_f32_e32 v22, 1.0, v22
	v_exp_f32_e32 v24, v24
	v_subbrev_co_u32_e32 v49, vcc, 0, v50, vcc
	v_sub_u32_e32 v50, 0, v49
	v_ldexp_f32 v17, v17, v50
	v_ldexp_f32 v27, v27, v50
	v_add_f32_e32 v50, -1.0, v17
	v_add_f32_e32 v51, 1.0, v50
	v_sub_f32_e32 v51, v17, v51
	v_add_f32_e32 v52, v27, v51
	v_add_f32_e32 v51, 1.0, v17
	v_add_f32_e32 v53, -1.0, v51
	v_sub_f32_e32 v17, v17, v53
	v_add_f32_e32 v17, v27, v17
	v_add_f32_e32 v27, v51, v17
	v_rcp_f32_e32 v58, v27
	v_sub_f32_e32 v51, v27, v51
	v_sub_f32_e32 v17, v17, v51
	v_add_f32_e32 v51, v50, v52
	v_sub_f32_e32 v50, v51, v50
	v_mul_f32_e32 v60, v51, v58
	v_sub_f32_e32 v59, v52, v50
	v_mul_f32_e32 v52, v27, v60
	v_fma_f32 v54, v60, v27, -v52
	v_fmac_f32_e32 v54, v60, v17
	v_add_f32_e32 v50, v52, v54
	v_sub_f32_e32 v53, v51, v50
	v_pk_add_f32 v[56:57], v[50:51], v[52:53] neg_lo:[0,1] neg_hi:[0,1]
	v_mov_b32_e32 v55, v50
	v_pk_add_f32 v[50:51], v[56:57], v[54:55] neg_lo:[0,1] neg_hi:[0,1]
	v_cmp_neq_f32_e32 vcc, s31, v9
	v_add_f32_e32 v51, v59, v51
	v_add_f32_e32 v50, v50, v51
	v_add_f32_e32 v51, v53, v50
	v_mul_f32_e32 v59, v58, v51
	v_mul_f32_e32 v52, v27, v59
	v_fma_f32 v54, v59, v27, -v52
	v_fmac_f32_e32 v54, v59, v17
	v_sub_f32_e32 v17, v53, v51
	v_add_f32_e32 v17, v50, v17
	v_add_f32_e32 v50, v52, v54
	v_sub_f32_e32 v53, v51, v50
	v_pk_add_f32 v[56:57], v[50:51], v[52:53] neg_lo:[0,1] neg_hi:[0,1]
	v_mov_b32_e32 v55, v50
	v_pk_add_f32 v[50:51], v[56:57], v[54:55] neg_lo:[0,1] neg_hi:[0,1]
	v_add_f32_e32 v27, v60, v59
	v_add_f32_e32 v17, v17, v51
	v_add_f32_e32 v17, v50, v17
	v_add_f32_e32 v17, v53, v17
	v_sub_f32_e32 v50, v27, v60
	v_mul_f32_e32 v17, v58, v17
	v_sub_f32_e32 v50, v59, v50
	v_add_f32_e32 v17, v50, v17
	v_add_f32_e32 v51, v27, v17
	v_mul_f32_e32 v52, v51, v51
	v_fmamk_f32 v50, v52, 0x3e9b6dac, v212
	v_fmaak_f32 v211, v52, v50, 0x3f2aaada
	v_cvt_f32_i32_e32 v50, v49
	v_sub_f32_e32 v27, v51, v27
	v_ldexp_f32 v53, v51, 1
	v_mul_f32_e32 v51, v51, v52
	v_pk_mul_f32 v[54:55], v[50:51], v[210:211]
	v_sub_f32_e32 v17, v17, v27
	v_fma_f32 v52, v50, s30, -v54
	v_fmac_f32_e32 v52, 0xb102e308, v50
	v_pk_add_f32 v[50:51], v[54:55], v[52:53]
	v_ldexp_f32 v17, v17, 1
	v_sub_f32_e32 v27, v51, v53
; DI float sigmoidf_(float x) { return 1.f / (1.f + __expf(-x)); }
; DI void hg_prep_unit(const Params& p, int l, int unit, unsigned char* smem) {
;     ...
;     float cum = 0.f;
; #pragma unroll
;     for (int i = 0; i < 16; ++i) {
;       const float kkv = fminf((1.f - lbv) * sigmoidf_(-KK[i]), 0.9999999f);
;       KK[i] = kkv;
;       cum += log1pf(-kkv);
;       G[i] = cum;
;     }
	v_sub_f32_e32 v27, v55, v27
	v_add_f32_e32 v57, v17, v27
	v_mov_b32_e32 v56, v54
	v_pk_add_f32 v[54:55], v[50:51], v[54:55] neg_lo:[0,1] neg_hi:[0,1]
	v_pk_add_f32 v[58:59], v[50:51], v[56:57]
	v_mov_b32_e32 v53, v50
	v_mov_b32_e32 v55, v59
	v_pk_add_f32 v[60:61], v[52:53], v[54:55] neg_lo:[0,1] neg_hi:[0,1]
	v_pk_add_f32 v[52:53], v[52:53], v[54:55]
	v_mov_b32_e32 v56, v57
	v_pk_add_f32 v[54:55], v[52:53], v[50:51] op_sel:[1,0] op_sel_hi:[0,1] neg_lo:[0,1] neg_hi:[0,1]
	v_pk_add_f32 v[62:63], v[58:59], v[54:55] op_sel_hi:[1,0] neg_lo:[0,1] neg_hi:[0,1]
	v_mov_b32_e32 v58, v59
	v_mov_b32_e32 v59, v53
	v_pk_mov_b32 v[54:55], v[50:51], v[54:55] op_sel:[1,0]
	v_mov_b32_e32 v57, v50
	v_pk_add_f32 v[54:55], v[58:59], v[54:55] neg_lo:[0,1] neg_hi:[0,1]
	v_mov_b32_e32 v62, v60
	v_pk_add_f32 v[50:51], v[56:57], v[54:55] neg_lo:[0,1] neg_hi:[0,1]
	v_mov_b32_e32 v61, v53
	v_pk_add_f32 v[54:55], v[62:63], v[50:51]
	v_div_scale_f32 v27, s[6:7], v11, v11, 1.0
	v_pk_add_f32 v[56:57], v[54:55], v[54:55] op_sel:[0,1] op_sel_hi:[1,0]
	v_cmp_lt_f32_e64 s[6:7], |v9|, s44
	v_pk_add_f32 v[52:53], v[52:53], v[56:57] op_sel:[1,0] op_sel_hi:[0,1]
	v_mov_b32_e32 v55, v52
	v_pk_add_f32 v[58:59], v[54:55], v[60:61] neg_lo:[0,1] neg_hi:[0,1]
	v_mov_b32_e32 v51, v56
	v_sub_f32_e32 v17, v54, v58
	v_pk_add_f32 v[50:51], v[50:51], v[58:59] neg_lo:[0,1] neg_hi:[0,1]
	v_sub_f32_e32 v17, v60, v17
	v_add_f32_e32 v17, v50, v17
	v_add_f32_e32 v17, v17, v51
	v_rcp_f32_e32 v50, v27
	v_add_f32_e32 v17, v52, v17
	v_cndmask_b32_e32 v17, v214, v17, vcc
	v_cndmask_b32_e64 v17, v17, -v9, s[6:7]
	v_add_f32_e32 v49, v48, v17
	v_fma_f32 v17, -v27, v50, 1.0
	v_fmac_f32_e32 v50, v17, v50
	v_div_scale_f32 v17, vcc, 1.0, v11, 1.0
	v_mul_f32_e32 v51, v17, v50
	v_fma_f32 v52, -v27, v51, v17
	v_fmac_f32_e32 v51, v52, v50
	v_fma_f32 v17, -v27, v51, v17
	v_div_fmas_f32 v17, v17, v50, v51
	v_div_fixup_f32 v11, v17, v11, 1.0
	v_mul_f32_e32 v11, v25, v11
	v_min_f32_e32 v11, 0x3f7ffffe, v11
	v_sub_f32_e32 v17, 1.0, v11
	v_add_f32_e32 v27, -1.0, v17
	v_sub_f32_e32 v50, v27, v17
	v_add_f32_e32 v50, 1.0, v50
	v_sub_f32_e64 v27, -v11, v27
	v_add_f32_e32 v27, v27, v50
	v_frexp_mant_f32_e32 v52, v17
	v_cvt_f64_f32_e32 v[50:51], v17
	v_frexp_exp_i32_f64_e32 v50, v[50:51]
	v_cmp_gt_f32_e32 vcc, s25, v52
	v_add_f32_e32 v24, 1.0, v24
	v_mul_f32_e32 v23, 0x3fb8aa3b, v23
	v_subbrev_co_u32_e32 v58, vcc, 0, v50, vcc
	v_sub_u32_e32 v50, 0, v58
	v_ldexp_f32 v17, v17, v50
	v_ldexp_f32 v27, v27, v50
	v_add_f32_e32 v50, -1.0, v17
	v_add_f32_e32 v51, 1.0, v50
	v_sub_f32_e32 v51, v17, v51
	v_add_f32_e32 v52, v27, v51
	v_add_f32_e32 v51, 1.0, v17
	v_add_f32_e32 v53, -1.0, v51
	v_sub_f32_e32 v17, v17, v53
	v_add_f32_e32 v17, v27, v17
	v_add_f32_e32 v27, v51, v17
	v_rcp_f32_e32 v59, v27
	v_sub_f32_e32 v51, v27, v51
	v_sub_f32_e32 v17, v17, v51
	v_add_f32_e32 v51, v50, v52
	v_sub_f32_e32 v50, v51, v50
	v_mul_f32_e32 v61, v51, v59
	v_sub_f32_e32 v60, v52, v50
	v_mul_f32_e32 v52, v27, v61
	v_fma_f32 v54, v61, v27, -v52
	v_fmac_f32_e32 v54, v61, v17
	v_add_f32_e32 v50, v52, v54
	v_sub_f32_e32 v53, v51, v50
	v_pk_add_f32 v[56:57], v[50:51], v[52:53] neg_lo:[0,1] neg_hi:[0,1]
	v_mov_b32_e32 v55, v50
	v_pk_add_f32 v[50:51], v[56:57], v[54:55] neg_lo:[0,1] neg_hi:[0,1]
	v_cmp_neq_f32_e32 vcc, s31, v11
	v_add_f32_e32 v51, v60, v51
	v_add_f32_e32 v50, v50, v51
	v_add_f32_e32 v51, v53, v50
	v_mul_f32_e32 v60, v59, v51
	v_mul_f32_e32 v52, v27, v60
	v_fma_f32 v54, v60, v27, -v52
	v_fmac_f32_e32 v54, v60, v17
	v_sub_f32_e32 v17, v53, v51
	v_add_f32_e32 v17, v50, v17
	v_add_f32_e32 v50, v52, v54
	v_sub_f32_e32 v53, v51, v50
	v_pk_add_f32 v[56:57], v[50:51], v[52:53] neg_lo:[0,1] neg_hi:[0,1]
	v_mov_b32_e32 v55, v50
	v_pk_add_f32 v[50:51], v[56:57], v[54:55] neg_lo:[0,1] neg_hi:[0,1]
	v_add_f32_e32 v27, v61, v60
	v_add_f32_e32 v17, v17, v51
	v_add_f32_e32 v17, v50, v17
	v_add_f32_e32 v17, v53, v17
	v_sub_f32_e32 v50, v27, v61
	v_mul_f32_e32 v17, v59, v17
	v_sub_f32_e32 v50, v60, v50
	v_add_f32_e32 v17, v50, v17
	v_add_f32_e32 v51, v27, v17
	v_mul_f32_e32 v52, v51, v51
	v_fmamk_f32 v50, v52, 0x3e9b6dac, v212
	v_fmaak_f32 v211, v52, v50, 0x3f2aaada
	v_cvt_f32_i32_e32 v50, v58
	v_sub_f32_e32 v27, v51, v27
	v_ldexp_f32 v53, v51, 1
	v_mul_f32_e32 v51, v51, v52
	v_pk_mul_f32 v[54:55], v[50:51], v[210:211]
	v_sub_f32_e32 v17, v17, v27
	v_fma_f32 v52, v50, s30, -v54
	v_fmac_f32_e32 v52, 0xb102e308, v50
	v_pk_add_f32 v[50:51], v[54:55], v[52:53]
	v_ldexp_f32 v17, v17, 1
	v_sub_f32_e32 v27, v51, v53
	v_sub_f32_e32 v27, v55, v27
	v_add_f32_e32 v57, v17, v27
	v_mov_b32_e32 v56, v54
	v_pk_add_f32 v[54:55], v[50:51], v[54:55] neg_lo:[0,1] neg_hi:[0,1]
	v_pk_add_f32 v[58:59], v[50:51], v[56:57]
	v_mov_b32_e32 v53, v50
	v_mov_b32_e32 v55, v59
	v_pk_add_f32 v[60:61], v[52:53], v[54:55] neg_lo:[0,1] neg_hi:[0,1]
	v_pk_add_f32 v[52:53], v[52:53], v[54:55]
	v_mov_b32_e32 v56, v57
	v_pk_add_f32 v[54:55], v[52:53], v[50:51] op_sel:[1,0] op_sel_hi:[0,1] neg_lo:[0,1] neg_hi:[0,1]
	v_pk_add_f32 v[62:63], v[58:59], v[54:55] op_sel_hi:[1,0] neg_lo:[0,1] neg_hi:[0,1]
	v_mov_b32_e32 v58, v59
	v_mov_b32_e32 v59, v53
	v_pk_mov_b32 v[54:55], v[50:51], v[54:55] op_sel:[1,0]
	v_mov_b32_e32 v57, v50
	v_pk_add_f32 v[54:55], v[58:59], v[54:55] neg_lo:[0,1] neg_hi:[0,1]
	v_mov_b32_e32 v62, v60
	v_pk_add_f32 v[50:51], v[56:57], v[54:55] neg_lo:[0,1] neg_hi:[0,1]
	v_mov_b32_e32 v61, v53
	v_pk_add_f32 v[54:55], v[62:63], v[50:51]
	v_div_scale_f32 v27, s[6:7], v12, v12, 1.0
	v_pk_add_f32 v[56:57], v[54:55], v[54:55] op_sel:[0,1] op_sel_hi:[1,0]
	v_cmp_lt_f32_e64 s[6:7], |v11|, s44
	v_pk_add_f32 v[52:53], v[52:53], v[56:57] op_sel:[1,0] op_sel_hi:[0,1]
	v_mov_b32_e32 v55, v52
; DI float sigmoidf_(float x) { return 1.f / (1.f + __expf(-x)); }
; DI void hg_prep_unit(const Params& p, int l, int unit, unsigned char* smem) {
;     ...
;     float cum = 0.f;
; #pragma unroll
;     for (int i = 0; i < 16; ++i) {
;       const float kkv = fminf((1.f - lbv) * sigmoidf_(-KK[i]), 0.9999999f);
;       KK[i] = kkv;
;       cum += log1pf(-kkv);
;       G[i] = cum;
;     }
	v_pk_add_f32 v[58:59], v[54:55], v[60:61] neg_lo:[0,1] neg_hi:[0,1]
	v_mov_b32_e32 v51, v56
	v_sub_f32_e32 v17, v54, v58
	v_pk_add_f32 v[50:51], v[50:51], v[58:59] neg_lo:[0,1] neg_hi:[0,1]
	v_sub_f32_e32 v17, v60, v17
	v_add_f32_e32 v17, v50, v17
	v_rcp_f32_e32 v50, v27
	v_add_f32_e32 v17, v17, v51
	v_add_f32_e32 v17, v52, v17
	v_cndmask_b32_e32 v17, v214, v17, vcc
	v_fma_f32 v51, -v27, v50, 1.0
	v_fmac_f32_e32 v50, v51, v50
	v_div_scale_f32 v51, vcc, 1.0, v12, 1.0
	v_mul_f32_e32 v52, v51, v50
	v_fma_f32 v53, -v27, v52, v51
	v_fmac_f32_e32 v52, v53, v50
	v_fma_f32 v27, -v27, v52, v51
	v_div_fmas_f32 v27, v27, v50, v52
	v_div_fixup_f32 v12, v27, v12, 1.0
	v_mul_f32_e32 v12, v25, v12
	v_min_f32_e32 v12, 0x3f7ffffe, v12
	v_sub_f32_e32 v27, 1.0, v12
	v_add_f32_e32 v50, -1.0, v27
	v_sub_f32_e32 v51, v50, v27
	v_add_f32_e32 v51, 1.0, v51
	v_sub_f32_e64 v50, -v12, v50
	v_add_f32_e32 v52, v50, v51
	v_frexp_mant_f32_e32 v53, v27
	v_cvt_f64_f32_e32 v[50:51], v27
	v_frexp_exp_i32_f64_e32 v50, v[50:51]
	v_cmp_gt_f32_e32 vcc, s25, v53
	v_cndmask_b32_e64 v17, v17, -v11, s[6:7]
	v_add_f32_e32 v17, v49, v17
	v_subbrev_co_u32_e32 v58, vcc, 0, v50, vcc
	v_sub_u32_e32 v50, 0, v58
	v_ldexp_f32 v27, v27, v50
	v_ldexp_f32 v50, v52, v50
	v_add_f32_e32 v52, -1.0, v27
	v_add_f32_e32 v51, 1.0, v52
	v_sub_f32_e32 v51, v27, v51
	v_add_f32_e32 v53, v50, v51
	v_add_f32_e32 v51, 1.0, v27
	v_add_f32_e32 v54, -1.0, v51
	v_sub_f32_e32 v27, v27, v54
	v_add_f32_e32 v27, v50, v27
	v_add_f32_e32 v59, v51, v27
	v_rcp_f32_e32 v60, v59
	v_sub_f32_e32 v50, v59, v51
	v_add_f32_e32 v51, v52, v53
	v_sub_f32_e32 v27, v27, v50
	v_mul_f32_e32 v62, v51, v60
	v_sub_f32_e32 v50, v51, v52
	v_mul_f32_e32 v52, v59, v62
	v_fma_f32 v54, v62, v59, -v52
	v_fmac_f32_e32 v54, v62, v27
	v_sub_f32_e32 v61, v53, v50
	v_add_f32_e32 v50, v52, v54
	v_sub_f32_e32 v53, v51, v50
	v_pk_add_f32 v[56:57], v[50:51], v[52:53] neg_lo:[0,1] neg_hi:[0,1]
	v_mov_b32_e32 v55, v50
	v_pk_add_f32 v[50:51], v[56:57], v[54:55] neg_lo:[0,1] neg_hi:[0,1]
	v_cmp_neq_f32_e32 vcc, s31, v12
	v_add_f32_e32 v51, v61, v51
	v_add_f32_e32 v50, v50, v51
	v_add_f32_e32 v51, v53, v50
	v_mul_f32_e32 v61, v60, v51
	v_mul_f32_e32 v52, v59, v61
	v_fma_f32 v54, v61, v59, -v52
	v_fmac_f32_e32 v54, v61, v27
	v_sub_f32_e32 v27, v53, v51
	v_add_f32_e32 v27, v50, v27
	v_add_f32_e32 v50, v52, v54
	v_sub_f32_e32 v53, v51, v50
	v_pk_add_f32 v[56:57], v[50:51], v[52:53] neg_lo:[0,1] neg_hi:[0,1]
	v_mov_b32_e32 v55, v50
	v_pk_add_f32 v[50:51], v[56:57], v[54:55] neg_lo:[0,1] neg_hi:[0,1]
	v_exp_f32_e32 v23, v23
	v_add_f32_e32 v27, v27, v51
	v_add_f32_e32 v27, v50, v27
	v_add_f32_e32 v51, v62, v61
	v_add_f32_e32 v27, v53, v27
	v_sub_f32_e32 v50, v51, v62
	v_mul_f32_e32 v27, v60, v27
	v_sub_f32_e32 v50, v61, v50
	v_add_f32_e32 v27, v50, v27
	v_add_f32_e32 v52, v51, v27
	v_mul_f32_e32 v54, v52, v52
	v_fmamk_f32 v50, v54, 0x3e9b6dac, v212
	v_fmaak_f32 v211, v54, v50, 0x3f2aaada
	v_cvt_f32_i32_e32 v50, v58
	v_sub_f32_e32 v51, v52, v51
	v_sub_f32_e32 v27, v27, v51
	v_mul_f32_e32 v51, v52, v54
	v_pk_mul_f32 v[54:55], v[50:51], v[210:211]
	v_ldexp_f32 v53, v52, 1
	v_fma_f32 v52, v50, s30, -v54
	v_fmac_f32_e32 v52, 0xb102e308, v50
	v_pk_add_f32 v[50:51], v[54:55], v[52:53]
	v_ldexp_f32 v27, v27, 1
	v_sub_f32_e32 v53, v51, v53
	v_sub_f32_e32 v53, v55, v53
	v_add_f32_e32 v57, v27, v53
	v_mov_b32_e32 v56, v54
	v_pk_add_f32 v[54:55], v[50:51], v[54:55] neg_lo:[0,1] neg_hi:[0,1]
	v_pk_add_f32 v[58:59], v[50:51], v[56:57]
	v_mov_b32_e32 v53, v50
	v_mov_b32_e32 v55, v59
	v_pk_add_f32 v[60:61], v[52:53], v[54:55] neg_lo:[0,1] neg_hi:[0,1]
	v_pk_add_f32 v[52:53], v[52:53], v[54:55]
	v_mov_b32_e32 v56, v57
	v_pk_add_f32 v[54:55], v[52:53], v[50:51] op_sel:[1,0] op_sel_hi:[0,1] neg_lo:[0,1] neg_hi:[0,1]
	v_pk_add_f32 v[62:63], v[58:59], v[54:55] op_sel_hi:[1,0] neg_lo:[0,1] neg_hi:[0,1]
	v_mov_b32_e32 v58, v59
	v_mov_b32_e32 v59, v53
	v_pk_mov_b32 v[54:55], v[50:51], v[54:55] op_sel:[1,0]
	v_mov_b32_e32 v57, v50
	v_pk_add_f32 v[54:55], v[58:59], v[54:55] neg_lo:[0,1] neg_hi:[0,1]
	v_mov_b32_e32 v62, v60
	v_pk_add_f32 v[50:51], v[56:57], v[54:55] neg_lo:[0,1] neg_hi:[0,1]
	v_mov_b32_e32 v61, v53
	v_pk_add_f32 v[54:55], v[62:63], v[50:51]
	v_add_f32_e32 v23, 1.0, v23
	v_pk_add_f32 v[56:57], v[54:55], v[54:55] op_sel:[0,1] op_sel_hi:[1,0]
	v_mul_f32_e32 v26, 0x3fb8aa3b, v26
	v_pk_add_f32 v[52:53], v[52:53], v[56:57] op_sel:[1,0] op_sel_hi:[0,1]
	v_mov_b32_e32 v55, v52
	v_pk_add_f32 v[58:59], v[54:55], v[60:61] neg_lo:[0,1] neg_hi:[0,1]
	v_mov_b32_e32 v51, v56
	v_sub_f32_e32 v27, v54, v58
	v_pk_add_f32 v[50:51], v[50:51], v[58:59] neg_lo:[0,1] neg_hi:[0,1]
	v_sub_f32_e32 v27, v60, v27
	v_add_f32_e32 v27, v50, v27
	v_add_f32_e32 v27, v27, v51
	v_div_scale_f32 v51, s[6:7], v14, v14, 1.0
	v_add_f32_e32 v27, v52, v27
	v_rcp_f32_e32 v52, v51
	v_cndmask_b32_e32 v27, v214, v27, vcc
	v_cmp_lt_f32_e64 s[6:7], |v12|, s44
	v_exp_f32_e32 v26, v26
	s_nop 0
	v_cndmask_b32_e64 v27, v27, -v12, s[6:7]
	v_add_f32_e32 v50, v17, v27
	v_fma_f32 v27, -v51, v52, 1.0
	v_fmac_f32_e32 v52, v27, v52
	v_div_scale_f32 v27, vcc, 1.0, v14, 1.0
	v_mul_f32_e32 v53, v27, v52
	v_fma_f32 v54, -v51, v53, v27
	v_fmac_f32_e32 v53, v54, v52
	v_fma_f32 v27, -v51, v53, v27
	v_div_fmas_f32 v27, v27, v52, v53
	v_div_fixup_f32 v14, v27, v14, 1.0
	v_mul_f32_e32 v14, v25, v14
	v_min_f32_e32 v14, 0x3f7ffffe, v14
	v_sub_f32_e32 v27, 1.0, v14
	v_add_f32_e32 v51, -1.0, v27
	v_sub_f32_e32 v52, v51, v27
	v_add_f32_e32 v52, 1.0, v52
	v_sub_f32_e64 v51, -v14, v51
	v_add_f32_e32 v51, v51, v52
	v_frexp_mant_f32_e32 v54, v27
	v_cvt_f64_f32_e32 v[52:53], v27
	v_frexp_exp_i32_f64_e32 v52, v[52:53]
	v_cmp_gt_f32_e32 vcc, s25, v54
; DI float sigmoidf_(float x) { return 1.f / (1.f + __expf(-x)); }
; DI void hg_prep_unit(const Params& p, int l, int unit, unsigned char* smem) {
;     ...
;     float cum = 0.f;
; #pragma unroll
;     for (int i = 0; i < 16; ++i) {
;       const float kkv = fminf((1.f - lbv) * sigmoidf_(-KK[i]), 0.9999999f);
;       KK[i] = kkv;
;       cum += log1pf(-kkv);
;       G[i] = cum;
;     }
	v_add_f32_e32 v26, 1.0, v26
	s_nop 0
	v_subbrev_co_u32_e32 v60, vcc, 0, v52, vcc
	v_sub_u32_e32 v52, 0, v60
	v_ldexp_f32 v27, v27, v52
	v_ldexp_f32 v51, v51, v52
	v_add_f32_e32 v52, -1.0, v27
	v_add_f32_e32 v53, 1.0, v52
	v_sub_f32_e32 v53, v27, v53
	v_add_f32_e32 v54, v51, v53
	v_add_f32_e32 v53, 1.0, v27
	v_add_f32_e32 v55, -1.0, v53
	v_sub_f32_e32 v27, v27, v55
	v_add_f32_e32 v27, v51, v27
	v_add_f32_e32 v51, v53, v27
	v_rcp_f32_e32 v61, v51
	v_sub_f32_e32 v53, v51, v53
	v_sub_f32_e32 v27, v27, v53
	v_add_f32_e32 v53, v52, v54
	v_sub_f32_e32 v52, v53, v52
	v_mul_f32_e32 v63, v53, v61
	v_sub_f32_e32 v62, v54, v52
	v_mul_f32_e32 v54, v51, v63
	v_fma_f32 v56, v63, v51, -v54
	v_fmac_f32_e32 v56, v63, v27
	v_add_f32_e32 v52, v54, v56
	v_sub_f32_e32 v55, v53, v52
	v_pk_add_f32 v[58:59], v[52:53], v[54:55] neg_lo:[0,1] neg_hi:[0,1]
	v_mov_b32_e32 v57, v52
	v_pk_add_f32 v[52:53], v[58:59], v[56:57] neg_lo:[0,1] neg_hi:[0,1]
	v_cmp_neq_f32_e32 vcc, s31, v14
	v_add_f32_e32 v53, v62, v53
	v_add_f32_e32 v52, v52, v53
	v_add_f32_e32 v53, v55, v52
	v_mul_f32_e32 v62, v61, v53
	v_mul_f32_e32 v54, v51, v62
	v_fma_f32 v56, v62, v51, -v54
	v_fmac_f32_e32 v56, v62, v27
	v_sub_f32_e32 v27, v55, v53
	v_add_f32_e32 v27, v52, v27
	v_add_f32_e32 v52, v54, v56
	v_sub_f32_e32 v55, v53, v52
	v_pk_add_f32 v[58:59], v[52:53], v[54:55] neg_lo:[0,1] neg_hi:[0,1]
	v_mov_b32_e32 v57, v52
	v_pk_add_f32 v[52:53], v[58:59], v[56:57] neg_lo:[0,1] neg_hi:[0,1]
	v_add_f32_e32 v51, v63, v62
	v_add_f32_e32 v27, v27, v53
	v_add_f32_e32 v27, v52, v27
	v_add_f32_e32 v27, v55, v27
	v_sub_f32_e32 v52, v51, v63
	v_mul_f32_e32 v27, v61, v27
	v_sub_f32_e32 v52, v62, v52
	v_add_f32_e32 v27, v52, v27
	v_add_f32_e32 v53, v51, v27
	v_mul_f32_e32 v54, v53, v53
	v_fmamk_f32 v52, v54, 0x3e9b6dac, v212
	v_fmaak_f32 v211, v54, v52, 0x3f2aaada
	v_cvt_f32_i32_e32 v52, v60
	v_sub_f32_e32 v51, v53, v51
	v_ldexp_f32 v55, v53, 1
	v_mul_f32_e32 v53, v53, v54
	v_pk_mul_f32 v[56:57], v[52:53], v[210:211]
	v_sub_f32_e32 v27, v27, v51
	v_fma_f32 v54, v52, s30, -v56
	v_fmac_f32_e32 v54, 0xb102e308, v52
	v_pk_add_f32 v[52:53], v[56:57], v[54:55]
	v_ldexp_f32 v27, v27, 1
	v_sub_f32_e32 v51, v53, v55
	v_sub_f32_e32 v51, v57, v51
	v_add_f32_e32 v59, v27, v51
	v_mov_b32_e32 v58, v56
	v_pk_add_f32 v[56:57], v[52:53], v[56:57] neg_lo:[0,1] neg_hi:[0,1]
	v_pk_add_f32 v[60:61], v[52:53], v[58:59]
	v_mov_b32_e32 v55, v52
	v_mov_b32_e32 v57, v61
	v_pk_add_f32 v[62:63], v[54:55], v[56:57] neg_lo:[0,1] neg_hi:[0,1]
	v_pk_add_f32 v[54:55], v[54:55], v[56:57]
	v_mov_b32_e32 v58, v59
	v_pk_add_f32 v[56:57], v[54:55], v[52:53] op_sel:[1,0] op_sel_hi:[0,1] neg_lo:[0,1] neg_hi:[0,1]
	v_pk_add_f32 v[64:65], v[60:61], v[56:57] op_sel_hi:[1,0] neg_lo:[0,1] neg_hi:[0,1]
	v_mov_b32_e32 v60, v61
	v_mov_b32_e32 v61, v55
	v_pk_mov_b32 v[56:57], v[52:53], v[56:57] op_sel:[1,0]
	v_mov_b32_e32 v59, v52
	v_pk_add_f32 v[56:57], v[60:61], v[56:57] neg_lo:[0,1] neg_hi:[0,1]
	v_mov_b32_e32 v64, v62
	v_pk_add_f32 v[52:53], v[58:59], v[56:57] neg_lo:[0,1] neg_hi:[0,1]
	v_mov_b32_e32 v63, v55
	v_pk_add_f32 v[56:57], v[64:65], v[52:53]
	s_nop 0
	v_pk_add_f32 v[58:59], v[56:57], v[56:57] op_sel:[0,1] op_sel_hi:[1,0]
	s_nop 0
	v_pk_add_f32 v[54:55], v[54:55], v[58:59] op_sel:[1,0] op_sel_hi:[0,1]
	v_mov_b32_e32 v57, v54
	v_pk_add_f32 v[60:61], v[56:57], v[62:63] neg_lo:[0,1] neg_hi:[0,1]
	v_mov_b32_e32 v53, v58
	v_sub_f32_e32 v27, v56, v60
	v_pk_add_f32 v[52:53], v[52:53], v[60:61] neg_lo:[0,1] neg_hi:[0,1]
	v_sub_f32_e32 v27, v62, v27
	v_add_f32_e32 v27, v52, v27
	v_div_scale_f32 v52, s[6:7], v13, v13, 1.0
	v_add_f32_e32 v27, v27, v53
	v_rcp_f32_e32 v53, v52
	v_add_f32_e32 v27, v54, v27
	v_cndmask_b32_e32 v27, v214, v27, vcc
	v_cmp_lt_f32_e64 s[6:7], |v14|, s44
	s_nop 1
	v_cndmask_b32_e64 v27, v27, -v14, s[6:7]
	v_add_f32_e32 v51, v50, v27
	v_fma_f32 v27, -v52, v53, 1.0
	v_fmac_f32_e32 v53, v27, v53
	v_div_scale_f32 v27, vcc, 1.0, v13, 1.0
	v_mul_f32_e32 v54, v27, v53
	v_fma_f32 v55, -v52, v54, v27
	v_fmac_f32_e32 v54, v55, v53
	v_fma_f32 v27, -v52, v54, v27
	v_div_fmas_f32 v27, v27, v53, v54
	v_div_fixup_f32 v13, v27, v13, 1.0
	v_mul_f32_e32 v13, v25, v13
	v_min_f32_e32 v13, 0x3f7ffffe, v13
	v_sub_f32_e32 v27, 1.0, v13
	v_add_f32_e32 v52, -1.0, v27
	v_sub_f32_e32 v53, v52, v27
	v_add_f32_e32 v53, 1.0, v53
	v_sub_f32_e64 v52, -v13, v52
	v_add_f32_e32 v54, v52, v53
	v_frexp_mant_f32_e32 v55, v27
	v_cvt_f64_f32_e32 v[52:53], v27
	v_frexp_exp_i32_f64_e32 v52, v[52:53]
	v_cmp_gt_f32_e32 vcc, s25, v55
	s_nop 1
	v_subbrev_co_u32_e32 v60, vcc, 0, v52, vcc
	v_sub_u32_e32 v52, 0, v60
	v_ldexp_f32 v27, v27, v52
	v_ldexp_f32 v52, v54, v52
	v_add_f32_e32 v54, -1.0, v27
	v_add_f32_e32 v53, 1.0, v54
	v_sub_f32_e32 v53, v27, v53
	v_add_f32_e32 v55, v52, v53
	v_add_f32_e32 v53, 1.0, v27
	v_add_f32_e32 v56, -1.0, v53
	v_sub_f32_e32 v27, v27, v56
	v_add_f32_e32 v27, v52, v27
	v_add_f32_e32 v61, v53, v27
	v_rcp_f32_e32 v62, v61
	v_sub_f32_e32 v52, v61, v53
	v_add_f32_e32 v53, v54, v55
	v_sub_f32_e32 v27, v27, v52
	v_mul_f32_e32 v64, v53, v62
	v_sub_f32_e32 v52, v53, v54
	v_mul_f32_e32 v54, v61, v64
	v_fma_f32 v56, v64, v61, -v54
	v_fmac_f32_e32 v56, v64, v27
	v_sub_f32_e32 v63, v55, v52
	v_add_f32_e32 v52, v54, v56
	v_sub_f32_e32 v55, v53, v52
	v_pk_add_f32 v[58:59], v[52:53], v[54:55] neg_lo:[0,1] neg_hi:[0,1]
	v_mov_b32_e32 v57, v52
	v_pk_add_f32 v[52:53], v[58:59], v[56:57] neg_lo:[0,1] neg_hi:[0,1]
	v_cmp_neq_f32_e32 vcc, s31, v13
	v_add_f32_e32 v53, v63, v53
	v_add_f32_e32 v52, v52, v53
	v_add_f32_e32 v53, v55, v52
	v_mul_f32_e32 v63, v62, v53
	v_mul_f32_e32 v54, v61, v63
	v_fma_f32 v56, v63, v61, -v54
	v_fmac_f32_e32 v56, v63, v27
	v_sub_f32_e32 v27, v55, v53
; DI float sigmoidf_(float x) { return 1.f / (1.f + __expf(-x)); }
; DI void hg_prep_unit(const Params& p, int l, int unit, unsigned char* smem) {
;     ...
;     float cum = 0.f;
; #pragma unroll
;     for (int i = 0; i < 16; ++i) {
;       const float kkv = fminf((1.f - lbv) * sigmoidf_(-KK[i]), 0.9999999f);
;       KK[i] = kkv;
;       cum += log1pf(-kkv);
;       G[i] = cum;
;     }
	v_add_f32_e32 v27, v52, v27
	v_add_f32_e32 v52, v54, v56
	v_sub_f32_e32 v55, v53, v52
	v_pk_add_f32 v[58:59], v[52:53], v[54:55] neg_lo:[0,1] neg_hi:[0,1]
	v_mov_b32_e32 v57, v52
	v_pk_add_f32 v[52:53], v[58:59], v[56:57] neg_lo:[0,1] neg_hi:[0,1]
	s_nop 0
	v_add_f32_e32 v27, v27, v53
	v_add_f32_e32 v27, v52, v27
	v_add_f32_e32 v53, v64, v63
	v_add_f32_e32 v27, v55, v27
	v_sub_f32_e32 v52, v53, v64
	v_mul_f32_e32 v27, v62, v27
	v_sub_f32_e32 v52, v63, v52
	v_add_f32_e32 v27, v52, v27
	v_add_f32_e32 v54, v53, v27
	v_mul_f32_e32 v56, v54, v54
	v_fmamk_f32 v52, v56, 0x3e9b6dac, v212
	v_fmaak_f32 v211, v56, v52, 0x3f2aaada
	v_cvt_f32_i32_e32 v52, v60
	v_sub_f32_e32 v53, v54, v53
	v_sub_f32_e32 v27, v27, v53
	v_mul_f32_e32 v53, v54, v56
	v_pk_mul_f32 v[56:57], v[52:53], v[210:211]
	v_ldexp_f32 v55, v54, 1
	v_fma_f32 v54, v52, s30, -v56
	v_fmac_f32_e32 v54, 0xb102e308, v52
	v_pk_add_f32 v[52:53], v[56:57], v[54:55]
	v_ldexp_f32 v27, v27, 1
	v_sub_f32_e32 v55, v53, v55
	v_sub_f32_e32 v55, v57, v55
	v_add_f32_e32 v59, v27, v55
	v_mov_b32_e32 v58, v56
	v_pk_add_f32 v[56:57], v[52:53], v[56:57] neg_lo:[0,1] neg_hi:[0,1]
	v_pk_add_f32 v[60:61], v[52:53], v[58:59]
	v_mov_b32_e32 v55, v52
	v_mov_b32_e32 v57, v61
	v_pk_add_f32 v[62:63], v[54:55], v[56:57] neg_lo:[0,1] neg_hi:[0,1]
	v_pk_add_f32 v[54:55], v[54:55], v[56:57]
	v_mov_b32_e32 v58, v59
	v_pk_add_f32 v[56:57], v[54:55], v[52:53] op_sel:[1,0] op_sel_hi:[0,1] neg_lo:[0,1] neg_hi:[0,1]
	v_pk_add_f32 v[64:65], v[60:61], v[56:57] op_sel_hi:[1,0] neg_lo:[0,1] neg_hi:[0,1]
	v_mov_b32_e32 v60, v61
	v_mov_b32_e32 v61, v55
	v_pk_mov_b32 v[56:57], v[52:53], v[56:57] op_sel:[1,0]
	v_mov_b32_e32 v59, v52
	v_pk_add_f32 v[56:57], v[60:61], v[56:57] neg_lo:[0,1] neg_hi:[0,1]
	v_mov_b32_e32 v64, v62
	v_pk_add_f32 v[52:53], v[58:59], v[56:57] neg_lo:[0,1] neg_hi:[0,1]
	v_mov_b32_e32 v63, v55
	v_pk_add_f32 v[56:57], v[64:65], v[52:53]
	s_nop 0
	v_pk_add_f32 v[58:59], v[56:57], v[56:57] op_sel:[0,1] op_sel_hi:[1,0]
	s_nop 0
	v_pk_add_f32 v[54:55], v[54:55], v[58:59] op_sel:[1,0] op_sel_hi:[0,1]
	v_mov_b32_e32 v57, v54
	v_pk_add_f32 v[60:61], v[56:57], v[62:63] neg_lo:[0,1] neg_hi:[0,1]
	v_mov_b32_e32 v53, v58
	v_sub_f32_e32 v27, v56, v60
	v_pk_add_f32 v[52:53], v[52:53], v[60:61] neg_lo:[0,1] neg_hi:[0,1]
	v_sub_f32_e32 v27, v62, v27
	v_add_f32_e32 v27, v52, v27
	v_add_f32_e32 v27, v27, v53
	v_div_scale_f32 v53, s[6:7], v15, v15, 1.0
	v_add_f32_e32 v27, v54, v27
	v_rcp_f32_e32 v54, v53
	v_cndmask_b32_e32 v27, v214, v27, vcc
	v_cmp_lt_f32_e64 s[6:7], |v13|, s44
	s_nop 1
	v_cndmask_b32_e64 v27, v27, -v13, s[6:7]
	v_add_f32_e32 v52, v51, v27
	v_fma_f32 v27, -v53, v54, 1.0
	v_fmac_f32_e32 v54, v27, v54
	v_div_scale_f32 v27, vcc, 1.0, v15, 1.0
	v_mul_f32_e32 v55, v27, v54
	v_fma_f32 v56, -v53, v55, v27
	v_fmac_f32_e32 v55, v56, v54
	v_fma_f32 v27, -v53, v55, v27
	v_div_fmas_f32 v27, v27, v54, v55
	v_div_fixup_f32 v15, v27, v15, 1.0
	v_mul_f32_e32 v15, v25, v15
	v_min_f32_e32 v15, 0x3f7ffffe, v15
	v_sub_f32_e32 v27, 1.0, v15
	v_add_f32_e32 v53, -1.0, v27
	v_sub_f32_e32 v54, v53, v27
	v_add_f32_e32 v54, 1.0, v54
	v_sub_f32_e64 v53, -v15, v53
	v_add_f32_e32 v53, v53, v54
	v_frexp_mant_f32_e32 v56, v27
	v_cvt_f64_f32_e32 v[54:55], v27
	v_frexp_exp_i32_f64_e32 v54, v[54:55]
	v_cmp_gt_f32_e32 vcc, s25, v56
	s_nop 1
	v_subbrev_co_u32_e32 v62, vcc, 0, v54, vcc
	v_sub_u32_e32 v54, 0, v62
	v_ldexp_f32 v27, v27, v54
	v_ldexp_f32 v53, v53, v54
	v_add_f32_e32 v54, -1.0, v27
	v_add_f32_e32 v55, 1.0, v54
	v_sub_f32_e32 v55, v27, v55
	v_add_f32_e32 v56, v53, v55
	v_add_f32_e32 v55, 1.0, v27
	v_add_f32_e32 v57, -1.0, v55
	v_sub_f32_e32 v27, v27, v57
	v_add_f32_e32 v27, v53, v27
	v_add_f32_e32 v53, v55, v27
	v_rcp_f32_e32 v63, v53
	v_sub_f32_e32 v55, v53, v55
	v_sub_f32_e32 v27, v27, v55
	v_add_f32_e32 v55, v54, v56
	v_sub_f32_e32 v54, v55, v54
	v_mul_f32_e32 v65, v55, v63
	v_sub_f32_e32 v64, v56, v54
	v_mul_f32_e32 v56, v53, v65
	v_fma_f32 v58, v65, v53, -v56
	v_fmac_f32_e32 v58, v65, v27
	v_add_f32_e32 v54, v56, v58
	v_sub_f32_e32 v57, v55, v54
	v_pk_add_f32 v[60:61], v[54:55], v[56:57] neg_lo:[0,1] neg_hi:[0,1]
	v_mov_b32_e32 v59, v54
	v_pk_add_f32 v[54:55], v[60:61], v[58:59] neg_lo:[0,1] neg_hi:[0,1]
	v_cmp_neq_f32_e32 vcc, s31, v15
	v_add_f32_e32 v55, v64, v55
	v_add_f32_e32 v54, v54, v55
	v_add_f32_e32 v55, v57, v54
	v_mul_f32_e32 v64, v63, v55
	v_mul_f32_e32 v56, v53, v64
	v_fma_f32 v58, v64, v53, -v56
	v_fmac_f32_e32 v58, v64, v27
	v_sub_f32_e32 v27, v57, v55
	v_add_f32_e32 v27, v54, v27
	v_add_f32_e32 v54, v56, v58
	v_sub_f32_e32 v57, v55, v54
	v_pk_add_f32 v[60:61], v[54:55], v[56:57] neg_lo:[0,1] neg_hi:[0,1]
	v_mov_b32_e32 v59, v54
	v_pk_add_f32 v[54:55], v[60:61], v[58:59] neg_lo:[0,1] neg_hi:[0,1]
	v_add_f32_e32 v53, v65, v64
	v_add_f32_e32 v27, v27, v55
	v_add_f32_e32 v27, v54, v27
	v_add_f32_e32 v27, v57, v27
	v_sub_f32_e32 v54, v53, v65
	v_mul_f32_e32 v27, v63, v27
	v_sub_f32_e32 v54, v64, v54
	v_add_f32_e32 v27, v54, v27
	v_add_f32_e32 v55, v53, v27
	v_mul_f32_e32 v56, v55, v55
	v_fmamk_f32 v54, v56, 0x3e9b6dac, v212
	v_fmaak_f32 v211, v56, v54, 0x3f2aaada
	v_cvt_f32_i32_e32 v54, v62
	v_sub_f32_e32 v53, v55, v53
	v_ldexp_f32 v57, v55, 1
	v_mul_f32_e32 v55, v55, v56
	v_pk_mul_f32 v[58:59], v[54:55], v[210:211]
	v_sub_f32_e32 v27, v27, v53
	v_fma_f32 v56, v54, s30, -v58
	v_fmac_f32_e32 v56, 0xb102e308, v54
	v_pk_add_f32 v[54:55], v[58:59], v[56:57]
	v_ldexp_f32 v27, v27, 1
	v_sub_f32_e32 v53, v55, v57
	v_sub_f32_e32 v53, v59, v53
	v_add_f32_e32 v61, v27, v53
	v_mov_b32_e32 v60, v58
	v_pk_add_f32 v[58:59], v[54:55], v[58:59] neg_lo:[0,1] neg_hi:[0,1]
	v_pk_add_f32 v[62:63], v[54:55], v[60:61]
	v_mov_b32_e32 v57, v54
; DI float sigmoidf_(float x) { return 1.f / (1.f + __expf(-x)); }
; DI void hg_prep_unit(const Params& p, int l, int unit, unsigned char* smem) {
;     ...
;     float cum = 0.f;
; #pragma unroll
;     for (int i = 0; i < 16; ++i) {
;       const float kkv = fminf((1.f - lbv) * sigmoidf_(-KK[i]), 0.9999999f);
;       KK[i] = kkv;
;       cum += log1pf(-kkv);
;       G[i] = cum;
;     }
	v_mov_b32_e32 v59, v63
	v_pk_add_f32 v[64:65], v[56:57], v[58:59] neg_lo:[0,1] neg_hi:[0,1]
	v_pk_add_f32 v[56:57], v[56:57], v[58:59]
	v_mov_b32_e32 v60, v61
	v_pk_add_f32 v[58:59], v[56:57], v[54:55] op_sel:[1,0] op_sel_hi:[0,1] neg_lo:[0,1] neg_hi:[0,1]
	v_pk_add_f32 v[66:67], v[62:63], v[58:59] op_sel_hi:[1,0] neg_lo:[0,1] neg_hi:[0,1]
	v_mov_b32_e32 v62, v63
	v_mov_b32_e32 v63, v57
	v_pk_mov_b32 v[58:59], v[54:55], v[58:59] op_sel:[1,0]
	v_mov_b32_e32 v61, v54
	v_pk_add_f32 v[58:59], v[62:63], v[58:59] neg_lo:[0,1] neg_hi:[0,1]
	v_mov_b32_e32 v66, v64
	v_pk_add_f32 v[54:55], v[60:61], v[58:59] neg_lo:[0,1] neg_hi:[0,1]
	v_mov_b32_e32 v65, v57
	v_pk_add_f32 v[58:59], v[66:67], v[54:55]
	s_nop 0
	v_pk_add_f32 v[60:61], v[58:59], v[58:59] op_sel:[0,1] op_sel_hi:[1,0]
	s_nop 0
	v_pk_add_f32 v[56:57], v[56:57], v[60:61] op_sel:[1,0] op_sel_hi:[0,1]
	v_mov_b32_e32 v59, v56
	v_pk_add_f32 v[62:63], v[58:59], v[64:65] neg_lo:[0,1] neg_hi:[0,1]
	v_mov_b32_e32 v55, v60
	v_sub_f32_e32 v27, v58, v62
	v_pk_add_f32 v[54:55], v[54:55], v[62:63] neg_lo:[0,1] neg_hi:[0,1]
	v_sub_f32_e32 v27, v64, v27
	v_add_f32_e32 v27, v54, v27
	v_div_scale_f32 v54, s[6:7], v18, v18, 1.0
	v_add_f32_e32 v27, v27, v55
	v_rcp_f32_e32 v55, v54
	v_add_f32_e32 v27, v56, v27
	v_cndmask_b32_e32 v27, v214, v27, vcc
	v_cmp_lt_f32_e64 s[6:7], |v15|, s44
	s_nop 1
	v_cndmask_b32_e64 v27, v27, -v15, s[6:7]
	v_add_f32_e32 v53, v52, v27
	v_fma_f32 v27, -v54, v55, 1.0
	v_fmac_f32_e32 v55, v27, v55
	v_div_scale_f32 v27, vcc, 1.0, v18, 1.0
	v_mul_f32_e32 v56, v27, v55
	v_fma_f32 v57, -v54, v56, v27
	v_fmac_f32_e32 v56, v57, v55
	v_fma_f32 v27, -v54, v56, v27
	v_div_fmas_f32 v27, v27, v55, v56
	v_div_fixup_f32 v18, v27, v18, 1.0
	v_mul_f32_e32 v18, v25, v18
	v_min_f32_e32 v18, 0x3f7ffffe, v18
	v_sub_f32_e32 v27, 1.0, v18
	v_add_f32_e32 v54, -1.0, v27
	v_sub_f32_e32 v55, v54, v27
	v_add_f32_e32 v55, 1.0, v55
	v_sub_f32_e64 v54, -v18, v54
	v_add_f32_e32 v56, v54, v55
	v_frexp_mant_f32_e32 v57, v27
	v_cvt_f64_f32_e32 v[54:55], v27
	v_frexp_exp_i32_f64_e32 v54, v[54:55]
	v_cmp_gt_f32_e32 vcc, s25, v57
	s_nop 1
	v_subbrev_co_u32_e32 v62, vcc, 0, v54, vcc
	v_sub_u32_e32 v54, 0, v62
	v_ldexp_f32 v27, v27, v54
	v_ldexp_f32 v54, v56, v54
	v_add_f32_e32 v56, -1.0, v27
	v_add_f32_e32 v55, 1.0, v56
	v_sub_f32_e32 v55, v27, v55
	v_add_f32_e32 v57, v54, v55
	v_add_f32_e32 v55, 1.0, v27
	v_add_f32_e32 v58, -1.0, v55
	v_sub_f32_e32 v27, v27, v58
	v_add_f32_e32 v27, v54, v27
	v_add_f32_e32 v63, v55, v27
	v_rcp_f32_e32 v64, v63
	v_sub_f32_e32 v54, v63, v55
	v_add_f32_e32 v55, v56, v57
	v_sub_f32_e32 v27, v27, v54
	v_mul_f32_e32 v66, v55, v64
	v_sub_f32_e32 v54, v55, v56
	v_mul_f32_e32 v56, v63, v66
	v_fma_f32 v58, v66, v63, -v56
	v_fmac_f32_e32 v58, v66, v27
	v_sub_f32_e32 v65, v57, v54
	v_add_f32_e32 v54, v56, v58
	v_sub_f32_e32 v57, v55, v54
	v_pk_add_f32 v[60:61], v[54:55], v[56:57] neg_lo:[0,1] neg_hi:[0,1]
	v_mov_b32_e32 v59, v54
	v_pk_add_f32 v[54:55], v[60:61], v[58:59] neg_lo:[0,1] neg_hi:[0,1]
	v_cmp_neq_f32_e32 vcc, s31, v18
	v_add_f32_e32 v55, v65, v55
	v_add_f32_e32 v54, v54, v55
	v_add_f32_e32 v55, v57, v54
	v_mul_f32_e32 v65, v64, v55
	v_mul_f32_e32 v56, v63, v65
	v_fma_f32 v58, v65, v63, -v56
	v_fmac_f32_e32 v58, v65, v27
	v_sub_f32_e32 v27, v57, v55
	v_add_f32_e32 v27, v54, v27
	v_add_f32_e32 v54, v56, v58
	v_sub_f32_e32 v57, v55, v54
	v_pk_add_f32 v[60:61], v[54:55], v[56:57] neg_lo:[0,1] neg_hi:[0,1]
	v_mov_b32_e32 v59, v54
	v_pk_add_f32 v[54:55], v[60:61], v[58:59] neg_lo:[0,1] neg_hi:[0,1]
	s_nop 0
	v_add_f32_e32 v27, v27, v55
	v_add_f32_e32 v27, v54, v27
	v_add_f32_e32 v55, v66, v65
	v_add_f32_e32 v27, v57, v27
	v_sub_f32_e32 v54, v55, v66
	v_mul_f32_e32 v27, v64, v27
	v_sub_f32_e32 v54, v65, v54
	v_add_f32_e32 v27, v54, v27
	v_add_f32_e32 v56, v55, v27
	v_mul_f32_e32 v58, v56, v56
	v_fmamk_f32 v54, v58, 0x3e9b6dac, v212
	v_fmaak_f32 v211, v58, v54, 0x3f2aaada
	v_cvt_f32_i32_e32 v54, v62
	v_sub_f32_e32 v55, v56, v55
	v_sub_f32_e32 v27, v27, v55
	v_mul_f32_e32 v55, v56, v58
	v_pk_mul_f32 v[58:59], v[54:55], v[210:211]
	v_ldexp_f32 v57, v56, 1
	v_fma_f32 v56, v54, s30, -v58
	v_fmac_f32_e32 v56, 0xb102e308, v54
	v_pk_add_f32 v[54:55], v[58:59], v[56:57]
	v_ldexp_f32 v27, v27, 1
	v_sub_f32_e32 v57, v55, v57
	v_sub_f32_e32 v57, v59, v57
	v_add_f32_e32 v61, v27, v57
	v_mov_b32_e32 v60, v58
	v_pk_add_f32 v[58:59], v[54:55], v[58:59] neg_lo:[0,1] neg_hi:[0,1]
	v_pk_add_f32 v[62:63], v[54:55], v[60:61]
	v_mov_b32_e32 v57, v54
	v_mov_b32_e32 v59, v63
	v_pk_add_f32 v[64:65], v[56:57], v[58:59] neg_lo:[0,1] neg_hi:[0,1]
	v_pk_add_f32 v[56:57], v[56:57], v[58:59]
	v_mov_b32_e32 v60, v61
	v_pk_add_f32 v[58:59], v[56:57], v[54:55] op_sel:[1,0] op_sel_hi:[0,1] neg_lo:[0,1] neg_hi:[0,1]
	v_pk_add_f32 v[66:67], v[62:63], v[58:59] op_sel_hi:[1,0] neg_lo:[0,1] neg_hi:[0,1]
	v_mov_b32_e32 v62, v63
	v_mov_b32_e32 v63, v57
	v_pk_mov_b32 v[58:59], v[54:55], v[58:59] op_sel:[1,0]
	v_mov_b32_e32 v61, v54
	v_pk_add_f32 v[58:59], v[62:63], v[58:59] neg_lo:[0,1] neg_hi:[0,1]
	v_mov_b32_e32 v66, v64
	v_pk_add_f32 v[54:55], v[60:61], v[58:59] neg_lo:[0,1] neg_hi:[0,1]
	v_mov_b32_e32 v65, v57
	v_pk_add_f32 v[58:59], v[66:67], v[54:55]
	s_nop 0
	v_pk_add_f32 v[60:61], v[58:59], v[58:59] op_sel:[0,1] op_sel_hi:[1,0]
	s_nop 0
	v_pk_add_f32 v[56:57], v[56:57], v[60:61] op_sel:[1,0] op_sel_hi:[0,1]
	v_mov_b32_e32 v59, v56
	v_pk_add_f32 v[62:63], v[58:59], v[64:65] neg_lo:[0,1] neg_hi:[0,1]
	v_mov_b32_e32 v55, v60
	v_sub_f32_e32 v27, v58, v62
	v_pk_add_f32 v[54:55], v[54:55], v[62:63] neg_lo:[0,1] neg_hi:[0,1]
	v_sub_f32_e32 v27, v64, v27
	v_add_f32_e32 v27, v54, v27
	v_add_f32_e32 v27, v27, v55
; DI float sigmoidf_(float x) { return 1.f / (1.f + __expf(-x)); }
; DI void hg_prep_unit(const Params& p, int l, int unit, unsigned char* smem) {
;     ...
;     float cum = 0.f;
; #pragma unroll
;     for (int i = 0; i < 16; ++i) {
;       const float kkv = fminf((1.f - lbv) * sigmoidf_(-KK[i]), 0.9999999f);
;       KK[i] = kkv;
;       cum += log1pf(-kkv);
;       G[i] = cum;
;     }
	v_div_scale_f32 v54, s[6:7], v20, v20, 1.0
	v_add_f32_e32 v27, v56, v27
	v_rcp_f32_e32 v56, v54
	v_cndmask_b32_e32 v27, v214, v27, vcc
	v_cmp_lt_f32_e64 s[6:7], |v18|, s44
	s_nop 1
	v_cndmask_b32_e64 v27, v27, -v18, s[6:7]
	v_add_f32_e32 v55, v53, v27
	v_fma_f32 v27, -v54, v56, 1.0
	v_fmac_f32_e32 v56, v27, v56
	v_div_scale_f32 v27, vcc, 1.0, v20, 1.0
	v_mul_f32_e32 v57, v27, v56
	v_fma_f32 v58, -v54, v57, v27
	v_fmac_f32_e32 v57, v58, v56
	v_fma_f32 v27, -v54, v57, v27
	v_div_fmas_f32 v27, v27, v56, v57
	v_div_fixup_f32 v20, v27, v20, 1.0
	v_mul_f32_e32 v20, v25, v20
	v_min_f32_e32 v20, 0x3f7ffffe, v20
	v_sub_f32_e32 v27, 1.0, v20
	v_add_f32_e32 v54, -1.0, v27
	v_sub_f32_e32 v56, v54, v27
	v_add_f32_e32 v56, 1.0, v56
	v_sub_f32_e64 v54, -v20, v54
	v_add_f32_e32 v54, v54, v56
	v_frexp_mant_f32_e32 v58, v27
	v_cvt_f64_f32_e32 v[56:57], v27
	v_frexp_exp_i32_f64_e32 v56, v[56:57]
	v_cmp_gt_f32_e32 vcc, s25, v58
	s_nop 1
	v_subbrev_co_u32_e32 v64, vcc, 0, v56, vcc
	v_sub_u32_e32 v56, 0, v64
	v_ldexp_f32 v27, v27, v56
	v_ldexp_f32 v54, v54, v56
	v_add_f32_e32 v56, -1.0, v27
	v_add_f32_e32 v57, 1.0, v56
	v_sub_f32_e32 v57, v27, v57
	v_add_f32_e32 v58, v54, v57
	v_add_f32_e32 v57, 1.0, v27
	v_add_f32_e32 v59, -1.0, v57
	v_sub_f32_e32 v27, v27, v59
	v_add_f32_e32 v27, v54, v27
	v_add_f32_e32 v54, v57, v27
	v_rcp_f32_e32 v65, v54
	v_sub_f32_e32 v57, v54, v57
	v_sub_f32_e32 v27, v27, v57
	v_add_f32_e32 v57, v56, v58
	v_sub_f32_e32 v56, v57, v56
	v_mul_f32_e32 v67, v57, v65
	v_sub_f32_e32 v66, v58, v56
	v_mul_f32_e32 v58, v54, v67
	v_fma_f32 v60, v67, v54, -v58
	v_fmac_f32_e32 v60, v67, v27
	v_add_f32_e32 v56, v58, v60
	v_sub_f32_e32 v59, v57, v56
	v_pk_add_f32 v[62:63], v[56:57], v[58:59] neg_lo:[0,1] neg_hi:[0,1]
	v_mov_b32_e32 v61, v56
	v_pk_add_f32 v[56:57], v[62:63], v[60:61] neg_lo:[0,1] neg_hi:[0,1]
	v_cmp_neq_f32_e32 vcc, s31, v20
	v_add_f32_e32 v57, v66, v57
	v_add_f32_e32 v56, v56, v57
	v_add_f32_e32 v57, v59, v56
	v_mul_f32_e32 v66, v65, v57
	v_mul_f32_e32 v58, v54, v66
	v_fma_f32 v60, v66, v54, -v58
	v_fmac_f32_e32 v60, v66, v27
	v_sub_f32_e32 v27, v59, v57
	v_add_f32_e32 v27, v56, v27
	v_add_f32_e32 v56, v58, v60
	v_sub_f32_e32 v59, v57, v56
	v_pk_add_f32 v[62:63], v[56:57], v[58:59] neg_lo:[0,1] neg_hi:[0,1]
	v_mov_b32_e32 v61, v56
	v_pk_add_f32 v[56:57], v[62:63], v[60:61] neg_lo:[0,1] neg_hi:[0,1]
	v_add_f32_e32 v54, v67, v66
	v_add_f32_e32 v27, v27, v57
	v_add_f32_e32 v27, v56, v27
	v_add_f32_e32 v27, v59, v27
	v_sub_f32_e32 v56, v54, v67
	v_mul_f32_e32 v27, v65, v27
	v_sub_f32_e32 v56, v66, v56
	v_add_f32_e32 v27, v56, v27
	v_add_f32_e32 v57, v54, v27
	v_mul_f32_e32 v58, v57, v57
	v_fmamk_f32 v56, v58, 0x3e9b6dac, v212
	v_fmaak_f32 v211, v58, v56, 0x3f2aaada
	v_cvt_f32_i32_e32 v56, v64
	v_sub_f32_e32 v54, v57, v54
	v_ldexp_f32 v59, v57, 1
	v_mul_f32_e32 v57, v57, v58
	v_pk_mul_f32 v[60:61], v[56:57], v[210:211]
	v_sub_f32_e32 v27, v27, v54
	v_fma_f32 v58, v56, s30, -v60
	v_fmac_f32_e32 v58, 0xb102e308, v56
	v_pk_add_f32 v[56:57], v[60:61], v[58:59]
	v_ldexp_f32 v27, v27, 1
	v_sub_f32_e32 v54, v57, v59
	v_sub_f32_e32 v54, v61, v54
	v_add_f32_e32 v63, v27, v54
	v_mov_b32_e32 v62, v60
	v_pk_add_f32 v[60:61], v[56:57], v[60:61] neg_lo:[0,1] neg_hi:[0,1]
	v_pk_add_f32 v[64:65], v[56:57], v[62:63]
	v_mov_b32_e32 v59, v56
	v_mov_b32_e32 v61, v65
	v_pk_add_f32 v[66:67], v[58:59], v[60:61] neg_lo:[0,1] neg_hi:[0,1]
	v_pk_add_f32 v[58:59], v[58:59], v[60:61]
	v_mov_b32_e32 v62, v63
	v_pk_add_f32 v[60:61], v[58:59], v[56:57] op_sel:[1,0] op_sel_hi:[0,1] neg_lo:[0,1] neg_hi:[0,1]
	v_pk_add_f32 v[68:69], v[64:65], v[60:61] op_sel_hi:[1,0] neg_lo:[0,1] neg_hi:[0,1]
	v_mov_b32_e32 v64, v65
	v_mov_b32_e32 v65, v59
	v_pk_mov_b32 v[60:61], v[56:57], v[60:61] op_sel:[1,0]
	v_mov_b32_e32 v63, v56
	v_pk_add_f32 v[60:61], v[64:65], v[60:61] neg_lo:[0,1] neg_hi:[0,1]
	v_mov_b32_e32 v68, v66
	v_pk_add_f32 v[56:57], v[62:63], v[60:61] neg_lo:[0,1] neg_hi:[0,1]
	v_mov_b32_e32 v67, v59
	v_pk_add_f32 v[60:61], v[68:69], v[56:57]
	v_div_scale_f32 v54, s[6:7], v19, v19, 1.0
	v_pk_add_f32 v[62:63], v[60:61], v[60:61] op_sel:[0,1] op_sel_hi:[1,0]
	v_cmp_lt_f32_e64 s[6:7], |v20|, s44
	v_pk_add_f32 v[58:59], v[58:59], v[62:63] op_sel:[1,0] op_sel_hi:[0,1]
	v_mov_b32_e32 v61, v58
	v_pk_add_f32 v[64:65], v[60:61], v[66:67] neg_lo:[0,1] neg_hi:[0,1]
	v_mov_b32_e32 v57, v62
	v_sub_f32_e32 v27, v60, v64
	v_pk_add_f32 v[56:57], v[56:57], v[64:65] neg_lo:[0,1] neg_hi:[0,1]
	v_sub_f32_e32 v27, v66, v27
	v_add_f32_e32 v27, v56, v27
	v_add_f32_e32 v27, v27, v57
	v_rcp_f32_e32 v57, v54
	v_add_f32_e32 v27, v58, v27
	v_cndmask_b32_e32 v27, v214, v27, vcc
	v_cndmask_b32_e64 v27, v27, -v20, s[6:7]
	v_add_f32_e32 v56, v55, v27
	v_fma_f32 v27, -v54, v57, 1.0
	v_fmac_f32_e32 v57, v27, v57
	v_div_scale_f32 v27, vcc, 1.0, v19, 1.0
	v_mul_f32_e32 v58, v27, v57
	v_fma_f32 v59, -v54, v58, v27
	v_fmac_f32_e32 v58, v59, v57
	v_fma_f32 v27, -v54, v58, v27
	v_div_fmas_f32 v27, v27, v57, v58
	v_div_fixup_f32 v19, v27, v19, 1.0
	v_mul_f32_e32 v19, v25, v19
	v_min_f32_e32 v19, 0x3f7ffffe, v19
	v_sub_f32_e32 v27, 1.0, v19
	v_add_f32_e32 v54, -1.0, v27
	v_sub_f32_e32 v57, v54, v27
	v_add_f32_e32 v57, 1.0, v57
	v_sub_f32_e64 v54, -v19, v54
	v_add_f32_e32 v54, v54, v57
	v_frexp_mant_f32_e32 v57, v27
	v_cvt_f64_f32_e32 v[58:59], v27
	v_frexp_exp_i32_f64_e32 v58, v[58:59]
	v_cmp_gt_f32_e32 vcc, s25, v57
	s_nop 1
	v_subbrev_co_u32_e32 v57, vcc, 0, v58, vcc
	v_sub_u32_e32 v58, 0, v57
	v_ldexp_f32 v27, v27, v58
	v_ldexp_f32 v54, v54, v58
	v_add_f32_e32 v58, -1.0, v27
	v_add_f32_e32 v59, 1.0, v58
	v_sub_f32_e32 v59, v27, v59
	v_add_f32_e32 v60, v54, v59
	v_add_f32_e32 v59, 1.0, v27
	v_add_f32_e32 v61, -1.0, v59
; DI float sigmoidf_(float x) { return 1.f / (1.f + __expf(-x)); }
; DI void hg_prep_unit(const Params& p, int l, int unit, unsigned char* smem) {
;     ...
;     float cum = 0.f;
; #pragma unroll
;     for (int i = 0; i < 16; ++i) {
;       const float kkv = fminf((1.f - lbv) * sigmoidf_(-KK[i]), 0.9999999f);
;       KK[i] = kkv;
;       cum += log1pf(-kkv);
;       G[i] = cum;
;     }
	v_sub_f32_e32 v27, v27, v61
	v_add_f32_e32 v27, v54, v27
	v_add_f32_e32 v54, v59, v27
	v_rcp_f32_e32 v66, v54
	v_sub_f32_e32 v59, v54, v59
	v_sub_f32_e32 v27, v27, v59
	v_add_f32_e32 v59, v58, v60
	v_sub_f32_e32 v58, v59, v58
	v_mul_f32_e32 v68, v59, v66
	v_sub_f32_e32 v67, v60, v58
	v_mul_f32_e32 v60, v54, v68
	v_fma_f32 v62, v68, v54, -v60
	v_fmac_f32_e32 v62, v68, v27
	v_add_f32_e32 v58, v60, v62
	v_sub_f32_e32 v61, v59, v58
	v_pk_add_f32 v[64:65], v[58:59], v[60:61] neg_lo:[0,1] neg_hi:[0,1]
	v_mov_b32_e32 v63, v58
	v_pk_add_f32 v[58:59], v[64:65], v[62:63] neg_lo:[0,1] neg_hi:[0,1]
	v_cmp_neq_f32_e32 vcc, s31, v19
	v_add_f32_e32 v59, v67, v59
	v_add_f32_e32 v58, v58, v59
	v_add_f32_e32 v59, v61, v58
	v_mul_f32_e32 v67, v66, v59
	v_mul_f32_e32 v60, v54, v67
	v_fma_f32 v62, v67, v54, -v60
	v_fmac_f32_e32 v62, v67, v27
	v_sub_f32_e32 v27, v61, v59
	v_add_f32_e32 v27, v58, v27
	v_add_f32_e32 v58, v60, v62
	v_sub_f32_e32 v61, v59, v58
	v_pk_add_f32 v[64:65], v[58:59], v[60:61] neg_lo:[0,1] neg_hi:[0,1]
	v_mov_b32_e32 v63, v58
	v_pk_add_f32 v[58:59], v[64:65], v[62:63] neg_lo:[0,1] neg_hi:[0,1]
	v_add_f32_e32 v54, v68, v67
	v_add_f32_e32 v27, v27, v59
	v_add_f32_e32 v27, v58, v27
	v_add_f32_e32 v27, v61, v27
	v_sub_f32_e32 v58, v54, v68
	v_mul_f32_e32 v27, v66, v27
	v_sub_f32_e32 v58, v67, v58
	v_add_f32_e32 v27, v58, v27
	v_add_f32_e32 v59, v54, v27
	v_mul_f32_e32 v60, v59, v59
	v_fmamk_f32 v58, v60, 0x3e9b6dac, v212
	v_fmaak_f32 v211, v60, v58, 0x3f2aaada
	v_cvt_f32_i32_e32 v58, v57
	v_sub_f32_e32 v54, v59, v54
	v_ldexp_f32 v61, v59, 1
	v_mul_f32_e32 v59, v59, v60
	v_pk_mul_f32 v[62:63], v[58:59], v[210:211]
	v_sub_f32_e32 v27, v27, v54
	v_fma_f32 v60, v58, s30, -v62
	v_fmac_f32_e32 v60, 0xb102e308, v58
	v_pk_add_f32 v[58:59], v[62:63], v[60:61]
	v_ldexp_f32 v27, v27, 1
	v_sub_f32_e32 v54, v59, v61
	v_sub_f32_e32 v54, v63, v54
	v_add_f32_e32 v65, v27, v54
	v_mov_b32_e32 v64, v62
	v_pk_add_f32 v[62:63], v[58:59], v[62:63] neg_lo:[0,1] neg_hi:[0,1]
	v_pk_add_f32 v[66:67], v[58:59], v[64:65]
	v_mov_b32_e32 v61, v58
	v_mov_b32_e32 v63, v67
	v_pk_add_f32 v[68:69], v[60:61], v[62:63] neg_lo:[0,1] neg_hi:[0,1]
	v_pk_add_f32 v[60:61], v[60:61], v[62:63]
	v_mov_b32_e32 v64, v65
	v_pk_add_f32 v[62:63], v[60:61], v[58:59] op_sel:[1,0] op_sel_hi:[0,1] neg_lo:[0,1] neg_hi:[0,1]
	v_pk_add_f32 v[70:71], v[66:67], v[62:63] op_sel_hi:[1,0] neg_lo:[0,1] neg_hi:[0,1]
	v_mov_b32_e32 v66, v67
	v_mov_b32_e32 v67, v61
	v_pk_mov_b32 v[62:63], v[58:59], v[62:63] op_sel:[1,0]
	v_mov_b32_e32 v65, v58
	v_pk_add_f32 v[62:63], v[66:67], v[62:63] neg_lo:[0,1] neg_hi:[0,1]
	v_mov_b32_e32 v70, v68
	v_pk_add_f32 v[58:59], v[64:65], v[62:63] neg_lo:[0,1] neg_hi:[0,1]
	v_mov_b32_e32 v69, v61
	v_pk_add_f32 v[62:63], v[70:71], v[58:59]
	v_div_scale_f32 v54, s[6:7], v21, v21, 1.0
	v_pk_add_f32 v[64:65], v[62:63], v[62:63] op_sel:[0,1] op_sel_hi:[1,0]
	v_cmp_lt_f32_e64 s[6:7], |v19|, s44
	v_pk_add_f32 v[60:61], v[60:61], v[64:65] op_sel:[1,0] op_sel_hi:[0,1]
	v_mov_b32_e32 v63, v60
	v_pk_add_f32 v[66:67], v[62:63], v[68:69] neg_lo:[0,1] neg_hi:[0,1]
	v_mov_b32_e32 v59, v64
	v_sub_f32_e32 v27, v62, v66
	v_pk_add_f32 v[58:59], v[58:59], v[66:67] neg_lo:[0,1] neg_hi:[0,1]
	v_sub_f32_e32 v27, v68, v27
	v_add_f32_e32 v27, v58, v27
	v_add_f32_e32 v27, v27, v59
	v_rcp_f32_e32 v58, v54
	v_add_f32_e32 v27, v60, v27
	v_cndmask_b32_e32 v27, v214, v27, vcc
	v_cndmask_b32_e64 v27, v27, -v19, s[6:7]
	v_add_f32_e32 v57, v56, v27
	v_fma_f32 v27, -v54, v58, 1.0
	v_fmac_f32_e32 v58, v27, v58
	v_div_scale_f32 v27, vcc, 1.0, v21, 1.0
	v_mul_f32_e32 v59, v27, v58
	v_fma_f32 v60, -v54, v59, v27
	v_fmac_f32_e32 v59, v60, v58
	v_fma_f32 v27, -v54, v59, v27
	v_div_fmas_f32 v27, v27, v58, v59
	v_div_fixup_f32 v21, v27, v21, 1.0
	v_mul_f32_e32 v21, v25, v21
	v_min_f32_e32 v21, 0x3f7ffffe, v21
	v_sub_f32_e32 v27, 1.0, v21
	v_add_f32_e32 v54, -1.0, v27
	v_sub_f32_e32 v58, v54, v27
	v_add_f32_e32 v58, 1.0, v58
	v_sub_f32_e64 v54, -v21, v54
	v_add_f32_e32 v54, v54, v58
	v_frexp_mant_f32_e32 v60, v27
	v_cvt_f64_f32_e32 v[58:59], v27
	v_frexp_exp_i32_f64_e32 v58, v[58:59]
	v_cmp_gt_f32_e32 vcc, s25, v60
	s_nop 1
	v_subbrev_co_u32_e32 v66, vcc, 0, v58, vcc
	v_sub_u32_e32 v58, 0, v66
	v_ldexp_f32 v27, v27, v58
	v_ldexp_f32 v54, v54, v58
	v_add_f32_e32 v58, -1.0, v27
	v_add_f32_e32 v59, 1.0, v58
	v_sub_f32_e32 v59, v27, v59
	v_add_f32_e32 v60, v54, v59
	v_add_f32_e32 v59, 1.0, v27
	v_add_f32_e32 v61, -1.0, v59
	v_sub_f32_e32 v27, v27, v61
	v_add_f32_e32 v27, v54, v27
	v_add_f32_e32 v54, v59, v27
	v_rcp_f32_e32 v67, v54
	v_sub_f32_e32 v59, v54, v59
	v_sub_f32_e32 v27, v27, v59
	v_add_f32_e32 v59, v58, v60
	v_sub_f32_e32 v58, v59, v58
	v_mul_f32_e32 v69, v59, v67
	v_sub_f32_e32 v68, v60, v58
	v_mul_f32_e32 v60, v54, v69
	v_fma_f32 v62, v69, v54, -v60
	v_fmac_f32_e32 v62, v69, v27
	v_add_f32_e32 v58, v60, v62
	v_sub_f32_e32 v61, v59, v58
	v_pk_add_f32 v[64:65], v[58:59], v[60:61] neg_lo:[0,1] neg_hi:[0,1]
	v_mov_b32_e32 v63, v58
	v_pk_add_f32 v[58:59], v[64:65], v[62:63] neg_lo:[0,1] neg_hi:[0,1]
	v_cmp_neq_f32_e32 vcc, s31, v21
	v_add_f32_e32 v59, v68, v59
	v_add_f32_e32 v58, v58, v59
	v_add_f32_e32 v59, v61, v58
	v_mul_f32_e32 v68, v67, v59
	v_mul_f32_e32 v60, v54, v68
	v_fma_f32 v62, v68, v54, -v60
	v_fmac_f32_e32 v62, v68, v27
	v_sub_f32_e32 v27, v61, v59
	v_add_f32_e32 v27, v58, v27
	v_add_f32_e32 v58, v60, v62
	v_sub_f32_e32 v61, v59, v58
	v_pk_add_f32 v[64:65], v[58:59], v[60:61] neg_lo:[0,1] neg_hi:[0,1]
	v_mov_b32_e32 v63, v58
	v_pk_add_f32 v[58:59], v[64:65], v[62:63] neg_lo:[0,1] neg_hi:[0,1]
	v_add_f32_e32 v54, v69, v68
	v_add_f32_e32 v27, v27, v59
	v_add_f32_e32 v27, v58, v27
	v_add_f32_e32 v27, v61, v27
; DI float sigmoidf_(float x) { return 1.f / (1.f + __expf(-x)); }
; DI void hg_prep_unit(const Params& p, int l, int unit, unsigned char* smem) {
;     ...
;     float cum = 0.f;
; #pragma unroll
;     for (int i = 0; i < 16; ++i) {
;       const float kkv = fminf((1.f - lbv) * sigmoidf_(-KK[i]), 0.9999999f);
;       KK[i] = kkv;
;       cum += log1pf(-kkv);
;       G[i] = cum;
;     }
	v_sub_f32_e32 v58, v54, v69
	v_mul_f32_e32 v27, v67, v27
	v_sub_f32_e32 v58, v68, v58
	v_add_f32_e32 v27, v58, v27
	v_add_f32_e32 v59, v54, v27
	v_mul_f32_e32 v60, v59, v59
	v_fmamk_f32 v58, v60, 0x3e9b6dac, v212
	v_fmaak_f32 v211, v60, v58, 0x3f2aaada
	v_cvt_f32_i32_e32 v58, v66
	v_sub_f32_e32 v54, v59, v54
	v_ldexp_f32 v61, v59, 1
	v_mul_f32_e32 v59, v59, v60
	v_pk_mul_f32 v[62:63], v[58:59], v[210:211]
	v_sub_f32_e32 v27, v27, v54
	v_fma_f32 v60, v58, s30, -v62
	v_fmac_f32_e32 v60, 0xb102e308, v58
	v_pk_add_f32 v[58:59], v[62:63], v[60:61]
	v_ldexp_f32 v27, v27, 1
	v_sub_f32_e32 v54, v59, v61
	v_sub_f32_e32 v54, v63, v54
	v_add_f32_e32 v65, v27, v54
	v_mov_b32_e32 v64, v62
	v_pk_add_f32 v[62:63], v[58:59], v[62:63] neg_lo:[0,1] neg_hi:[0,1]
	v_pk_add_f32 v[66:67], v[58:59], v[64:65]
	v_mov_b32_e32 v61, v58
	v_mov_b32_e32 v63, v67
	v_pk_add_f32 v[68:69], v[60:61], v[62:63] neg_lo:[0,1] neg_hi:[0,1]
	v_pk_add_f32 v[60:61], v[60:61], v[62:63]
	v_mov_b32_e32 v64, v65
	v_pk_add_f32 v[62:63], v[60:61], v[58:59] op_sel:[1,0] op_sel_hi:[0,1] neg_lo:[0,1] neg_hi:[0,1]
	v_pk_add_f32 v[70:71], v[66:67], v[62:63] op_sel_hi:[1,0] neg_lo:[0,1] neg_hi:[0,1]
	v_mov_b32_e32 v66, v67
	v_mov_b32_e32 v67, v61
	v_pk_mov_b32 v[62:63], v[58:59], v[62:63] op_sel:[1,0]
	v_mov_b32_e32 v65, v58
	v_pk_add_f32 v[62:63], v[66:67], v[62:63] neg_lo:[0,1] neg_hi:[0,1]
	v_mov_b32_e32 v70, v68
	v_pk_add_f32 v[58:59], v[64:65], v[62:63] neg_lo:[0,1] neg_hi:[0,1]
	v_mov_b32_e32 v69, v61
	v_pk_add_f32 v[62:63], v[70:71], v[58:59]
	v_div_scale_f32 v54, s[6:7], v22, v22, 1.0
	v_pk_add_f32 v[64:65], v[62:63], v[62:63] op_sel:[0,1] op_sel_hi:[1,0]
	v_cmp_lt_f32_e64 s[6:7], |v21|, s44
	v_pk_add_f32 v[60:61], v[60:61], v[64:65] op_sel:[1,0] op_sel_hi:[0,1]
	v_mov_b32_e32 v63, v60
	v_pk_add_f32 v[66:67], v[62:63], v[68:69] neg_lo:[0,1] neg_hi:[0,1]
	v_mov_b32_e32 v59, v64
	v_sub_f32_e32 v27, v62, v66
	v_pk_add_f32 v[58:59], v[58:59], v[66:67] neg_lo:[0,1] neg_hi:[0,1]
	v_sub_f32_e32 v27, v68, v27
	v_add_f32_e32 v27, v58, v27
	v_add_f32_e32 v27, v27, v59
	v_rcp_f32_e32 v59, v54
	v_add_f32_e32 v27, v60, v27
	v_cndmask_b32_e32 v27, v214, v27, vcc
	v_cndmask_b32_e64 v27, v27, -v21, s[6:7]
	v_add_f32_e32 v58, v57, v27
	v_fma_f32 v27, -v54, v59, 1.0
	v_fmac_f32_e32 v59, v27, v59
	v_div_scale_f32 v27, vcc, 1.0, v22, 1.0
	v_mul_f32_e32 v60, v27, v59
	v_fma_f32 v61, -v54, v60, v27
	v_fmac_f32_e32 v60, v61, v59
	v_fma_f32 v27, -v54, v60, v27
	v_div_fmas_f32 v27, v27, v59, v60
	v_div_fixup_f32 v22, v27, v22, 1.0
	v_mul_f32_e32 v22, v25, v22
	v_min_f32_e32 v22, 0x3f7ffffe, v22
	v_sub_f32_e32 v27, 1.0, v22
	v_add_f32_e32 v54, -1.0, v27
	v_sub_f32_e32 v59, v54, v27
	v_add_f32_e32 v59, 1.0, v59
	v_sub_f32_e64 v54, -v22, v54
	v_add_f32_e32 v54, v54, v59
	v_frexp_mant_f32_e32 v59, v27
	v_cvt_f64_f32_e32 v[60:61], v27
	v_frexp_exp_i32_f64_e32 v60, v[60:61]
	v_cmp_gt_f32_e32 vcc, s25, v59
	s_nop 1
	v_subbrev_co_u32_e32 v59, vcc, 0, v60, vcc
	v_sub_u32_e32 v60, 0, v59
	v_ldexp_f32 v27, v27, v60
	v_ldexp_f32 v54, v54, v60
	v_add_f32_e32 v60, -1.0, v27
	v_add_f32_e32 v61, 1.0, v60
	v_sub_f32_e32 v61, v27, v61
	v_add_f32_e32 v62, v54, v61
	v_add_f32_e32 v61, 1.0, v27
	v_add_f32_e32 v63, -1.0, v61
	v_sub_f32_e32 v27, v27, v63
	v_add_f32_e32 v27, v54, v27
	v_add_f32_e32 v54, v61, v27
	v_rcp_f32_e32 v68, v54
	v_sub_f32_e32 v61, v54, v61
	v_sub_f32_e32 v27, v27, v61
	v_add_f32_e32 v61, v60, v62
	v_sub_f32_e32 v60, v61, v60
	v_mul_f32_e32 v70, v61, v68
	v_sub_f32_e32 v69, v62, v60
	v_mul_f32_e32 v62, v54, v70
	v_fma_f32 v64, v70, v54, -v62
	v_fmac_f32_e32 v64, v70, v27
	v_add_f32_e32 v60, v62, v64
	v_sub_f32_e32 v63, v61, v60
	v_pk_add_f32 v[66:67], v[60:61], v[62:63] neg_lo:[0,1] neg_hi:[0,1]
	v_mov_b32_e32 v65, v60
	v_pk_add_f32 v[60:61], v[66:67], v[64:65] neg_lo:[0,1] neg_hi:[0,1]
	v_cmp_neq_f32_e32 vcc, s31, v22
	v_add_f32_e32 v61, v69, v61
	v_add_f32_e32 v60, v60, v61
	v_add_f32_e32 v61, v63, v60
	v_mul_f32_e32 v69, v68, v61
	v_mul_f32_e32 v62, v54, v69
	v_fma_f32 v64, v69, v54, -v62
	v_fmac_f32_e32 v64, v69, v27
	v_sub_f32_e32 v27, v63, v61
	v_add_f32_e32 v27, v60, v27
	v_add_f32_e32 v60, v62, v64
	v_sub_f32_e32 v63, v61, v60
	v_pk_add_f32 v[66:67], v[60:61], v[62:63] neg_lo:[0,1] neg_hi:[0,1]
	v_mov_b32_e32 v65, v60
	v_pk_add_f32 v[60:61], v[66:67], v[64:65] neg_lo:[0,1] neg_hi:[0,1]
	v_add_f32_e32 v54, v70, v69
	v_add_f32_e32 v27, v27, v61
	v_add_f32_e32 v27, v60, v27
	v_add_f32_e32 v27, v63, v27
	v_sub_f32_e32 v60, v54, v70
	v_mul_f32_e32 v27, v68, v27
	v_sub_f32_e32 v60, v69, v60
	v_add_f32_e32 v27, v60, v27
	v_add_f32_e32 v61, v54, v27
	v_mul_f32_e32 v62, v61, v61
	v_fmamk_f32 v60, v62, 0x3e9b6dac, v212
	v_fmaak_f32 v211, v62, v60, 0x3f2aaada
	v_cvt_f32_i32_e32 v60, v59
	v_sub_f32_e32 v54, v61, v54
	v_ldexp_f32 v63, v61, 1
	v_mul_f32_e32 v61, v61, v62
	v_pk_mul_f32 v[64:65], v[60:61], v[210:211]
	v_sub_f32_e32 v27, v27, v54
	v_fma_f32 v62, v60, s30, -v64
	v_fmac_f32_e32 v62, 0xb102e308, v60
	v_pk_add_f32 v[60:61], v[64:65], v[62:63]
	v_ldexp_f32 v27, v27, 1
	v_sub_f32_e32 v54, v61, v63
	v_sub_f32_e32 v54, v65, v54
	v_add_f32_e32 v67, v27, v54
	v_mov_b32_e32 v66, v64
	v_pk_add_f32 v[64:65], v[60:61], v[64:65] neg_lo:[0,1] neg_hi:[0,1]
	v_pk_add_f32 v[68:69], v[60:61], v[66:67]
	v_mov_b32_e32 v63, v60
	v_mov_b32_e32 v65, v69
	v_pk_add_f32 v[70:71], v[62:63], v[64:65] neg_lo:[0,1] neg_hi:[0,1]
	v_pk_add_f32 v[62:63], v[62:63], v[64:65]
	v_mov_b32_e32 v66, v67
	v_pk_add_f32 v[64:65], v[62:63], v[60:61] op_sel:[1,0] op_sel_hi:[0,1] neg_lo:[0,1] neg_hi:[0,1]
	v_pk_add_f32 v[72:73], v[68:69], v[64:65] op_sel_hi:[1,0] neg_lo:[0,1] neg_hi:[0,1]
	v_mov_b32_e32 v68, v69
	v_mov_b32_e32 v69, v63
; DI float sigmoidf_(float x) { return 1.f / (1.f + __expf(-x)); }
; DI void hg_prep_unit(const Params& p, int l, int unit, unsigned char* smem) {
;     ...
;     float cum = 0.f;
; #pragma unroll
;     for (int i = 0; i < 16; ++i) {
;       const float kkv = fminf((1.f - lbv) * sigmoidf_(-KK[i]), 0.9999999f);
;       KK[i] = kkv;
;       cum += log1pf(-kkv);
;       G[i] = cum;
;     }
	v_pk_mov_b32 v[64:65], v[60:61], v[64:65] op_sel:[1,0]
	v_mov_b32_e32 v67, v60
	v_pk_add_f32 v[64:65], v[68:69], v[64:65] neg_lo:[0,1] neg_hi:[0,1]
	v_mov_b32_e32 v72, v70
	v_pk_add_f32 v[60:61], v[66:67], v[64:65] neg_lo:[0,1] neg_hi:[0,1]
	v_mov_b32_e32 v71, v63
	v_pk_add_f32 v[64:65], v[72:73], v[60:61]
	v_div_scale_f32 v54, s[6:7], v24, v24, 1.0
	v_pk_add_f32 v[66:67], v[64:65], v[64:65] op_sel:[0,1] op_sel_hi:[1,0]
	v_cmp_lt_f32_e64 s[6:7], |v22|, s44
	v_pk_add_f32 v[62:63], v[62:63], v[66:67] op_sel:[1,0] op_sel_hi:[0,1]
	v_mov_b32_e32 v65, v62
	v_pk_add_f32 v[68:69], v[64:65], v[70:71] neg_lo:[0,1] neg_hi:[0,1]
	v_mov_b32_e32 v61, v66
	v_sub_f32_e32 v27, v64, v68
	v_pk_add_f32 v[60:61], v[60:61], v[68:69] neg_lo:[0,1] neg_hi:[0,1]
	v_sub_f32_e32 v27, v70, v27
	v_add_f32_e32 v27, v60, v27
	v_add_f32_e32 v27, v27, v61
	v_rcp_f32_e32 v60, v54
	v_add_f32_e32 v27, v62, v27
	v_cndmask_b32_e32 v27, v214, v27, vcc
	v_cndmask_b32_e64 v27, v27, -v22, s[6:7]
	v_add_f32_e32 v59, v58, v27
	v_fma_f32 v27, -v54, v60, 1.0
	v_fmac_f32_e32 v60, v27, v60
	v_div_scale_f32 v27, vcc, 1.0, v24, 1.0
	v_mul_f32_e32 v61, v27, v60
	v_fma_f32 v62, -v54, v61, v27
	v_fmac_f32_e32 v61, v62, v60
	v_fma_f32 v27, -v54, v61, v27
	v_div_fmas_f32 v27, v27, v60, v61
	v_div_fixup_f32 v24, v27, v24, 1.0
	v_mul_f32_e32 v24, v25, v24
	v_min_f32_e32 v24, 0x3f7ffffe, v24
	v_sub_f32_e32 v27, 1.0, v24
	v_add_f32_e32 v54, -1.0, v27
	v_sub_f32_e32 v60, v54, v27
	v_add_f32_e32 v60, 1.0, v60
	v_sub_f32_e64 v54, -v24, v54
	v_add_f32_e32 v54, v54, v60
	v_frexp_mant_f32_e32 v62, v27
	v_cvt_f64_f32_e32 v[60:61], v27
	v_frexp_exp_i32_f64_e32 v60, v[60:61]
	v_cmp_gt_f32_e32 vcc, s25, v62
	s_nop 1
	v_subbrev_co_u32_e32 v68, vcc, 0, v60, vcc
	v_sub_u32_e32 v60, 0, v68
	v_ldexp_f32 v27, v27, v60
	v_ldexp_f32 v54, v54, v60
	v_add_f32_e32 v60, -1.0, v27
	v_add_f32_e32 v61, 1.0, v60
	v_sub_f32_e32 v61, v27, v61
	v_add_f32_e32 v62, v54, v61
	v_add_f32_e32 v61, 1.0, v27
	v_add_f32_e32 v63, -1.0, v61
	v_sub_f32_e32 v27, v27, v63
	v_add_f32_e32 v27, v54, v27
	v_add_f32_e32 v54, v61, v27
	v_rcp_f32_e32 v69, v54
	v_sub_f32_e32 v61, v54, v61
	v_sub_f32_e32 v27, v27, v61
	v_add_f32_e32 v61, v60, v62
	v_sub_f32_e32 v60, v61, v60
	v_mul_f32_e32 v71, v61, v69
	v_sub_f32_e32 v70, v62, v60
	v_mul_f32_e32 v62, v54, v71
	v_fma_f32 v64, v71, v54, -v62
	v_fmac_f32_e32 v64, v71, v27
	v_add_f32_e32 v60, v62, v64
	v_sub_f32_e32 v63, v61, v60
	v_pk_add_f32 v[66:67], v[60:61], v[62:63] neg_lo:[0,1] neg_hi:[0,1]
	v_mov_b32_e32 v65, v60
	v_pk_add_f32 v[60:61], v[66:67], v[64:65] neg_lo:[0,1] neg_hi:[0,1]
	v_cmp_neq_f32_e32 vcc, s31, v24
	v_add_f32_e32 v61, v70, v61
	v_add_f32_e32 v60, v60, v61
	v_add_f32_e32 v61, v63, v60
	v_mul_f32_e32 v70, v69, v61
	v_mul_f32_e32 v62, v54, v70
	v_fma_f32 v64, v70, v54, -v62
	v_fmac_f32_e32 v64, v70, v27
	v_sub_f32_e32 v27, v63, v61
	v_add_f32_e32 v27, v60, v27
	v_add_f32_e32 v60, v62, v64
	v_sub_f32_e32 v63, v61, v60
	v_pk_add_f32 v[66:67], v[60:61], v[62:63] neg_lo:[0,1] neg_hi:[0,1]
	v_mov_b32_e32 v65, v60
	v_pk_add_f32 v[60:61], v[66:67], v[64:65] neg_lo:[0,1] neg_hi:[0,1]
	v_add_f32_e32 v54, v71, v70
	v_add_f32_e32 v27, v27, v61
	v_add_f32_e32 v27, v60, v27
	v_add_f32_e32 v27, v63, v27
	v_sub_f32_e32 v60, v54, v71
	v_mul_f32_e32 v27, v69, v27
	v_sub_f32_e32 v60, v70, v60
	v_add_f32_e32 v27, v60, v27
	v_add_f32_e32 v61, v54, v27
	v_mul_f32_e32 v62, v61, v61
	v_fmamk_f32 v60, v62, 0x3e9b6dac, v212
	v_fmaak_f32 v211, v62, v60, 0x3f2aaada
	v_cvt_f32_i32_e32 v60, v68
	v_sub_f32_e32 v54, v61, v54
	v_ldexp_f32 v63, v61, 1
	v_mul_f32_e32 v61, v61, v62
	v_pk_mul_f32 v[64:65], v[60:61], v[210:211]
	v_sub_f32_e32 v27, v27, v54
	v_fma_f32 v62, v60, s30, -v64
	v_fmac_f32_e32 v62, 0xb102e308, v60
	v_pk_add_f32 v[60:61], v[64:65], v[62:63]
	v_ldexp_f32 v27, v27, 1
	v_sub_f32_e32 v54, v61, v63
	v_sub_f32_e32 v54, v65, v54
	v_add_f32_e32 v67, v27, v54
	v_mov_b32_e32 v66, v64
	v_pk_add_f32 v[64:65], v[60:61], v[64:65] neg_lo:[0,1] neg_hi:[0,1]
	v_pk_add_f32 v[68:69], v[60:61], v[66:67]
	v_mov_b32_e32 v63, v60
	v_mov_b32_e32 v65, v69
	v_pk_add_f32 v[70:71], v[62:63], v[64:65] neg_lo:[0,1] neg_hi:[0,1]
	v_pk_add_f32 v[62:63], v[62:63], v[64:65]
	v_mov_b32_e32 v66, v67
	v_pk_add_f32 v[64:65], v[62:63], v[60:61] op_sel:[1,0] op_sel_hi:[0,1] neg_lo:[0,1] neg_hi:[0,1]
	v_pk_add_f32 v[72:73], v[68:69], v[64:65] op_sel_hi:[1,0] neg_lo:[0,1] neg_hi:[0,1]
	v_mov_b32_e32 v68, v69
	v_mov_b32_e32 v69, v63
	v_pk_mov_b32 v[64:65], v[60:61], v[64:65] op_sel:[1,0]
	v_mov_b32_e32 v67, v60
	v_pk_add_f32 v[64:65], v[68:69], v[64:65] neg_lo:[0,1] neg_hi:[0,1]
	v_mov_b32_e32 v72, v70
	v_pk_add_f32 v[60:61], v[66:67], v[64:65] neg_lo:[0,1] neg_hi:[0,1]
	v_mov_b32_e32 v71, v63
	v_pk_add_f32 v[64:65], v[72:73], v[60:61]
	v_div_scale_f32 v54, s[6:7], v23, v23, 1.0
	v_pk_add_f32 v[66:67], v[64:65], v[64:65] op_sel:[0,1] op_sel_hi:[1,0]
	v_cmp_lt_f32_e64 s[6:7], |v24|, s44
	v_pk_add_f32 v[62:63], v[62:63], v[66:67] op_sel:[1,0] op_sel_hi:[0,1]
	v_mov_b32_e32 v65, v62
	v_pk_add_f32 v[68:69], v[64:65], v[70:71] neg_lo:[0,1] neg_hi:[0,1]
	v_mov_b32_e32 v61, v66
	v_sub_f32_e32 v27, v64, v68
	v_pk_add_f32 v[60:61], v[60:61], v[68:69] neg_lo:[0,1] neg_hi:[0,1]
	v_sub_f32_e32 v27, v70, v27
	v_add_f32_e32 v27, v60, v27
	v_add_f32_e32 v27, v27, v61
	v_rcp_f32_e32 v61, v54
	v_add_f32_e32 v27, v62, v27
	v_cndmask_b32_e32 v27, v214, v27, vcc
	v_cndmask_b32_e64 v27, v27, -v24, s[6:7]
	v_add_f32_e32 v60, v59, v27
	v_fma_f32 v27, -v54, v61, 1.0
	v_fmac_f32_e32 v61, v27, v61
	v_div_scale_f32 v27, vcc, 1.0, v23, 1.0
	v_mul_f32_e32 v62, v27, v61
	v_fma_f32 v63, -v54, v62, v27
	v_fmac_f32_e32 v62, v63, v61
	v_fma_f32 v27, -v54, v62, v27
; DI float sigmoidf_(float x) { return 1.f / (1.f + __expf(-x)); }
; DI void hg_prep_unit(const Params& p, int l, int unit, unsigned char* smem) {
;     ...
;     float cum = 0.f;
; #pragma unroll
;     for (int i = 0; i < 16; ++i) {
;       const float kkv = fminf((1.f - lbv) * sigmoidf_(-KK[i]), 0.9999999f);
;       KK[i] = kkv;
;       cum += log1pf(-kkv);
;       G[i] = cum;
;     }
	v_div_fmas_f32 v27, v27, v61, v62
	v_div_fixup_f32 v23, v27, v23, 1.0
	v_mul_f32_e32 v23, v25, v23
	v_min_f32_e32 v23, 0x3f7ffffe, v23
	v_sub_f32_e32 v27, 1.0, v23
	v_add_f32_e32 v54, -1.0, v27
	v_sub_f32_e32 v61, v54, v27
	v_add_f32_e32 v61, 1.0, v61
	v_sub_f32_e64 v54, -v23, v54
	v_add_f32_e32 v54, v54, v61
	v_frexp_mant_f32_e32 v61, v27
	v_cvt_f64_f32_e32 v[62:63], v27
	v_frexp_exp_i32_f64_e32 v62, v[62:63]
	v_cmp_gt_f32_e32 vcc, s25, v61
	s_nop 1
	v_subbrev_co_u32_e32 v61, vcc, 0, v62, vcc
	v_sub_u32_e32 v62, 0, v61
	v_ldexp_f32 v27, v27, v62
	v_ldexp_f32 v54, v54, v62
	v_add_f32_e32 v62, -1.0, v27
	v_add_f32_e32 v63, 1.0, v62
	v_sub_f32_e32 v63, v27, v63
	v_add_f32_e32 v64, v54, v63
	v_add_f32_e32 v63, 1.0, v27
	v_add_f32_e32 v65, -1.0, v63
	v_sub_f32_e32 v27, v27, v65
	v_add_f32_e32 v27, v54, v27
	v_add_f32_e32 v54, v63, v27
	v_rcp_f32_e32 v70, v54
	v_sub_f32_e32 v63, v54, v63
	v_sub_f32_e32 v27, v27, v63
	v_add_f32_e32 v63, v62, v64
	v_sub_f32_e32 v62, v63, v62
	v_mul_f32_e32 v72, v63, v70
	v_sub_f32_e32 v71, v64, v62
	v_mul_f32_e32 v64, v54, v72
	v_fma_f32 v66, v72, v54, -v64
	v_fmac_f32_e32 v66, v72, v27
	v_add_f32_e32 v62, v64, v66
	v_sub_f32_e32 v65, v63, v62
	v_pk_add_f32 v[68:69], v[62:63], v[64:65] neg_lo:[0,1] neg_hi:[0,1]
	v_mov_b32_e32 v67, v62
	v_pk_add_f32 v[62:63], v[68:69], v[66:67] neg_lo:[0,1] neg_hi:[0,1]
	v_cmp_neq_f32_e32 vcc, s31, v23
	v_add_f32_e32 v63, v71, v63
	v_add_f32_e32 v62, v62, v63
	v_add_f32_e32 v63, v65, v62
	v_mul_f32_e32 v71, v70, v63
	v_mul_f32_e32 v64, v54, v71
	v_fma_f32 v66, v71, v54, -v64
	v_fmac_f32_e32 v66, v71, v27
	v_sub_f32_e32 v27, v65, v63
	v_add_f32_e32 v27, v62, v27
	v_add_f32_e32 v62, v64, v66
	v_sub_f32_e32 v65, v63, v62
	v_pk_add_f32 v[68:69], v[62:63], v[64:65] neg_lo:[0,1] neg_hi:[0,1]
	v_mov_b32_e32 v67, v62
	v_pk_add_f32 v[62:63], v[68:69], v[66:67] neg_lo:[0,1] neg_hi:[0,1]
	v_add_f32_e32 v54, v72, v71
	v_add_f32_e32 v27, v27, v63
	v_add_f32_e32 v27, v62, v27
	v_add_f32_e32 v27, v65, v27
	v_sub_f32_e32 v62, v54, v72
	v_mul_f32_e32 v27, v70, v27
	v_sub_f32_e32 v62, v71, v62
	v_add_f32_e32 v27, v62, v27
	v_add_f32_e32 v63, v54, v27
	v_mul_f32_e32 v64, v63, v63
	v_fmamk_f32 v62, v64, 0x3e9b6dac, v212
	v_fmaak_f32 v211, v64, v62, 0x3f2aaada
	v_cvt_f32_i32_e32 v62, v61
	v_sub_f32_e32 v54, v63, v54
	v_ldexp_f32 v65, v63, 1
	v_mul_f32_e32 v63, v63, v64
	v_pk_mul_f32 v[66:67], v[62:63], v[210:211]
	v_sub_f32_e32 v27, v27, v54
	v_fma_f32 v64, v62, s30, -v66
	v_fmac_f32_e32 v64, 0xb102e308, v62
	v_pk_add_f32 v[62:63], v[66:67], v[64:65]
	v_ldexp_f32 v27, v27, 1
	v_sub_f32_e32 v54, v63, v65
	v_sub_f32_e32 v54, v67, v54
	v_add_f32_e32 v69, v27, v54
	v_mov_b32_e32 v68, v66
	v_pk_add_f32 v[66:67], v[62:63], v[66:67] neg_lo:[0,1] neg_hi:[0,1]
	v_pk_add_f32 v[70:71], v[62:63], v[68:69]
	v_mov_b32_e32 v65, v62
	v_mov_b32_e32 v67, v71
	v_pk_add_f32 v[72:73], v[64:65], v[66:67] neg_lo:[0,1] neg_hi:[0,1]
	v_pk_add_f32 v[64:65], v[64:65], v[66:67]
	v_mov_b32_e32 v68, v69
	v_pk_add_f32 v[66:67], v[64:65], v[62:63] op_sel:[1,0] op_sel_hi:[0,1] neg_lo:[0,1] neg_hi:[0,1]
	v_pk_add_f32 v[74:75], v[70:71], v[66:67] op_sel_hi:[1,0] neg_lo:[0,1] neg_hi:[0,1]
	v_mov_b32_e32 v70, v71
	v_mov_b32_e32 v71, v65
	v_pk_mov_b32 v[66:67], v[62:63], v[66:67] op_sel:[1,0]
	v_mov_b32_e32 v69, v62
	v_pk_add_f32 v[66:67], v[70:71], v[66:67] neg_lo:[0,1] neg_hi:[0,1]
	v_mov_b32_e32 v74, v72
	v_pk_add_f32 v[62:63], v[68:69], v[66:67] neg_lo:[0,1] neg_hi:[0,1]
	v_mov_b32_e32 v73, v65
	v_pk_add_f32 v[66:67], v[74:75], v[62:63]
	v_div_scale_f32 v54, s[6:7], v26, v26, 1.0
	v_pk_add_f32 v[68:69], v[66:67], v[66:67] op_sel:[0,1] op_sel_hi:[1,0]
	v_cmp_lt_f32_e64 s[6:7], |v23|, s44
	v_pk_add_f32 v[64:65], v[64:65], v[68:69] op_sel:[1,0] op_sel_hi:[0,1]
	v_mov_b32_e32 v67, v64
	v_pk_add_f32 v[70:71], v[66:67], v[72:73] neg_lo:[0,1] neg_hi:[0,1]
	v_mov_b32_e32 v63, v68
	v_sub_f32_e32 v27, v66, v70
	v_pk_add_f32 v[62:63], v[62:63], v[70:71] neg_lo:[0,1] neg_hi:[0,1]
	v_sub_f32_e32 v27, v72, v27
	v_add_f32_e32 v27, v62, v27
	v_add_f32_e32 v27, v27, v63
	v_rcp_f32_e32 v62, v54
	v_add_f32_e32 v27, v64, v27
	v_cndmask_b32_e32 v27, v214, v27, vcc
	v_cndmask_b32_e64 v27, v27, -v23, s[6:7]
	v_add_f32_e32 v61, v60, v27
	v_fma_f32 v27, -v54, v62, 1.0
	v_fmac_f32_e32 v62, v27, v62
	v_div_scale_f32 v27, vcc, 1.0, v26, 1.0
	v_mul_f32_e32 v63, v27, v62
	v_fma_f32 v64, -v54, v63, v27
	v_fmac_f32_e32 v63, v64, v62
	v_fma_f32 v27, -v54, v63, v27
	v_div_fmas_f32 v27, v27, v62, v63
	v_div_fixup_f32 v26, v27, v26, 1.0
	v_mul_f32_e32 v25, v25, v26
	v_min_f32_e32 v25, 0x3f7ffffe, v25
	v_sub_f32_e32 v54, 1.0, v25
	v_add_f32_e32 v26, -1.0, v54
	v_sub_f32_e32 v27, v26, v54
	v_add_f32_e32 v27, 1.0, v27
	v_sub_f32_e64 v26, -v25, v26
	v_add_f32_e32 v62, v26, v27
	v_frexp_mant_f32_e32 v63, v54
	v_cvt_f64_f32_e32 v[26:27], v54
	v_frexp_exp_i32_f64_e32 v26, v[26:27]
	v_cmp_gt_f32_e32 vcc, s25, v63
	v_cmp_lt_f32_e64 s[6:7], |v25|, s44
	s_mov_b32 s25, 0x1fffffc
	v_subbrev_co_u32_e32 v68, vcc, 0, v26, vcc
	v_sub_u32_e32 v26, 0, v68
	v_ldexp_f32 v27, v54, v26
	v_add_f32_e32 v54, -1.0, v27
	v_add_f32_e32 v63, 1.0, v27
	v_ldexp_f32 v26, v62, v26
	v_add_f32_e32 v62, 1.0, v54
	v_add_f32_e32 v64, -1.0, v63
	v_sub_f32_e32 v62, v27, v62
	v_sub_f32_e32 v27, v27, v64
	v_add_f32_e32 v62, v26, v62
	v_add_f32_e32 v26, v26, v27
	v_add_f32_e32 v69, v63, v26
	v_rcp_f32_e32 v71, v69
	v_sub_f32_e32 v27, v69, v63
	v_sub_f32_e32 v70, v26, v27
	v_add_f32_e32 v27, v54, v62
	v_sub_f32_e32 v26, v27, v54
	v_mul_f32_e32 v72, v27, v71
	v_sub_f32_e32 v54, v62, v26
	v_mul_f32_e32 v62, v69, v72
	v_fma_f32 v64, v72, v69, -v62
	v_fmac_f32_e32 v64, v72, v70
	v_add_f32_e32 v26, v62, v64
; DI float siluf_(float x) { return x / (1.f + __expf(-x)); }
; DI void hg_prep_unit(const Params& p, int l, int unit, unsigned char* smem) {
;     ...
;       cum += log1pf(-kkv);
;       G[i] = cum;
;     }
;     sTot[hf * 128 + dk] = cum;
; #pragma unroll
;     for (int q = 0; q < 2; ++q) {
;       u32x4 w; w[0] = vv[4 * q]; w[1] = vv[4 * q + 1]; w[2] = vv[4 * q + 2]; w[3] = vv[4 * q + 3];
;       *(u32x4*)(g_vT + fragn_idx(dk, i0 + 8 * q, 2)) = w;
;       *(u32x4*)(sVT + dk * 40 + i0 + 8 * q) = w;
;     }
;     __syncthreads();
;     const float t0 = sTot[dk], t1 = sTot[128 + dk];
;     const float Gl = t0 + t1, Gr = t0, goff = hf ? t0 : 0.f;
;     unsigned kh[8];
; #pragma unroll
;     for (int i = 0; i < 16; ++i) {
;       const int ig = i0 + i;
;       const float Gi = G[i] + goff;
;       const float kkv = KK[i];
;       const float q = siluf_(Q[i]);
	v_sub_f32_e32 v63, v27, v26
	v_pk_add_f32 v[66:67], v[26:27], v[62:63] neg_lo:[0,1] neg_hi:[0,1]
	v_mov_b32_e32 v65, v26
	v_pk_add_f32 v[26:27], v[66:67], v[64:65] neg_lo:[0,1] neg_hi:[0,1]
	v_cmp_neq_f32_e32 vcc, s31, v25
	v_add_f32_e32 v27, v54, v27
	v_add_f32_e32 v26, v26, v27
	v_add_f32_e32 v27, v63, v26
	v_mul_f32_e32 v54, v71, v27
	v_mul_f32_e32 v62, v69, v54
	v_fma_f32 v64, v54, v69, -v62
	v_fmac_f32_e32 v64, v54, v70
	v_sub_f32_e32 v63, v63, v27
	v_add_f32_e32 v69, v26, v63
	v_add_f32_e32 v26, v62, v64
	v_sub_f32_e32 v63, v27, v26
	v_pk_add_f32 v[66:67], v[26:27], v[62:63] neg_lo:[0,1] neg_hi:[0,1]
	v_mov_b32_e32 v65, v26
	v_pk_add_f32 v[26:27], v[66:67], v[64:65] neg_lo:[0,1] neg_hi:[0,1]
	s_movk_i32 s44, 0x50
	v_add_f32_e32 v27, v69, v27
	v_add_f32_e32 v26, v26, v27
	v_add_f32_e32 v27, v72, v54
	v_add_f32_e32 v26, v63, v26
	v_sub_f32_e32 v62, v27, v72
	v_mul_f32_e32 v26, v71, v26
	v_sub_f32_e32 v54, v54, v62
	v_add_f32_e32 v54, v54, v26
	v_add_f32_e32 v62, v27, v54
	v_mul_f32_e32 v64, v62, v62
	v_fmamk_f32 v26, v64, 0x3e9b6dac, v212
	v_fmaak_f32 v211, v64, v26, 0x3f2aaada
	v_cvt_f32_i32_e32 v26, v68
	v_sub_f32_e32 v27, v62, v27
	v_sub_f32_e32 v27, v54, v27
	v_ldexp_f32 v54, v27, 1
	v_mul_f32_e32 v27, v62, v64
	v_pk_mul_f32 v[64:65], v[26:27], v[210:211]
	v_ldexp_f32 v63, v62, 1
	v_fma_f32 v62, v26, s30, -v64
	v_fmac_f32_e32 v62, 0xb102e308, v26
	v_pk_add_f32 v[26:27], v[64:65], v[62:63]
	v_mov_b32_e32 v66, v64
	v_sub_f32_e32 v63, v27, v63
	v_sub_f32_e32 v63, v65, v63
	v_add_f32_e32 v67, v54, v63
	v_pk_add_f32 v[64:65], v[26:27], v[64:65] neg_lo:[0,1] neg_hi:[0,1]
	v_pk_add_f32 v[68:69], v[26:27], v[66:67]
	v_mov_b32_e32 v63, v26
	v_mov_b32_e32 v65, v69
	v_pk_add_f32 v[70:71], v[62:63], v[64:65] neg_lo:[0,1] neg_hi:[0,1]
	v_pk_add_f32 v[62:63], v[62:63], v[64:65]
	v_mov_b32_e32 v66, v67
	v_pk_add_f32 v[64:65], v[62:63], v[26:27] op_sel:[1,0] op_sel_hi:[0,1] neg_lo:[0,1] neg_hi:[0,1]
	v_pk_add_f32 v[72:73], v[68:69], v[64:65] op_sel_hi:[1,0] neg_lo:[0,1] neg_hi:[0,1]
	v_mov_b32_e32 v68, v69
	v_mov_b32_e32 v69, v63
	v_pk_mov_b32 v[64:65], v[26:27], v[64:65] op_sel:[1,0]
	v_mov_b32_e32 v67, v26
	v_pk_add_f32 v[64:65], v[68:69], v[64:65] neg_lo:[0,1] neg_hi:[0,1]
	v_mov_b32_e32 v72, v70
	v_pk_add_f32 v[26:27], v[66:67], v[64:65] neg_lo:[0,1] neg_hi:[0,1]
	v_mov_b32_e32 v71, v63
	v_pk_add_f32 v[64:65], v[72:73], v[26:27]
	s_mov_b64 s[30:31], 0x4000
	v_pk_add_f32 v[66:67], v[64:65], v[64:65] op_sel:[0,1] op_sel_hi:[1,0]
	s_nop 0
	v_pk_add_f32 v[62:63], v[62:63], v[66:67] op_sel:[1,0] op_sel_hi:[0,1]
	v_mov_b32_e32 v65, v62
	v_pk_add_f32 v[68:69], v[64:65], v[70:71] neg_lo:[0,1] neg_hi:[0,1]
	v_mov_b32_e32 v27, v66
	v_sub_f32_e32 v54, v64, v68
	v_pk_add_f32 v[26:27], v[26:27], v[68:69] neg_lo:[0,1] neg_hi:[0,1]
	v_sub_f32_e32 v54, v70, v54
	v_add_f32_e32 v26, v26, v54
	v_add_f32_e32 v26, v26, v27
	v_add_f32_e32 v26, v62, v26
	v_cndmask_b32_e32 v26, v214, v26, vcc
	v_cndmask_b32_e64 v26, v26, -v25, s[6:7]
	v_lshrrev_b32_e32 v27, 4, v28
	v_add_f32_e32 v63, v61, v26
	v_lshrrev_b32_e32 v26, 7, v28
	v_and_b32_e32 v27, 6, v27
	v_lshlrev_b32_e32 v62, 1, v31
	s_movk_i32 s7, 0x50
	v_and_b32_e32 v54, 31, v28
	v_mad_u32_u24 v66, v29, s7, v62
	v_add_lshl_u32 v62, v27, v26, 9
	v_lshl_or_b32 v26, v54, 3, v62
	v_ashrrev_i32_e32 v27, 31, v26
	v_lshl_add_u64 v[26:27], v[26:27], 1, s[28:29]
	s_movk_i32 s6, 0x4000
	v_lshl_add_u64 v[64:65], v[26:27], 0, s[30:31]
	v_add_co_u32_e32 v26, vcc, s6, v26
	v_lshlrev_b32_e32 v67, 2, v28
	s_nop 0
	v_addc_co_u32_e32 v27, vcc, 0, v27, vcc
	ds_write_b32 v67, v63 offset:27648
	flat_store_dwordx4 v[26:27], v[0:3]
	ds_write_b128 v66, v[0:3] offset:17408
	flat_store_dwordx4 v[64:65], v[4:7] offset:512
	v_mul_i32_i24_e32 v0, 0xffffffb4, v29
	v_mul_f32_e32 v3, 0xbfb8aa3b, v43
	v_mad_u32_u24 v0, v29, s7, v0
	v_exp_f32_e32 v3, v3
	ds_write_b128 v66, v[4:7] offset:17424
	s_waitcnt lgkmcnt(0)
	s_barrier
	ds_read2st64_b32 v[26:27], v0 offset0:108 offset1:110
	v_bfe_u32 v0, v28, 5, 2
	v_lshrrev_b32_e32 v2, 3, v30
	v_lshlrev_b32_e32 v65, 16, v45
	v_lshlrev_b32_e32 v45, 16, v44
	v_and_or_b32 v0, v2, s25, v0
	v_lshlrev_b32_e32 v44, 3, v28
	v_lshlrev_b32_e32 v0, 7, v0
	v_and_b32_e32 v2, 64, v67
	v_and_b32_e32 v4, 32, v44
	v_lshlrev_b32_e32 v66, 16, v46
	v_or3_b32 v46, v0, v2, v4
	v_add_f32_e32 v0, 1.0, v3
	v_div_scale_f32 v2, s[30:31], v0, v0, v43
	v_rcp_f32_e32 v3, v2
	v_and_b32_e32 v1, 3, v28
	v_lshrrev_b32_e32 v4, 1, v28
	v_and_or_b32 v64, v4, 4, v1
	v_fma_f32 v1, -v2, v3, 1.0
	s_movk_i32 s6, 0x80
	v_fmac_f32_e32 v3, v1, v3
	v_div_scale_f32 v1, vcc, v43, v0, v43
	v_cmp_gt_u32_e64 s[6:7], s6, v28
	v_mul_f32_e32 v5, v1, v3
	v_fma_f32 v6, -v2, v5, v1
	s_waitcnt lgkmcnt(0)
; DI bfr f2bf(float a) { return (bfr)(pk2(a, 0.f) & 0xffffu); }
; DI float siluf_(float x) { return x / (1.f + __expf(-x)); }
; DI void hg_prep_unit(const Params& p, int l, int unit, unsigned char* smem) {
;     ...
; #pragma unroll
;     for (int i = 0; i < 16; ++i) {
;       const int ig = i0 + i;
;       const float Gi = G[i] + goff;
;       const float kkv = KK[i];
;       const float q = siluf_(Q[i]);
;       g_qhat[fragp_idx(ig, dk, 4)] = f2bf(q * __expf(Gi));
;       const float khv = kkv * __expf(Gl - Gi);
;       if (i & 1) kh[i >> 1] |= ((unsigned)f2bf(khv)) << 16; else kh[i >> 1] = f2bf(khv);
;       sQt[ig * 136 + dk] = f2bf(q * __expf(fminf(Gi - Gr, 80.f)));
;       sKt[ig * 136 + dk] = f2bf(kkv * __expf(fminf(Gr - Gi, 80.f)));
;     }
; #pragma unroll
;     for (int q = 0; q < 2; ++q) { u32x4 w; w[0] = kh[4 * q]; w[1] = kh[4 * q + 1]; w[2] = kh[4 * q + 2]; w[3] = kh[4 * q + 3]; *(u32x4*)(g_khT + fragn_idx(dk, i0 + 8 * q, 2)) = w; }
;     if (hf == 0) ((float*)(WS_ + O_HGD))[(size_t)unit * 128 + dk] = __expf(Gl);
	v_cndmask_b32_e64 v7, v26, 0, s[6:7]
	v_add_f32_e32 v4, v7, v47
	v_fmac_f32_e32 v5, v6, v3
	v_fma_f32 v1, -v2, v5, v1
	v_mul_f32_e32 v2, 0x3fb8aa3b, v4
	v_exp_f32_e32 v2, v2
	v_div_fmas_f32 v1, v1, v3, v5
	v_div_fixup_f32 v3, v1, v0, v43
	v_sub_f32_e32 v1, v4, v26
	v_mul_f32_e32 v0, v3, v2
	v_cvt_pk_bf16_f32 v2, v0, s0
	v_and_or_b32 v0, v30, 16, v46
	v_min_f32_e32 v1, 0x42a00000, v1
	v_lshl_or_b32 v0, v0, 3, v64
	v_mul_f32_e32 v1, 0x3fb8aa3b, v1
	v_exp_f32_e32 v5, v1
	v_ashrrev_i32_e32 v1, 31, v0
	v_lshl_add_u64 v[0:1], v[0:1], 1, s[28:29]
	s_movk_i32 s25, 0x88
	flat_store_short v[0:1], v2
	v_mul_lo_u32 v1, v31, s25
	v_or_b32_e32 v1, v1, v29
	v_lshlrev_b32_e32 v43, 1, v1
	v_sub_f32_e32 v1, v26, v4
	v_min_f32_e32 v1, 0x42a00000, v1
	v_mul_f32_e32 v1, 0x3fb8aa3b, v1
	v_mul_f32_e32 v2, 0xbfb8aa3b, v42
	v_exp_f32_e32 v1, v1
	v_exp_f32_e32 v2, v2
	v_mul_f32_e32 v0, v3, v5
	v_cvt_pk_bf16_f32 v0, v0, s0
	ds_write_b16 v43, v0
	v_mul_f32_e32 v0, v8, v1
	v_add_f32_e32 v1, 1.0, v2
	v_div_scale_f32 v2, s[30:31], v1, v1, v42
	v_rcp_f32_e32 v3, v2
	v_add_f32_e32 v5, v7, v48
	v_cvt_pk_bf16_f32 v0, v0, s0
	ds_write_b16 v43, v0 offset:8704
	v_fma_f32 v6, -v2, v3, 1.0
	v_fmac_f32_e32 v3, v6, v3
	v_div_scale_f32 v6, vcc, v42, v1, v42
	v_mul_f32_e32 v47, v6, v3
	v_fma_f32 v48, -v2, v47, v6
	v_fmac_f32_e32 v47, v48, v3
	v_fma_f32 v2, -v2, v47, v6
	v_mul_f32_e32 v6, 0x3fb8aa3b, v5
	v_exp_f32_e32 v6, v6
	v_div_fmas_f32 v2, v2, v3, v47
	v_div_fixup_f32 v2, v2, v1, v42
	v_or_b32_e32 v0, 1, v31
	v_mul_f32_e32 v1, v2, v6
	v_cvt_pk_bf16_f32 v3, v1, s0
	v_sub_f32_e32 v1, v5, v26
	v_and_or_b32 v0, v0, 17, v46
	v_min_f32_e32 v1, 0x42a00000, v1
	v_lshl_or_b32 v0, v0, 3, v64
	v_mul_f32_e32 v1, 0x3fb8aa3b, v1
	v_exp_f32_e32 v6, v1
	v_ashrrev_i32_e32 v1, 31, v0
	v_lshl_add_u64 v[0:1], v[0:1], 1, s[28:29]
	flat_store_short v[0:1], v3
	v_sub_f32_e32 v1, v26, v5
	v_min_f32_e32 v1, 0x42a00000, v1
	v_mul_f32_e32 v0, v2, v6
	v_mul_f32_e32 v1, 0x3fb8aa3b, v1
	v_mul_f32_e32 v2, 0xbfb8aa3b, v16
	v_exp_f32_e32 v1, v1
	v_exp_f32_e32 v2, v2
	v_cvt_pk_bf16_f32 v0, v0, s0
	ds_write_b16 v43, v0 offset:272
	v_mul_f32_e32 v0, v10, v1
	v_add_f32_e32 v1, 1.0, v2
	v_div_scale_f32 v2, s[30:31], v1, v1, v16
	v_rcp_f32_e32 v3, v2
	v_add_f32_e32 v42, v7, v49
	v_cvt_pk_bf16_f32 v0, v0, s0
	ds_write_b16 v43, v0 offset:8976
	v_fma_f32 v6, -v2, v3, 1.0
	v_fmac_f32_e32 v3, v6, v3
	v_div_scale_f32 v6, vcc, v16, v1, v16
	v_mul_f32_e32 v47, v6, v3
	v_fma_f32 v48, -v2, v47, v6
	v_fmac_f32_e32 v47, v48, v3
	v_fma_f32 v2, -v2, v47, v6
	v_mul_f32_e32 v6, 0x3fb8aa3b, v42
	v_exp_f32_e32 v6, v6
	v_or_b32_e32 v0, 2, v31
	v_div_fmas_f32 v2, v2, v3, v47
	v_div_fixup_f32 v2, v2, v1, v16
	v_and_or_b32 v0, v0, 18, v46
	v_mul_f32_e32 v1, v2, v6
	v_lshl_or_b32 v0, v0, 3, v64
	v_cvt_pk_bf16_f32 v3, v1, s0
	v_ashrrev_i32_e32 v1, 31, v0
	v_lshl_add_u64 v[0:1], v[0:1], 1, s[28:29]
	flat_store_short v[0:1], v3
	v_sub_f32_e32 v0, v42, v26
	v_min_f32_e32 v0, 0x42a00000, v0
	v_mul_f32_e32 v0, 0x3fb8aa3b, v0
	v_sub_f32_e32 v1, v26, v42
	v_exp_f32_e32 v0, v0
	v_min_f32_e32 v1, 0x42a00000, v1
	v_mul_f32_e32 v1, 0x3fb8aa3b, v1
	v_exp_f32_e32 v1, v1
	v_mul_f32_e32 v0, v2, v0
	v_cvt_pk_bf16_f32 v0, v0, s0
	ds_write_b16 v43, v0 offset:544
	v_mul_f32_e32 v0, v9, v1
	v_mul_f32_e32 v1, 0xbfb8aa3b, v41
	v_exp_f32_e32 v1, v1
	v_mov_b32_e32 v6, v26
	v_mov_b32_e32 v16, v27
	v_cvt_pk_bf16_f32 v0, v0, s0
	v_pk_add_f32 v[16:17], v[6:7], v[16:17]
	ds_write_b16 v43, v0 offset:9248
	v_sub_f32_e32 v0, v16, v4
	v_add_f32_e32 v4, 1.0, v1
	v_sub_f32_e32 v2, v16, v5
	v_div_scale_f32 v5, s[30:31], v4, v4, v41
	v_rcp_f32_e32 v6, v5
	v_sub_f32_e32 v1, v16, v42
	v_or_b32_e32 v3, 3, v31
	v_and_or_b32 v3, v3, 19, v46
	v_fma_f32 v27, -v5, v6, 1.0
	v_fmac_f32_e32 v6, v27, v6
	v_div_scale_f32 v27, vcc, v41, v4, v41
	v_mul_f32_e32 v42, v27, v6
	v_fma_f32 v47, -v5, v42, v27
	v_fmac_f32_e32 v42, v47, v6
	v_fma_f32 v5, -v5, v42, v27
	v_mul_f32_e32 v27, 0x3fb8aa3b, v17
	v_exp_f32_e32 v27, v27
	v_div_fmas_f32 v5, v5, v6, v42
	v_div_fixup_f32 v6, v5, v4, v41
	v_mul_f32_e32 v0, 0x3fb8aa3b, v0
	v_mul_f32_e32 v4, v6, v27
	v_mul_f32_e32 v1, 0x3fb8aa3b, v1
	v_cvt_pk_bf16_f32 v27, v4, s0
	v_lshl_or_b32 v4, v3, 3, v64
	v_sub_f32_e32 v3, v16, v17
	v_exp_f32_e32 v0, v0
	v_mul_f32_e32 v2, 0x3fb8aa3b, v2
	v_exp_f32_e32 v1, v1
	v_mul_f32_e32 v3, 0x3fb8aa3b, v3
	v_exp_f32_e32 v2, v2
	v_exp_f32_e32 v3, v3
	v_ashrrev_i32_e32 v5, 31, v4
	v_lshl_add_u64 v[4:5], v[4:5], 1, s[28:29]
	v_pk_mul_f32 v[0:1], v[8:9], v[0:1]
	flat_store_short v[4:5], v27
	v_cvt_pk_bf16_f32 v4, v0, v1
	v_pk_mul_f32 v[0:1], v[10:11], v[2:3]
	v_sub_f32_e32 v2, v17, v26
	v_min_f32_e32 v2, 0x42a00000, v2
	v_cvt_pk_bf16_f32 v0, v0, v1
	v_mul_f32_e32 v2, 0x3fb8aa3b, v2
	v_sub_f32_e32 v3, v26, v17
	v_and_b32_e32 v1, 0xffff0000, v0
	v_exp_f32_e32 v2, v2
	v_lshlrev_b32_e32 v0, 16, v0
	v_min_f32_e32 v3, 0x42a00000, v3
	v_or_b32_sdwa v1, v1, v4 dst_sel:DWORD dst_unused:UNUSED_PAD src0_sel:DWORD src1_sel:WORD_1
	v_or_b32_sdwa v0, v0, v4 dst_sel:DWORD dst_unused:UNUSED_PAD src0_sel:DWORD src1_sel:WORD_0
	v_mul_f32_e32 v3, 0x3fb8aa3b, v3
	v_mul_f32_e32 v4, 0xbfb8aa3b, v40
	v_exp_f32_e32 v3, v3
	v_exp_f32_e32 v4, v4
	v_mul_f32_e32 v2, v6, v2
	v_cvt_pk_bf16_f32 v2, v2, s0
	ds_write_b16 v43, v2 offset:816
	v_mul_f32_e32 v2, v11, v3
	v_add_f32_e32 v3, 1.0, v4
	v_div_scale_f32 v4, s[30:31], v3, v3, v40
	v_rcp_f32_e32 v5, v4
	v_add_f32_e32 v6, v7, v50
	v_cvt_pk_bf16_f32 v2, v2, s0
	ds_write_b16 v43, v2 offset:9520
	v_fma_f32 v8, -v4, v5, 1.0
	v_fmac_f32_e32 v5, v8, v5
	v_div_scale_f32 v8, vcc, v40, v3, v40
	v_mul_f32_e32 v9, v8, v5
	v_fma_f32 v10, -v4, v9, v8
	v_fmac_f32_e32 v9, v10, v5
	v_fma_f32 v4, -v4, v9, v8
; DI bfr f2bf(float a) { return (bfr)(pk2(a, 0.f) & 0xffffu); }
; DI float siluf_(float x) { return x / (1.f + __expf(-x)); }
; DI void hg_prep_unit(const Params& p, int l, int unit, unsigned char* smem) {
;     ...
; #pragma unroll
;     for (int i = 0; i < 16; ++i) {
;       const int ig = i0 + i;
;       const float Gi = G[i] + goff;
;       const float kkv = KK[i];
;       const float q = siluf_(Q[i]);
;       g_qhat[fragp_idx(ig, dk, 4)] = f2bf(q * __expf(Gi));
;       const float khv = kkv * __expf(Gl - Gi);
;       if (i & 1) kh[i >> 1] |= ((unsigned)f2bf(khv)) << 16; else kh[i >> 1] = f2bf(khv);
;       sQt[ig * 136 + dk] = f2bf(q * __expf(fminf(Gi - Gr, 80.f)));
;       sKt[ig * 136 + dk] = f2bf(kkv * __expf(fminf(Gr - Gi, 80.f)));
;     }
; #pragma unroll
;     for (int q = 0; q < 2; ++q) { u32x4 w; w[0] = kh[4 * q]; w[1] = kh[4 * q + 1]; w[2] = kh[4 * q + 2]; w[3] = kh[4 * q + 3]; *(u32x4*)(g_khT + fragn_idx(dk, i0 + 8 * q, 2)) = w; }
;     if (hf == 0) ((float*)(WS_ + O_HGD))[(size_t)unit * 128 + dk] = __expf(Gl);
	v_mul_f32_e32 v8, 0x3fb8aa3b, v6
	v_exp_f32_e32 v8, v8
	v_or_b32_e32 v2, 4, v31
	v_div_fmas_f32 v4, v4, v5, v9
	v_div_fixup_f32 v4, v4, v3, v40
	v_and_or_b32 v2, v2, 20, v46
	v_mul_f32_e32 v3, v4, v8
	v_lshl_or_b32 v2, v2, 3, v64
	v_cvt_pk_bf16_f32 v5, v3, s0
	v_ashrrev_i32_e32 v3, 31, v2
	v_lshl_add_u64 v[2:3], v[2:3], 1, s[28:29]
	flat_store_short v[2:3], v5
	v_sub_f32_e32 v2, v6, v26
	v_min_f32_e32 v2, 0x42a00000, v2
	v_mul_f32_e32 v2, 0x3fb8aa3b, v2
	v_exp_f32_e32 v3, v2
	v_mul_f32_e32 v5, 0xbfb8aa3b, v39
	v_exp_f32_e32 v5, v5
	v_sub_f32_e32 v2, v16, v6
	v_mul_f32_e32 v3, v4, v3
	v_sub_f32_e32 v4, v26, v6
	v_min_f32_e32 v4, 0x42a00000, v4
	v_mul_f32_e32 v4, 0x3fb8aa3b, v4
	v_exp_f32_e32 v4, v4
	v_cvt_pk_bf16_f32 v3, v3, s0
	ds_write_b16 v43, v3 offset:1088
	v_add_f32_e32 v8, v7, v51
	v_mul_f32_e32 v3, v12, v4
	v_add_f32_e32 v4, 1.0, v5
	v_div_scale_f32 v5, s[30:31], v4, v4, v39
	v_rcp_f32_e32 v6, v5
	v_cvt_pk_bf16_f32 v3, v3, s0
	ds_write_b16 v43, v3 offset:9792
	v_or_b32_e32 v3, 5, v31
	v_fma_f32 v9, -v5, v6, 1.0
	v_fmac_f32_e32 v6, v9, v6
	v_div_scale_f32 v9, vcc, v39, v4, v39
	v_mul_f32_e32 v10, v9, v6
	v_fma_f32 v11, -v5, v10, v9
	v_fmac_f32_e32 v10, v11, v6
	v_fma_f32 v5, -v5, v10, v9
	v_mul_f32_e32 v9, 0x3fb8aa3b, v8
	v_exp_f32_e32 v9, v9
	v_div_fmas_f32 v5, v5, v6, v10
	v_div_fixup_f32 v6, v5, v4, v39
	v_and_or_b32 v3, v3, 21, v46
	v_mul_f32_e32 v4, v6, v9
	v_cvt_pk_bf16_f32 v9, v4, s0
	v_lshl_or_b32 v4, v3, 3, v64
	v_sub_f32_e32 v3, v8, v26
	v_min_f32_e32 v3, 0x42a00000, v3
	v_mul_f32_e32 v3, 0x3fb8aa3b, v3
	v_ashrrev_i32_e32 v5, 31, v4
	v_exp_f32_e32 v3, v3
	v_lshl_add_u64 v[4:5], v[4:5], 1, s[28:29]
	flat_store_short v[4:5], v9
	v_sub_f32_e32 v5, v26, v8
	v_min_f32_e32 v5, 0x42a00000, v5
	v_mul_f32_e32 v3, v6, v3
	v_mul_f32_e32 v5, 0x3fb8aa3b, v5
	v_mul_f32_e32 v6, 0xbfb8aa3b, v38
	v_exp_f32_e32 v5, v5
	v_exp_f32_e32 v6, v6
	v_cvt_pk_bf16_f32 v3, v3, s0
	ds_write_b16 v43, v3 offset:1360
	v_mul_f32_e32 v3, v14, v5
	v_add_f32_e32 v5, 1.0, v6
	v_div_scale_f32 v6, s[30:31], v5, v5, v38
	v_sub_f32_e32 v4, v16, v8
	v_rcp_f32_e32 v8, v6
	v_add_f32_e32 v10, v7, v52
	v_cvt_pk_bf16_f32 v3, v3, s0
	ds_write_b16 v43, v3 offset:10064
	v_fma_f32 v9, -v6, v8, 1.0
	v_fmac_f32_e32 v8, v9, v8
	v_div_scale_f32 v9, vcc, v38, v5, v38
	v_mul_f32_e32 v11, v9, v8
	v_fma_f32 v17, -v6, v11, v9
	v_fmac_f32_e32 v11, v17, v8
	v_fma_f32 v6, -v6, v11, v9
	v_mul_f32_e32 v9, 0x3fb8aa3b, v10
	v_exp_f32_e32 v9, v9
	v_or_b32_e32 v3, 6, v31
	v_div_fmas_f32 v6, v6, v8, v11
	v_and_or_b32 v3, v3, 22, v46
	v_div_fixup_f32 v5, v6, v5, v38
	v_lshl_or_b32 v8, v3, 3, v64
	v_sub_f32_e32 v3, v10, v26
	v_mul_f32_e32 v6, v5, v9
	v_ashrrev_i32_e32 v9, 31, v8
	v_min_f32_e32 v3, 0x42a00000, v3
	v_cvt_pk_bf16_f32 v6, v6, s0
	v_lshl_add_u64 v[8:9], v[8:9], 1, s[28:29]
	v_mul_f32_e32 v3, 0x3fb8aa3b, v3
	flat_store_short v[8:9], v6
	v_exp_f32_e32 v6, v3
	v_mul_f32_e32 v8, 0xbfb8aa3b, v37
	v_exp_f32_e32 v8, v8
	v_sub_f32_e32 v3, v16, v10
	v_mul_f32_e32 v5, v5, v6
	v_sub_f32_e32 v6, v26, v10
	v_min_f32_e32 v6, 0x42a00000, v6
	v_mul_f32_e32 v6, 0x3fb8aa3b, v6
	v_exp_f32_e32 v6, v6
	v_cvt_pk_bf16_f32 v5, v5, s0
	ds_write_b16 v43, v5 offset:1632
	v_add_f32_e32 v10, v7, v53
	v_mul_f32_e32 v5, v13, v6
	v_add_f32_e32 v6, 1.0, v8
	v_div_scale_f32 v8, s[30:31], v6, v6, v37
	v_rcp_f32_e32 v9, v8
	v_cvt_pk_bf16_f32 v5, v5, s0
	ds_write_b16 v43, v5 offset:10336
	v_or_b32_e32 v5, 7, v31
	v_fma_f32 v11, -v8, v9, 1.0
	v_fmac_f32_e32 v9, v11, v9
	v_div_scale_f32 v11, vcc, v37, v6, v37
	v_mul_f32_e32 v17, v11, v9
	v_fma_f32 v27, -v8, v17, v11
	v_fmac_f32_e32 v17, v27, v9
	v_fma_f32 v8, -v8, v17, v11
	v_mul_f32_e32 v11, 0x3fb8aa3b, v10
	v_exp_f32_e32 v11, v11
	v_div_fmas_f32 v8, v8, v9, v17
	v_div_fixup_f32 v6, v8, v6, v37
	v_and_or_b32 v5, v5, 23, v46
	v_mul_f32_e32 v8, v6, v11
	v_mul_f32_e32 v2, 0x3fb8aa3b, v2
	v_mul_f32_e32 v3, 0x3fb8aa3b, v3
	v_cvt_pk_bf16_f32 v11, v8, s0
	v_lshl_or_b32 v8, v5, 3, v64
	v_sub_f32_e32 v5, v16, v10
	v_exp_f32_e32 v2, v2
	v_mul_f32_e32 v4, 0x3fb8aa3b, v4
	v_exp_f32_e32 v3, v3
	v_mul_f32_e32 v5, 0x3fb8aa3b, v5
	v_exp_f32_e32 v4, v4
	v_exp_f32_e32 v5, v5
	v_ashrrev_i32_e32 v9, 31, v8
	v_lshl_add_u64 v[8:9], v[8:9], 1, s[28:29]
	v_pk_mul_f32 v[2:3], v[12:13], v[2:3]
	flat_store_short v[8:9], v11
	v_cvt_pk_bf16_f32 v8, v2, v3
	v_pk_mul_f32 v[2:3], v[14:15], v[4:5]
	v_sub_f32_e32 v4, v10, v26
	v_min_f32_e32 v4, 0x42a00000, v4
	v_mul_f32_e32 v4, 0x3fb8aa3b, v4
	v_exp_f32_e32 v4, v4
	v_sub_f32_e32 v5, v26, v10
	v_min_f32_e32 v5, 0x42a00000, v5
	v_mul_f32_e32 v5, 0x3fb8aa3b, v5
	v_mul_f32_e32 v4, v6, v4
	v_mul_f32_e32 v6, 0xbfb8aa3b, v36
	v_exp_f32_e32 v5, v5
	v_exp_f32_e32 v6, v6
	v_cvt_pk_bf16_f32 v4, v4, s0
	v_cvt_pk_bf16_f32 v2, v2, v3
	ds_write_b16 v43, v4 offset:1904
	v_mul_f32_e32 v4, v15, v5
	v_add_f32_e32 v5, 1.0, v6
	v_and_b32_e32 v3, 0xffff0000, v2
	v_lshlrev_b32_e32 v2, 16, v2
	v_div_scale_f32 v6, s[30:31], v5, v5, v36
	v_or_b32_sdwa v3, v3, v8 dst_sel:DWORD dst_unused:UNUSED_PAD src0_sel:DWORD src1_sel:WORD_1
	v_or_b32_sdwa v2, v2, v8 dst_sel:DWORD dst_unused:UNUSED_PAD src0_sel:DWORD src1_sel:WORD_0
	v_rcp_f32_e32 v8, v6
	v_add_f32_e32 v9, v7, v55
	v_cvt_pk_bf16_f32 v4, v4, s0
	ds_write_b16 v43, v4 offset:10608
	v_fma_f32 v10, -v6, v8, 1.0
	v_fmac_f32_e32 v8, v10, v8
	v_div_scale_f32 v10, vcc, v36, v5, v36
	v_mul_f32_e32 v11, v10, v8
	v_fma_f32 v12, -v6, v11, v10
	v_fmac_f32_e32 v11, v12, v8
	v_fma_f32 v6, -v6, v11, v10
	v_mul_f32_e32 v10, 0x3fb8aa3b, v9
	v_exp_f32_e32 v10, v10
	v_or_b32_e32 v4, 8, v31
	v_div_fmas_f32 v6, v6, v8, v11
	v_div_fixup_f32 v6, v6, v5, v36
	v_and_or_b32 v4, v4, 24, v46
	v_mul_f32_e32 v5, v6, v10
	v_lshl_or_b32 v4, v4, 3, v64
; DI bfr f2bf(float a) { return (bfr)(pk2(a, 0.f) & 0xffffu); }
; DI float siluf_(float x) { return x / (1.f + __expf(-x)); }
; DI void hg_prep_unit(const Params& p, int l, int unit, unsigned char* smem) {
;     ...
; #pragma unroll
;     for (int i = 0; i < 16; ++i) {
;       const int ig = i0 + i;
;       const float Gi = G[i] + goff;
;       const float kkv = KK[i];
;       const float q = siluf_(Q[i]);
;       g_qhat[fragp_idx(ig, dk, 4)] = f2bf(q * __expf(Gi));
;       const float khv = kkv * __expf(Gl - Gi);
;       if (i & 1) kh[i >> 1] |= ((unsigned)f2bf(khv)) << 16; else kh[i >> 1] = f2bf(khv);
;       sQt[ig * 136 + dk] = f2bf(q * __expf(fminf(Gi - Gr, 80.f)));
;       sKt[ig * 136 + dk] = f2bf(kkv * __expf(fminf(Gr - Gi, 80.f)));
;     }
; #pragma unroll
;     for (int q = 0; q < 2; ++q) { u32x4 w; w[0] = kh[4 * q]; w[1] = kh[4 * q + 1]; w[2] = kh[4 * q + 2]; w[3] = kh[4 * q + 3]; *(u32x4*)(g_khT + fragn_idx(dk, i0 + 8 * q, 2)) = w; }
;     if (hf == 0) ((float*)(WS_ + O_HGD))[(size_t)unit * 128 + dk] = __expf(Gl);
	v_cvt_pk_bf16_f32 v8, v5, s0
	v_ashrrev_i32_e32 v5, 31, v4
	v_lshl_add_u64 v[4:5], v[4:5], 1, s[28:29]
	flat_store_short v[4:5], v8
	v_sub_f32_e32 v4, v9, v26
	v_min_f32_e32 v4, 0x42a00000, v4
	v_mul_f32_e32 v4, 0x3fb8aa3b, v4
	v_exp_f32_e32 v5, v4
	v_mul_f32_e32 v8, 0xbfb8aa3b, v35
	v_exp_f32_e32 v8, v8
	v_sub_f32_e32 v4, v16, v9
	v_mul_f32_e32 v5, v6, v5
	v_sub_f32_e32 v6, v26, v9
	v_min_f32_e32 v6, 0x42a00000, v6
	v_mul_f32_e32 v6, 0x3fb8aa3b, v6
	v_exp_f32_e32 v6, v6
	v_cvt_pk_bf16_f32 v5, v5, s0
	ds_write_b16 v43, v5 offset:2176
	v_add_f32_e32 v10, v7, v56
	v_mul_f32_e32 v5, v18, v6
	v_add_f32_e32 v6, 1.0, v8
	v_div_scale_f32 v8, s[30:31], v6, v6, v35
	v_rcp_f32_e32 v9, v8
	v_cvt_pk_bf16_f32 v5, v5, s0
	ds_write_b16 v43, v5 offset:10880
	v_or_b32_e32 v5, 9, v31
	v_fma_f32 v11, -v8, v9, 1.0
	v_fmac_f32_e32 v9, v11, v9
	v_div_scale_f32 v11, vcc, v35, v6, v35
	v_mul_f32_e32 v12, v11, v9
	v_fma_f32 v13, -v8, v12, v11
	v_fmac_f32_e32 v12, v13, v9
	v_fma_f32 v8, -v8, v12, v11
	v_mul_f32_e32 v11, 0x3fb8aa3b, v10
	v_exp_f32_e32 v11, v11
	v_div_fmas_f32 v8, v8, v9, v12
	v_div_fixup_f32 v6, v8, v6, v35
	v_and_or_b32 v5, v5, 25, v46
	v_mul_f32_e32 v8, v6, v11
	v_cvt_pk_bf16_f32 v11, v8, s0
	v_lshl_or_b32 v8, v5, 3, v64
	v_sub_f32_e32 v5, v10, v26
	v_min_f32_e32 v5, 0x42a00000, v5
	v_mul_f32_e32 v5, 0x3fb8aa3b, v5
	v_exp_f32_e32 v5, v5
	v_ashrrev_i32_e32 v9, 31, v8
	v_lshl_add_u64 v[8:9], v[8:9], 1, s[28:29]
	flat_store_short v[8:9], v11
	v_mul_f32_e32 v5, v6, v5
	v_sub_f32_e32 v6, v26, v10
	v_min_f32_e32 v6, 0x42a00000, v6
	v_mul_f32_e32 v6, 0x3fb8aa3b, v6
	v_mul_f32_e32 v9, 0xbfb8aa3b, v34
	v_exp_f32_e32 v6, v6
	v_exp_f32_e32 v9, v9
	v_cvt_pk_bf16_f32 v5, v5, s0
	ds_write_b16 v43, v5 offset:2448
	v_mul_f32_e32 v5, v20, v6
	v_add_f32_e32 v6, 1.0, v9
	v_div_scale_f32 v9, s[30:31], v6, v6, v34
	v_sub_f32_e32 v8, v16, v10
	v_rcp_f32_e32 v10, v9
	v_add_f32_e32 v12, v7, v57
	v_cvt_pk_bf16_f32 v5, v5, s0
	ds_write_b16 v43, v5 offset:11152
	v_fma_f32 v11, -v9, v10, 1.0
	v_fmac_f32_e32 v10, v11, v10
	v_div_scale_f32 v11, vcc, v34, v6, v34
	v_mul_f32_e32 v13, v11, v10
	v_fma_f32 v14, -v9, v13, v11
	v_fmac_f32_e32 v13, v14, v10
	v_fma_f32 v9, -v9, v13, v11
	v_mul_f32_e32 v11, 0x3fb8aa3b, v12
	v_exp_f32_e32 v11, v11
	v_or_b32_e32 v5, 10, v31
	v_div_fmas_f32 v9, v9, v10, v13
	v_and_or_b32 v5, v5, 26, v46
	v_div_fixup_f32 v6, v9, v6, v34
	v_lshl_or_b32 v10, v5, 3, v64
	v_sub_f32_e32 v5, v12, v26
	v_mul_f32_e32 v9, v6, v11
	v_ashrrev_i32_e32 v11, 31, v10
	v_min_f32_e32 v5, 0x42a00000, v5
	v_cvt_pk_bf16_f32 v9, v9, s0
	v_lshl_add_u64 v[10:11], v[10:11], 1, s[28:29]
	v_mul_f32_e32 v5, 0x3fb8aa3b, v5
	flat_store_short v[10:11], v9
	v_exp_f32_e32 v9, v5
	v_mul_f32_e32 v10, 0xbfb8aa3b, v33
	v_exp_f32_e32 v10, v10
	v_sub_f32_e32 v5, v16, v12
	v_mul_f32_e32 v6, v6, v9
	v_sub_f32_e32 v9, v26, v12
	v_min_f32_e32 v9, 0x42a00000, v9
	v_mul_f32_e32 v9, 0x3fb8aa3b, v9
	v_exp_f32_e32 v9, v9
	v_cvt_pk_bf16_f32 v6, v6, s0
	ds_write_b16 v43, v6 offset:2720
	v_add_f32_e32 v12, v7, v58
	v_mul_f32_e32 v6, v19, v9
	v_add_f32_e32 v9, 1.0, v10
	v_div_scale_f32 v10, s[30:31], v9, v9, v33
	v_rcp_f32_e32 v11, v10
	v_cvt_pk_bf16_f32 v6, v6, s0
	ds_write_b16 v43, v6 offset:11424
	v_or_b32_e32 v6, 11, v31
	v_fma_f32 v13, -v10, v11, 1.0
	v_fmac_f32_e32 v11, v13, v11
	v_div_scale_f32 v13, vcc, v33, v9, v33
	v_mul_f32_e32 v14, v13, v11
	v_fma_f32 v15, -v10, v14, v13
	v_fmac_f32_e32 v14, v15, v11
	v_fma_f32 v10, -v10, v14, v13
	v_mul_f32_e32 v13, 0x3fb8aa3b, v12
	v_exp_f32_e32 v13, v13
	v_div_fmas_f32 v10, v10, v11, v14
	v_and_or_b32 v6, v6, 27, v46
	v_mul_f32_e32 v4, 0x3fb8aa3b, v4
	v_mul_f32_e32 v5, 0x3fb8aa3b, v5
	v_div_fixup_f32 v14, v10, v9, v33
	v_lshl_or_b32 v10, v6, 3, v64
	v_sub_f32_e32 v6, v16, v12
	v_exp_f32_e32 v4, v4
	v_mul_f32_e32 v8, 0x3fb8aa3b, v8
	v_exp_f32_e32 v5, v5
	v_mul_f32_e32 v9, v14, v13
	v_mul_f32_e32 v6, 0x3fb8aa3b, v6
	v_exp_f32_e32 v8, v8
	v_cvt_pk_bf16_f32 v13, v9, s0
	v_exp_f32_e32 v9, v6
	v_pk_mul_f32 v[4:5], v[18:19], v[4:5]
	v_ashrrev_i32_e32 v11, 31, v10
	v_cvt_pk_bf16_f32 v6, v4, v5
	v_pk_mul_f32 v[4:5], v[20:21], v[8:9]
	v_sub_f32_e32 v8, v12, v26
	v_min_f32_e32 v8, 0x42a00000, v8
	v_mul_f32_e32 v8, 0x3fb8aa3b, v8
	v_exp_f32_e32 v8, v8
	v_cvt_pk_bf16_f32 v4, v4, v5
	v_and_b32_e32 v5, 0xffff0000, v4
	v_lshlrev_b32_e32 v4, 16, v4
	v_or_b32_sdwa v5, v5, v6 dst_sel:DWORD dst_unused:UNUSED_PAD src0_sel:DWORD src1_sel:WORD_1
	v_or_b32_sdwa v4, v4, v6 dst_sel:DWORD dst_unused:UNUSED_PAD src0_sel:DWORD src1_sel:WORD_0
	v_mul_f32_e32 v6, v14, v8
	v_sub_f32_e32 v8, v26, v12
	v_min_f32_e32 v8, 0x42a00000, v8
	v_mul_f32_e32 v8, 0x3fb8aa3b, v8
	v_mul_f32_e32 v9, 0xbfb8aa3b, v32
	v_exp_f32_e32 v8, v8
	v_exp_f32_e32 v9, v9
	v_lshl_add_u64 v[10:11], v[10:11], 1, s[28:29]
	v_cvt_pk_bf16_f32 v6, v6, s0
	flat_store_short v[10:11], v13
	ds_write_b16 v43, v6 offset:2992
	v_mul_f32_e32 v6, v21, v8
	v_add_f32_e32 v8, 1.0, v9
	v_div_scale_f32 v9, s[30:31], v8, v8, v32
	v_rcp_f32_e32 v10, v9
	v_add_f32_e32 v11, v7, v59
	v_cvt_pk_bf16_f32 v6, v6, s0
	ds_write_b16 v43, v6 offset:11696
	v_fma_f32 v12, -v9, v10, 1.0
	v_fmac_f32_e32 v10, v12, v10
	v_div_scale_f32 v12, vcc, v32, v8, v32
	v_mul_f32_e32 v13, v12, v10
	v_fma_f32 v14, -v9, v13, v12
	v_fmac_f32_e32 v13, v14, v10
	v_fma_f32 v9, -v9, v13, v12
	v_mul_f32_e32 v12, 0x3fb8aa3b, v11
	v_exp_f32_e32 v12, v12
	v_div_fmas_f32 v9, v9, v10, v13
	v_or_b32_e32 v6, 12, v31
	v_div_fixup_f32 v10, v9, v8, v32
	v_mul_f32_e32 v8, v10, v12
	v_and_or_b32 v6, v6, 28, v46
	v_cvt_pk_bf16_f32 v12, v8, s0
	v_lshl_or_b32 v8, v6, 3, v64
	v_sub_f32_e32 v6, v11, v26
	v_min_f32_e32 v6, 0x42a00000, v6
	v_mul_f32_e32 v6, 0x3fb8aa3b, v6
	v_ashrrev_i32_e32 v9, 31, v8
; DI bfr f2bf(float a) { return (bfr)(pk2(a, 0.f) & 0xffffu); }
; DI float siluf_(float x) { return x / (1.f + __expf(-x)); }
; DI void hg_prep_unit(const Params& p, int l, int unit, unsigned char* smem) {
;     ...
; #pragma unroll
;     for (int i = 0; i < 16; ++i) {
;       const int ig = i0 + i;
;       const float Gi = G[i] + goff;
;       const float kkv = KK[i];
;       const float q = siluf_(Q[i]);
;       g_qhat[fragp_idx(ig, dk, 4)] = f2bf(q * __expf(Gi));
;       const float khv = kkv * __expf(Gl - Gi);
;       if (i & 1) kh[i >> 1] |= ((unsigned)f2bf(khv)) << 16; else kh[i >> 1] = f2bf(khv);
;       sQt[ig * 136 + dk] = f2bf(q * __expf(fminf(Gi - Gr, 80.f)));
;       sKt[ig * 136 + dk] = f2bf(kkv * __expf(fminf(Gr - Gi, 80.f)));
;     }
; #pragma unroll
;     for (int q = 0; q < 2; ++q) { u32x4 w; w[0] = kh[4 * q]; w[1] = kh[4 * q + 1]; w[2] = kh[4 * q + 2]; w[3] = kh[4 * q + 3]; *(u32x4*)(g_khT + fragn_idx(dk, i0 + 8 * q, 2)) = w; }
;     if (hf == 0) ((float*)(WS_ + O_HGD))[(size_t)unit * 128 + dk] = __expf(Gl);
	v_exp_f32_e32 v6, v6
	v_lshl_add_u64 v[8:9], v[8:9], 1, s[28:29]
	flat_store_short v[8:9], v12
	v_sub_f32_e32 v9, v26, v11
	v_min_f32_e32 v9, 0x42a00000, v9
	v_mul_f32_e32 v6, v10, v6
	v_mul_f32_e32 v9, 0x3fb8aa3b, v9
	v_mul_f32_e32 v10, 0xbfb8aa3b, v66
	v_exp_f32_e32 v9, v9
	v_exp_f32_e32 v10, v10
	v_cvt_pk_bf16_f32 v6, v6, s0
	ds_write_b16 v43, v6 offset:3264
	v_mul_f32_e32 v6, v22, v9
	v_add_f32_e32 v9, 1.0, v10
	v_div_scale_f32 v10, s[30:31], v9, v9, v66
	v_sub_f32_e32 v8, v16, v11
	v_rcp_f32_e32 v11, v10
	v_add_f32_e32 v12, v7, v60
	v_cvt_pk_bf16_f32 v6, v6, s0
	ds_write_b16 v43, v6 offset:11968
	v_fma_f32 v13, -v10, v11, 1.0
	v_fmac_f32_e32 v11, v13, v11
	v_div_scale_f32 v13, vcc, v66, v9, v66
	v_mul_f32_e32 v14, v13, v11
	v_fma_f32 v15, -v10, v14, v13
	v_fmac_f32_e32 v14, v15, v11
	v_fma_f32 v10, -v10, v14, v13
	v_mul_f32_e32 v13, 0x3fb8aa3b, v12
	v_exp_f32_e32 v13, v13
	v_div_fmas_f32 v10, v10, v11, v14
	v_or_b32_e32 v6, 13, v31
	v_div_fixup_f32 v9, v10, v9, v66
	v_mul_f32_e32 v10, v9, v13
	v_and_or_b32 v6, v6, 29, v46
	v_cvt_pk_bf16_f32 v13, v10, s0
	v_lshl_or_b32 v10, v6, 3, v64
	v_sub_f32_e32 v6, v12, v26
	v_ashrrev_i32_e32 v11, 31, v10
	v_min_f32_e32 v6, 0x42a00000, v6
	v_lshl_add_u64 v[10:11], v[10:11], 1, s[28:29]
	v_mul_f32_e32 v6, 0x3fb8aa3b, v6
	flat_store_short v[10:11], v13
	v_exp_f32_e32 v10, v6
	v_mul_f32_e32 v11, 0xbfb8aa3b, v65
	v_exp_f32_e32 v11, v11
	v_sub_f32_e32 v6, v16, v12
	v_mul_f32_e32 v9, v9, v10
	v_sub_f32_e32 v10, v26, v12
	v_min_f32_e32 v10, 0x42a00000, v10
	v_mul_f32_e32 v10, 0x3fb8aa3b, v10
	v_exp_f32_e32 v10, v10
	v_cvt_pk_bf16_f32 v9, v9, s0
	ds_write_b16 v43, v9 offset:3536
	v_add_f32_e32 v13, v7, v61
	v_mul_f32_e32 v9, v24, v10
	v_add_f32_e32 v10, 1.0, v11
	v_div_scale_f32 v11, s[30:31], v10, v10, v65
	v_rcp_f32_e32 v12, v11
	v_cvt_pk_bf16_f32 v9, v9, s0
	ds_write_b16 v43, v9 offset:12240
	v_or_b32_e32 v9, 14, v31
	v_fma_f32 v14, -v11, v12, 1.0
	v_fmac_f32_e32 v12, v14, v12
	v_div_scale_f32 v14, vcc, v65, v10, v65
	v_mul_f32_e32 v15, v14, v12
	v_fma_f32 v17, -v11, v15, v14
	v_fmac_f32_e32 v15, v17, v12
	v_fma_f32 v11, -v11, v15, v14
	v_mul_f32_e32 v14, 0x3fb8aa3b, v13
	v_exp_f32_e32 v14, v14
	v_div_fmas_f32 v11, v11, v12, v15
	v_div_fixup_f32 v12, v11, v10, v65
	v_and_or_b32 v9, v9, 30, v46
	v_mul_f32_e32 v10, v12, v14
	v_cvt_pk_bf16_f32 v14, v10, s0
	v_lshl_or_b32 v10, v9, 3, v64
	v_sub_f32_e32 v9, v13, v26
	v_ashrrev_i32_e32 v11, 31, v10
	v_min_f32_e32 v9, 0x42a00000, v9
	v_lshl_add_u64 v[10:11], v[10:11], 1, s[28:29]
	v_mul_f32_e32 v9, 0x3fb8aa3b, v9
	flat_store_short v[10:11], v14
	v_exp_f32_e32 v10, v9
	v_sub_f32_e32 v11, v26, v13
	v_min_f32_e32 v11, 0x42a00000, v11
	v_mul_f32_e32 v11, 0x3fb8aa3b, v11
	v_mul_f32_e32 v10, v12, v10
	v_mul_f32_e32 v12, 0xbfb8aa3b, v45
	v_exp_f32_e32 v11, v11
	v_exp_f32_e32 v12, v12
	v_cvt_pk_bf16_f32 v10, v10, s0
	ds_write_b16 v43, v10 offset:3808
	v_mul_f32_e32 v10, v23, v11
	v_add_f32_e32 v11, 1.0, v12
	v_div_scale_f32 v12, s[30:31], v11, v11, v45
	v_sub_f32_e32 v9, v16, v13
	v_rcp_f32_e32 v13, v12
	v_add_f32_e32 v15, v7, v63
	v_cvt_pk_bf16_f32 v10, v10, s0
	ds_write_b16 v43, v10 offset:12512
	v_fma_f32 v7, -v12, v13, 1.0
	v_fmac_f32_e32 v13, v7, v13
	v_div_scale_f32 v7, vcc, v45, v11, v45
	v_mul_f32_e32 v10, v7, v13
	v_fma_f32 v17, -v12, v10, v7
	v_fmac_f32_e32 v10, v17, v13
	v_fma_f32 v7, -v12, v10, v7
	v_mul_f32_e32 v12, 0x3fb8aa3b, v15
	v_exp_f32_e32 v12, v12
	v_mul_f32_e32 v8, 0x3fb8aa3b, v8
	v_mul_f32_e32 v9, 0x3fb8aa3b, v9
	v_div_fmas_f32 v7, v7, v13, v10
	v_exp_f32_e32 v8, v8
	v_exp_f32_e32 v9, v9
	v_div_fixup_f32 v13, v7, v11, v45
	v_or_b32_e32 v14, 15, v30
	v_mul_f32_e32 v7, v13, v12
	v_cvt_pk_bf16_f32 v12, v7, s0
	v_and_or_b32 v7, v14, 31, v46
	v_lshl_or_b32 v10, v7, 3, v64
	v_sub_f32_e32 v7, v16, v15
	v_mul_f32_e32 v6, 0x3fb8aa3b, v6
	v_mul_f32_e32 v7, 0x3fb8aa3b, v7
	v_pk_mul_f32 v[8:9], v[22:23], v[8:9]
	v_exp_f32_e32 v6, v6
	v_exp_f32_e32 v7, v7
	v_cvt_pk_bf16_f32 v8, v8, v9
	v_sub_f32_e32 v9, v15, v26
	v_min_f32_e32 v9, 0x42a00000, v9
	v_mul_f32_e32 v9, 0x3fb8aa3b, v9
	v_exp_f32_e32 v9, v9
	v_pk_mul_f32 v[6:7], v[24:25], v[6:7]
	v_ashrrev_i32_e32 v11, 31, v10
	v_cvt_pk_bf16_f32 v6, v6, v7
	v_and_b32_e32 v7, 0xffff0000, v6
	v_lshlrev_b32_e32 v6, 16, v6
	v_or_b32_sdwa v7, v7, v8 dst_sel:DWORD dst_unused:UNUSED_PAD src0_sel:DWORD src1_sel:WORD_1
	v_or_b32_sdwa v6, v6, v8 dst_sel:DWORD dst_unused:UNUSED_PAD src0_sel:DWORD src1_sel:WORD_0
	v_mul_f32_e32 v8, v13, v9
	v_sub_f32_e32 v9, v26, v15
	v_min_f32_e32 v9, 0x42a00000, v9
	v_mul_f32_e32 v9, 0x3fb8aa3b, v9
	v_exp_f32_e32 v9, v9
	v_lshl_add_u64 v[10:11], v[10:11], 1, s[28:29]
	flat_store_short v[10:11], v12
	v_mul_lo_u32 v10, v14, s25
	v_cvt_pk_bf16_f32 v8, v8, s0
	v_add_lshl_u32 v10, v10, v29, 1
	ds_write_b16 v10, v8
	v_mul_f32_e32 v8, v25, v9
	v_cvt_pk_bf16_f32 v8, v8, s0
	s_movk_i32 s25, 0xf8
	ds_write_b16 v10, v8 offset:8704
	v_and_or_b32 v8, v44, s25, v62
	v_ashrrev_i32_e32 v9, 31, v8
	v_lshl_add_u64 v[8:9], v[8:9], 1, s[28:29]
	s_mov_b64 s[28:29], 0x2000
	v_lshl_add_u64 v[10:11], v[8:9], 0, s[28:29]
	v_add_co_u32_e32 v8, vcc, 0x2000, v8
	s_nop 1
	v_addc_co_u32_e32 v9, vcc, 0, v9, vcc
	flat_store_dwordx4 v[8:9], v[0:3]
	flat_store_dwordx4 v[10:11], v[4:7] offset:512
	s_and_saveexec_b64 s[28:29], s[6:7]
	s_cbranch_execz .LBB0_321
	s_mov_b32 s25, s45
	s_lshl_b64 s[6:7], s[24:25], 9
	v_mul_f32_e32 v0, 0x3fb8aa3b, v16
	s_add_u32 s6, s8, s6
	v_exp_f32_e32 v2, v0
	s_addc_u32 s7, s9, s7
	v_lshlrev_b32_e32 v208, 2, v29
	v_lshl_add_u64 v[0:1], s[6:7], 0, v[208:209]
	v_add_co_u32_e32 v0, vcc, 0x67fcf000, v0
	s_nop 1
	v_addc_co_u32_e32 v1, vcc, 0, v1, vcc
	flat_store_dword v[0:1], v2 offset:1536
